# S5 scan phases: B-bar*u and C*x matrix instructions spread between the recurrence vector instructions instead of issued as a block
# baseline (speedup 1.0000x reference)
;     __device__ __forceinline__ bf16* R(int i) const { return (bf16*)(ws + OFF_R0 + (size_t)i * RSZ); }
; template <bool FINAL> __device__ __forceinline__ void phase_s5_scan(const Fr& F) {
;     ...
;     for (int ti = (F.gw & 15); ti < NB * 68; ti += 16) {
;         const int b = ti / 68, chunk = ti - b * 68, sbg = (s * 4 + b) * 64 + g, task = sbg * 68 + chunk;
;         float xr = FINAL ? e0 : 0.f, xi = FINAL ? e1 : 0.f;
;         bf16* Yb = F.R(4 + s);
;         u32x4 uc[4];
; #pragma unroll
;         for (int sb = 0; sb < 4; ++sb) uc[sb] = ua[sb];
;         if (ti + 16 < NB * 68) {
;             const int tn = ti + 16, bn = tn / 68, cn = tn - bn * 68;
; #pragma unroll
;             for (int sb = 0; sb < 4; ++sb) ua[sb] = lq < 2 ? *(const u32x4*)(U + ((size_t)bn * TB + tokof(s, cn * 64 + sb * 16 + l15)) * D + g * 16 + 8 * lq) : (u32x4){0u, 0u, 0u, 0u};
;             if (FINAL) { const float* e = E + ((size_t)(((s * 4 + bn) * 64 + g) * 68 + cn) * 64 + lane) * 2; e0 = e[0]; e1 = e[1]; }
;         }
; #pragma unroll
;         for (int sub = 0; sub < 4; ++sub) {
;             const bf16x8 A1 = __builtin_bit_cast(bf16x8, uc[sub]);
; #pragma unroll
;             for (int nt = 0; nt < 8; ++nt) {
;                 f32x4 acc = {0.f, 0.f, 0.f, 0.f};
;                 acc = __builtin_amdgcn_mfma_f32_16x16x32_bf16(A1, B1[nt], acc, 0, 0, 0);
; #pragma unroll
;                 for (int reg = 0; reg < 4; ++reg) BUl[(4 * lq + reg) * 132 + 16 * nt + l15] = acc[reg];
;             }
;             asm volatile("s_waitcnt lgkmcnt(0)" ::: "memory");
; #pragma unroll 4
;             for (int jj = 0; jj < 16; ++jj) {
;                 const float br_ = BUl[jj * 132 + lane], bi_ = BUl[jj * 132 + 64 + lane];
;                 const float nr = ar * xr - ai * xi + br_, ni = ar * xi + ai * xr + bi_; xr = nr; xi = ni;
;                 if (FINAL) { BUl[jj * 132 + lane] = xr; BUl[jj * 132 + 64 + lane] = xi; }
.Ls5a_grp:
	s_lshl_b32 s15, s14, 2
	v_lshrrev_b32_e32 v244, 2, v236
	v_add_u32_e32 v244, s15, v244
	v_mul_u32_u24_e32 v245, 0xf1, v244
	v_lshrrev_b32_e32 v245, 14, v245
	v_mul_u32_u24_e32 v232, 68, v245
	v_sub_u32_e32 v244, v244, v232
	v_and_b32_e32 v232, 3, v236
	v_lshl_add_u32 v232, v244, 6, v232
	v_mov_b32_e32 v233, 0x11ff
	v_mov_b32_e32 v234, 0xff
	v_cmp_gt_u32_e32 vcc, 4, v244
	s_nop 1
	v_cndmask_b32_e32 v233, v233, v234, vcc
	v_sub_u32_e32 v233, v233, v232
	s_cmp_eq_u32 s9, 0
	s_cselect_b64 vcc, -1, 0
	s_nop 1
	v_cndmask_b32_e32 v232, v233, v232, vcc
	v_mul_u32_u24_e32 v245, 0x1100, v245
	v_add_u32_e32 v232, v232, v245
	s_lshl_b32 s16, s8, 5
	v_and_b32_e32 v233, 1, v237
	v_lshl_add_u32 v233, v233, 4, s16
	v_lshl_add_u32 v235, v232, 11, v233
	v_add_u32_e32 v244, s15, v237
	v_mul_u32_u24_e32 v245, 0xf1, v244
	v_lshrrev_b32_e32 v245, 14, v245
	v_mul_u32_u24_e32 v232, 68, v245
	v_sub_u32_e32 v244, v244, v232
	s_lshl_b32 s17, s9, 2
	v_add_u32_e32 v245, s17, v245
	v_lshl_add_u32 v245, v245, 6, s8
	v_mul_u32_u24_e32 v245, 68, v245
	v_add_u32_e32 v245, v245, v244
	v_lshl_add_u32 v245, v245, 6, v236
	v_lshlrev_b32_e32 v240, 3, v245
	s_add_i32 s54, s14, 16
	s_lshl_b32 s15, s54, 2
	v_lshrrev_b32_e32 v244, 2, v236
	v_add_u32_e32 v244, s15, v244
	v_mul_u32_u24_e32 v245, 0xf1, v244
	v_lshrrev_b32_e32 v245, 14, v245
	v_mul_u32_u24_e32 v232, 68, v245
	v_sub_u32_e32 v244, v244, v232
	v_and_b32_e32 v232, 3, v236
	v_lshl_add_u32 v232, v244, 6, v232
	v_mov_b32_e32 v233, 0x11ff
	v_mov_b32_e32 v234, 0xff
	v_cmp_gt_u32_e32 vcc, 4, v244
	s_nop 1
	v_cndmask_b32_e32 v233, v233, v234, vcc
	v_sub_u32_e32 v233, v233, v232
	s_cmp_eq_u32 s9, 0
	s_cselect_b64 vcc, -1, 0
	s_nop 1
	v_cndmask_b32_e32 v232, v233, v232, vcc
	v_mul_u32_u24_e32 v245, 0x1100, v245
	v_add_u32_e32 v232, v232, v245
	s_lshl_b32 s16, s8, 5
	v_and_b32_e32 v233, 1, v237
	v_lshl_add_u32 v233, v233, 4, s16
	v_lshl_add_u32 v238, v232, 11, v233
	s_waitcnt vmcnt(19)
	v_mov_b32_e32 v200, 0
	v_mov_b32_e32 v201, 0
	v_mov_b32_e32 v202, 0
	v_mov_b32_e32 v203, 0
	v_mov_b32_e32 v204, 0
	v_mov_b32_e32 v205, 0
	v_mov_b32_e32 v206, 0
	v_mov_b32_e32 v207, 0
	v_mfma_f32_16x16x32_bf16 v[136:139], v[56:59], v[0:3], 0
	v_mfma_f32_16x16x32_bf16 v[140:143], v[56:59], v[4:7], 0
	v_mfma_f32_16x16x32_bf16 v[144:147], v[56:59], v[8:11], 0
	v_mfma_f32_16x16x32_bf16 v[148:151], v[56:59], v[12:15], 0
	v_mfma_f32_16x16x32_bf16 v[152:155], v[56:59], v[16:19], 0
	v_mfma_f32_16x16x32_bf16 v[156:159], v[56:59], v[20:23], 0
	v_mfma_f32_16x16x32_bf16 v[160:163], v[56:59], v[24:27], 0
	v_mfma_f32_16x16x32_bf16 v[164:167], v[56:59], v[28:31], 0
	s_waitcnt vmcnt(18)
	v_pk_mov_b32 v[232:233], v[136:137], v[152:153] op_sel:[0,0]
	v_pk_mov_b32 v[234:235], v[140:141], v[156:157] op_sel:[0,0]
	v_pk_mov_b32 v[244:245], v[144:145], v[160:161] op_sel:[0,0]
	v_mfma_f32_16x16x32_bf16 v[168:171], v[60:63], v[0:3], 0
	v_pk_mov_b32 v[254:255], v[148:149], v[164:165] op_sel:[0,0]
	v_pk_fma_f32 v[232:233], v[32:33], v[200:201], v[232:233] op_sel_hi:[0,1,1]
	v_pk_fma_f32 v[234:235], v[34:35], v[202:203], v[234:235] op_sel_hi:[0,1,1]
	v_mfma_f32_16x16x32_bf16 v[172:175], v[60:63], v[4:7], 0
	v_pk_fma_f32 v[244:245], v[36:37], v[204:205], v[244:245] op_sel_hi:[0,1,1]
	v_pk_fma_f32 v[254:255], v[38:39], v[206:207], v[254:255] op_sel_hi:[0,1,1]
	v_pk_fma_f32 v[200:201], v[32:33], v[200:201], v[232:233] op_sel:[1,1,0] op_sel_hi:[1,0,1] neg_lo:[1,0,0]
	v_mfma_f32_16x16x32_bf16 v[176:179], v[60:63], v[8:11], 0
	v_pk_fma_f32 v[202:203], v[34:35], v[202:203], v[234:235] op_sel:[1,1,0] op_sel_hi:[1,0,1] neg_lo:[1,0,0]
	v_pk_fma_f32 v[204:205], v[36:37], v[204:205], v[244:245] op_sel:[1,1,0] op_sel_hi:[1,0,1] neg_lo:[1,0,0]
	v_pk_fma_f32 v[206:207], v[38:39], v[206:207], v[254:255] op_sel:[1,1,0] op_sel_hi:[1,0,1] neg_lo:[1,0,0]
	v_mfma_f32_16x16x32_bf16 v[180:183], v[60:63], v[12:15], 0
	v_pk_mov_b32 v[232:233], v[136:137], v[152:153] op_sel:[1,1]
	v_pk_mov_b32 v[234:235], v[140:141], v[156:157] op_sel:[1,1]
	v_pk_mov_b32 v[244:245], v[144:145], v[160:161] op_sel:[1,1]
	v_mfma_f32_16x16x32_bf16 v[184:187], v[60:63], v[16:19], 0
	v_pk_mov_b32 v[254:255], v[148:149], v[164:165] op_sel:[1,1]
	v_pk_fma_f32 v[232:233], v[32:33], v[200:201], v[232:233] op_sel_hi:[0,1,1]
	v_pk_fma_f32 v[234:235], v[34:35], v[202:203], v[234:235] op_sel_hi:[0,1,1]
	v_mfma_f32_16x16x32_bf16 v[188:191], v[60:63], v[20:23], 0
	v_pk_fma_f32 v[244:245], v[36:37], v[204:205], v[244:245] op_sel_hi:[0,1,1]
	v_pk_fma_f32 v[254:255], v[38:39], v[206:207], v[254:255] op_sel_hi:[0,1,1]
	v_pk_fma_f32 v[200:201], v[32:33], v[200:201], v[232:233] op_sel:[1,1,0] op_sel_hi:[1,0,1] neg_lo:[1,0,0]
	v_mfma_f32_16x16x32_bf16 v[192:195], v[60:63], v[24:27], 0
	v_pk_fma_f32 v[202:203], v[34:35], v[202:203], v[234:235] op_sel:[1,1,0] op_sel_hi:[1,0,1] neg_lo:[1,0,0]
	v_pk_fma_f32 v[204:205], v[36:37], v[204:205], v[244:245] op_sel:[1,1,0] op_sel_hi:[1,0,1] neg_lo:[1,0,0]
	v_pk_fma_f32 v[206:207], v[38:39], v[206:207], v[254:255] op_sel:[1,1,0] op_sel_hi:[1,0,1] neg_lo:[1,0,0]
	v_mfma_f32_16x16x32_bf16 v[196:199], v[60:63], v[28:31], 0
	v_pk_mov_b32 v[232:233], v[138:139], v[154:155] op_sel:[0,0]
	v_pk_mov_b32 v[234:235], v[142:143], v[158:159] op_sel:[0,0]
	v_pk_mov_b32 v[244:245], v[146:147], v[162:163] op_sel:[0,0]
	v_pk_mov_b32 v[254:255], v[150:151], v[166:167] op_sel:[0,0]
	v_pk_fma_f32 v[232:233], v[32:33], v[200:201], v[232:233] op_sel_hi:[0,1,1]
	v_pk_fma_f32 v[234:235], v[34:35], v[202:203], v[234:235] op_sel_hi:[0,1,1]
	v_pk_fma_f32 v[244:245], v[36:37], v[204:205], v[244:245] op_sel_hi:[0,1,1]
	v_pk_fma_f32 v[254:255], v[38:39], v[206:207], v[254:255] op_sel_hi:[0,1,1]
; template <bool FINAL> __device__ __forceinline__ void phase_s5_scan(const Fr& F) {
;     ...
;         for (int sub = 0; sub < 4; ++sub) {
;             const bf16x8 A1 = __builtin_bit_cast(bf16x8, uc[sub]);
; #pragma unroll
;             for (int nt = 0; nt < 8; ++nt) {
;                 f32x4 acc = {0.f, 0.f, 0.f, 0.f};
;                 acc = __builtin_amdgcn_mfma_f32_16x16x32_bf16(A1, B1[nt], acc, 0, 0, 0);
; #pragma unroll
;                 for (int reg = 0; reg < 4; ++reg) BUl[(4 * lq + reg) * 132 + 16 * nt + l15] = acc[reg];
;             }
;             asm volatile("s_waitcnt lgkmcnt(0)" ::: "memory");
; #pragma unroll 4
;             for (int jj = 0; jj < 16; ++jj) {
;                 const float br_ = BUl[jj * 132 + lane], bi_ = BUl[jj * 132 + 64 + lane];
;                 const float nr = ar * xr - ai * xi + br_, ni = ar * xi + ai * xr + bi_; xr = nr; xi = ni;
	v_pk_fma_f32 v[200:201], v[32:33], v[200:201], v[232:233] op_sel:[1,1,0] op_sel_hi:[1,0,1] neg_lo:[1,0,0]
	v_pk_fma_f32 v[202:203], v[34:35], v[202:203], v[234:235] op_sel:[1,1,0] op_sel_hi:[1,0,1] neg_lo:[1,0,0]
	v_pk_fma_f32 v[204:205], v[36:37], v[204:205], v[244:245] op_sel:[1,1,0] op_sel_hi:[1,0,1] neg_lo:[1,0,0]
	v_pk_fma_f32 v[206:207], v[38:39], v[206:207], v[254:255] op_sel:[1,1,0] op_sel_hi:[1,0,1] neg_lo:[1,0,0]
	v_pk_mov_b32 v[232:233], v[138:139], v[154:155] op_sel:[1,1]
	v_pk_mov_b32 v[234:235], v[142:143], v[158:159] op_sel:[1,1]
	v_pk_mov_b32 v[244:245], v[146:147], v[162:163] op_sel:[1,1]
	v_pk_mov_b32 v[254:255], v[150:151], v[166:167] op_sel:[1,1]
	v_pk_fma_f32 v[232:233], v[32:33], v[200:201], v[232:233] op_sel_hi:[0,1,1]
	v_pk_fma_f32 v[234:235], v[34:35], v[202:203], v[234:235] op_sel_hi:[0,1,1]
	v_pk_fma_f32 v[244:245], v[36:37], v[204:205], v[244:245] op_sel_hi:[0,1,1]
	v_pk_fma_f32 v[254:255], v[38:39], v[206:207], v[254:255] op_sel_hi:[0,1,1]
	v_pk_fma_f32 v[200:201], v[32:33], v[200:201], v[232:233] op_sel:[1,1,0] op_sel_hi:[1,0,1] neg_lo:[1,0,0]
	v_pk_fma_f32 v[202:203], v[34:35], v[202:203], v[234:235] op_sel:[1,1,0] op_sel_hi:[1,0,1] neg_lo:[1,0,0]
	v_pk_fma_f32 v[204:205], v[36:37], v[204:205], v[244:245] op_sel:[1,1,0] op_sel_hi:[1,0,1] neg_lo:[1,0,0]
	v_pk_fma_f32 v[206:207], v[38:39], v[206:207], v[254:255] op_sel:[1,1,0] op_sel_hi:[1,0,1] neg_lo:[1,0,0]
	global_load_dwordx4 v[56:59], v238, s[20:21]
	v_add_u32_e32 v238, v238, v243
	s_waitcnt vmcnt(18)
	v_pk_mov_b32 v[232:233], v[168:169], v[184:185] op_sel:[0,0]
	v_pk_mov_b32 v[234:235], v[172:173], v[188:189] op_sel:[0,0]
	v_pk_mov_b32 v[244:245], v[176:177], v[192:193] op_sel:[0,0]
	v_mfma_f32_16x16x32_bf16 v[136:139], v[64:67], v[0:3], 0
	v_pk_mov_b32 v[254:255], v[180:181], v[196:197] op_sel:[0,0]
	v_pk_fma_f32 v[232:233], v[32:33], v[200:201], v[232:233] op_sel_hi:[0,1,1]
	v_pk_fma_f32 v[234:235], v[34:35], v[202:203], v[234:235] op_sel_hi:[0,1,1]
	v_mfma_f32_16x16x32_bf16 v[140:143], v[64:67], v[4:7], 0
	v_pk_fma_f32 v[244:245], v[36:37], v[204:205], v[244:245] op_sel_hi:[0,1,1]
	v_pk_fma_f32 v[254:255], v[38:39], v[206:207], v[254:255] op_sel_hi:[0,1,1]
	v_pk_fma_f32 v[200:201], v[32:33], v[200:201], v[232:233] op_sel:[1,1,0] op_sel_hi:[1,0,1] neg_lo:[1,0,0]
	v_mfma_f32_16x16x32_bf16 v[144:147], v[64:67], v[8:11], 0
	v_pk_fma_f32 v[202:203], v[34:35], v[202:203], v[234:235] op_sel:[1,1,0] op_sel_hi:[1,0,1] neg_lo:[1,0,0]
	v_pk_fma_f32 v[204:205], v[36:37], v[204:205], v[244:245] op_sel:[1,1,0] op_sel_hi:[1,0,1] neg_lo:[1,0,0]
	v_pk_fma_f32 v[206:207], v[38:39], v[206:207], v[254:255] op_sel:[1,1,0] op_sel_hi:[1,0,1] neg_lo:[1,0,0]
	v_mfma_f32_16x16x32_bf16 v[148:151], v[64:67], v[12:15], 0
	v_pk_mov_b32 v[232:233], v[168:169], v[184:185] op_sel:[1,1]
	v_pk_mov_b32 v[234:235], v[172:173], v[188:189] op_sel:[1,1]
	v_pk_mov_b32 v[244:245], v[176:177], v[192:193] op_sel:[1,1]
	v_mfma_f32_16x16x32_bf16 v[152:155], v[64:67], v[16:19], 0
	v_pk_mov_b32 v[254:255], v[180:181], v[196:197] op_sel:[1,1]
	v_pk_fma_f32 v[232:233], v[32:33], v[200:201], v[232:233] op_sel_hi:[0,1,1]
	v_pk_fma_f32 v[234:235], v[34:35], v[202:203], v[234:235] op_sel_hi:[0,1,1]
	v_mfma_f32_16x16x32_bf16 v[156:159], v[64:67], v[20:23], 0
	v_pk_fma_f32 v[244:245], v[36:37], v[204:205], v[244:245] op_sel_hi:[0,1,1]
	v_pk_fma_f32 v[254:255], v[38:39], v[206:207], v[254:255] op_sel_hi:[0,1,1]
	v_pk_fma_f32 v[200:201], v[32:33], v[200:201], v[232:233] op_sel:[1,1,0] op_sel_hi:[1,0,1] neg_lo:[1,0,0]
	v_mfma_f32_16x16x32_bf16 v[160:163], v[64:67], v[24:27], 0
	v_pk_fma_f32 v[202:203], v[34:35], v[202:203], v[234:235] op_sel:[1,1,0] op_sel_hi:[1,0,1] neg_lo:[1,0,0]
	v_pk_fma_f32 v[204:205], v[36:37], v[204:205], v[244:245] op_sel:[1,1,0] op_sel_hi:[1,0,1] neg_lo:[1,0,0]
	v_pk_fma_f32 v[206:207], v[38:39], v[206:207], v[254:255] op_sel:[1,1,0] op_sel_hi:[1,0,1] neg_lo:[1,0,0]
	v_mfma_f32_16x16x32_bf16 v[164:167], v[64:67], v[28:31], 0
	v_pk_mov_b32 v[232:233], v[170:171], v[186:187] op_sel:[0,0]
	v_pk_mov_b32 v[234:235], v[174:175], v[190:191] op_sel:[0,0]
	v_pk_mov_b32 v[244:245], v[178:179], v[194:195] op_sel:[0,0]
	v_pk_mov_b32 v[254:255], v[182:183], v[198:199] op_sel:[0,0]
	v_pk_fma_f32 v[232:233], v[32:33], v[200:201], v[232:233] op_sel_hi:[0,1,1]
	v_pk_fma_f32 v[234:235], v[34:35], v[202:203], v[234:235] op_sel_hi:[0,1,1]
	v_pk_fma_f32 v[244:245], v[36:37], v[204:205], v[244:245] op_sel_hi:[0,1,1]
	v_pk_fma_f32 v[254:255], v[38:39], v[206:207], v[254:255] op_sel_hi:[0,1,1]
	v_pk_fma_f32 v[200:201], v[32:33], v[200:201], v[232:233] op_sel:[1,1,0] op_sel_hi:[1,0,1] neg_lo:[1,0,0]
	v_pk_fma_f32 v[202:203], v[34:35], v[202:203], v[234:235] op_sel:[1,1,0] op_sel_hi:[1,0,1] neg_lo:[1,0,0]
	v_pk_fma_f32 v[204:205], v[36:37], v[204:205], v[244:245] op_sel:[1,1,0] op_sel_hi:[1,0,1] neg_lo:[1,0,0]
	v_pk_fma_f32 v[206:207], v[38:39], v[206:207], v[254:255] op_sel:[1,1,0] op_sel_hi:[1,0,1] neg_lo:[1,0,0]
	v_pk_mov_b32 v[232:233], v[170:171], v[186:187] op_sel:[1,1]
	v_pk_mov_b32 v[234:235], v[174:175], v[190:191] op_sel:[1,1]
	v_pk_mov_b32 v[244:245], v[178:179], v[194:195] op_sel:[1,1]
	v_pk_mov_b32 v[254:255], v[182:183], v[198:199] op_sel:[1,1]
	v_pk_fma_f32 v[232:233], v[32:33], v[200:201], v[232:233] op_sel_hi:[0,1,1]
	v_pk_fma_f32 v[234:235], v[34:35], v[202:203], v[234:235] op_sel_hi:[0,1,1]
	v_pk_fma_f32 v[244:245], v[36:37], v[204:205], v[244:245] op_sel_hi:[0,1,1]
	v_pk_fma_f32 v[254:255], v[38:39], v[206:207], v[254:255] op_sel_hi:[0,1,1]
	v_pk_fma_f32 v[200:201], v[32:33], v[200:201], v[232:233] op_sel:[1,1,0] op_sel_hi:[1,0,1] neg_lo:[1,0,0]
	v_pk_fma_f32 v[202:203], v[34:35], v[202:203], v[234:235] op_sel:[1,1,0] op_sel_hi:[1,0,1] neg_lo:[1,0,0]
	v_pk_fma_f32 v[204:205], v[36:37], v[204:205], v[244:245] op_sel:[1,1,0] op_sel_hi:[1,0,1] neg_lo:[1,0,0]
	v_pk_fma_f32 v[206:207], v[38:39], v[206:207], v[254:255] op_sel:[1,1,0] op_sel_hi:[1,0,1] neg_lo:[1,0,0]
	global_load_dwordx4 v[60:63], v238, s[20:21]
	v_add_u32_e32 v238, v238, v243
	s_waitcnt vmcnt(18)
; template <bool FINAL> __device__ __forceinline__ void phase_s5_scan(const Fr& F) {
;     ...
;         for (int sub = 0; sub < 4; ++sub) {
;             const bf16x8 A1 = __builtin_bit_cast(bf16x8, uc[sub]);
; #pragma unroll
;             for (int nt = 0; nt < 8; ++nt) {
;                 f32x4 acc = {0.f, 0.f, 0.f, 0.f};
;                 acc = __builtin_amdgcn_mfma_f32_16x16x32_bf16(A1, B1[nt], acc, 0, 0, 0);
; #pragma unroll
;                 for (int reg = 0; reg < 4; ++reg) BUl[(4 * lq + reg) * 132 + 16 * nt + l15] = acc[reg];
;             }
;             asm volatile("s_waitcnt lgkmcnt(0)" ::: "memory");
; #pragma unroll 4
;             for (int jj = 0; jj < 16; ++jj) {
;                 const float br_ = BUl[jj * 132 + lane], bi_ = BUl[jj * 132 + 64 + lane];
;                 const float nr = ar * xr - ai * xi + br_, ni = ar * xi + ai * xr + bi_; xr = nr; xi = ni;
	v_pk_mov_b32 v[232:233], v[136:137], v[152:153] op_sel:[0,0]
	v_pk_mov_b32 v[234:235], v[140:141], v[156:157] op_sel:[0,0]
	v_pk_mov_b32 v[244:245], v[144:145], v[160:161] op_sel:[0,0]
	v_mfma_f32_16x16x32_bf16 v[168:171], v[68:71], v[0:3], 0
	v_pk_mov_b32 v[254:255], v[148:149], v[164:165] op_sel:[0,0]
	v_pk_fma_f32 v[232:233], v[32:33], v[200:201], v[232:233] op_sel_hi:[0,1,1]
	v_pk_fma_f32 v[234:235], v[34:35], v[202:203], v[234:235] op_sel_hi:[0,1,1]
	v_mfma_f32_16x16x32_bf16 v[172:175], v[68:71], v[4:7], 0
	v_pk_fma_f32 v[244:245], v[36:37], v[204:205], v[244:245] op_sel_hi:[0,1,1]
	v_pk_fma_f32 v[254:255], v[38:39], v[206:207], v[254:255] op_sel_hi:[0,1,1]
	v_pk_fma_f32 v[200:201], v[32:33], v[200:201], v[232:233] op_sel:[1,1,0] op_sel_hi:[1,0,1] neg_lo:[1,0,0]
	v_mfma_f32_16x16x32_bf16 v[176:179], v[68:71], v[8:11], 0
	v_pk_fma_f32 v[202:203], v[34:35], v[202:203], v[234:235] op_sel:[1,1,0] op_sel_hi:[1,0,1] neg_lo:[1,0,0]
	v_pk_fma_f32 v[204:205], v[36:37], v[204:205], v[244:245] op_sel:[1,1,0] op_sel_hi:[1,0,1] neg_lo:[1,0,0]
	v_pk_fma_f32 v[206:207], v[38:39], v[206:207], v[254:255] op_sel:[1,1,0] op_sel_hi:[1,0,1] neg_lo:[1,0,0]
	v_mfma_f32_16x16x32_bf16 v[180:183], v[68:71], v[12:15], 0
	v_pk_mov_b32 v[232:233], v[136:137], v[152:153] op_sel:[1,1]
	v_pk_mov_b32 v[234:235], v[140:141], v[156:157] op_sel:[1,1]
	v_pk_mov_b32 v[244:245], v[144:145], v[160:161] op_sel:[1,1]
	v_mfma_f32_16x16x32_bf16 v[184:187], v[68:71], v[16:19], 0
	v_pk_mov_b32 v[254:255], v[148:149], v[164:165] op_sel:[1,1]
	v_pk_fma_f32 v[232:233], v[32:33], v[200:201], v[232:233] op_sel_hi:[0,1,1]
	v_pk_fma_f32 v[234:235], v[34:35], v[202:203], v[234:235] op_sel_hi:[0,1,1]
	v_mfma_f32_16x16x32_bf16 v[188:191], v[68:71], v[20:23], 0
	v_pk_fma_f32 v[244:245], v[36:37], v[204:205], v[244:245] op_sel_hi:[0,1,1]
	v_pk_fma_f32 v[254:255], v[38:39], v[206:207], v[254:255] op_sel_hi:[0,1,1]
	v_pk_fma_f32 v[200:201], v[32:33], v[200:201], v[232:233] op_sel:[1,1,0] op_sel_hi:[1,0,1] neg_lo:[1,0,0]
	v_mfma_f32_16x16x32_bf16 v[192:195], v[68:71], v[24:27], 0
	v_pk_fma_f32 v[202:203], v[34:35], v[202:203], v[234:235] op_sel:[1,1,0] op_sel_hi:[1,0,1] neg_lo:[1,0,0]
	v_pk_fma_f32 v[204:205], v[36:37], v[204:205], v[244:245] op_sel:[1,1,0] op_sel_hi:[1,0,1] neg_lo:[1,0,0]
	v_pk_fma_f32 v[206:207], v[38:39], v[206:207], v[254:255] op_sel:[1,1,0] op_sel_hi:[1,0,1] neg_lo:[1,0,0]
	v_mfma_f32_16x16x32_bf16 v[196:199], v[68:71], v[28:31], 0
	v_pk_mov_b32 v[232:233], v[138:139], v[154:155] op_sel:[0,0]
	v_pk_mov_b32 v[234:235], v[142:143], v[158:159] op_sel:[0,0]
	v_pk_mov_b32 v[244:245], v[146:147], v[162:163] op_sel:[0,0]
	v_pk_mov_b32 v[254:255], v[150:151], v[166:167] op_sel:[0,0]
	v_pk_fma_f32 v[232:233], v[32:33], v[200:201], v[232:233] op_sel_hi:[0,1,1]
	v_pk_fma_f32 v[234:235], v[34:35], v[202:203], v[234:235] op_sel_hi:[0,1,1]
	v_pk_fma_f32 v[244:245], v[36:37], v[204:205], v[244:245] op_sel_hi:[0,1,1]
	v_pk_fma_f32 v[254:255], v[38:39], v[206:207], v[254:255] op_sel_hi:[0,1,1]
	v_pk_fma_f32 v[200:201], v[32:33], v[200:201], v[232:233] op_sel:[1,1,0] op_sel_hi:[1,0,1] neg_lo:[1,0,0]
	v_pk_fma_f32 v[202:203], v[34:35], v[202:203], v[234:235] op_sel:[1,1,0] op_sel_hi:[1,0,1] neg_lo:[1,0,0]
	v_pk_fma_f32 v[204:205], v[36:37], v[204:205], v[244:245] op_sel:[1,1,0] op_sel_hi:[1,0,1] neg_lo:[1,0,0]
	v_pk_fma_f32 v[206:207], v[38:39], v[206:207], v[254:255] op_sel:[1,1,0] op_sel_hi:[1,0,1] neg_lo:[1,0,0]
	v_pk_mov_b32 v[232:233], v[138:139], v[154:155] op_sel:[1,1]
	v_pk_mov_b32 v[234:235], v[142:143], v[158:159] op_sel:[1,1]
	v_pk_mov_b32 v[244:245], v[146:147], v[162:163] op_sel:[1,1]
	v_pk_mov_b32 v[254:255], v[150:151], v[166:167] op_sel:[1,1]
	v_pk_fma_f32 v[232:233], v[32:33], v[200:201], v[232:233] op_sel_hi:[0,1,1]
	v_pk_fma_f32 v[234:235], v[34:35], v[202:203], v[234:235] op_sel_hi:[0,1,1]
	v_pk_fma_f32 v[244:245], v[36:37], v[204:205], v[244:245] op_sel_hi:[0,1,1]
	v_pk_fma_f32 v[254:255], v[38:39], v[206:207], v[254:255] op_sel_hi:[0,1,1]
	v_pk_fma_f32 v[200:201], v[32:33], v[200:201], v[232:233] op_sel:[1,1,0] op_sel_hi:[1,0,1] neg_lo:[1,0,0]
	v_pk_fma_f32 v[202:203], v[34:35], v[202:203], v[234:235] op_sel:[1,1,0] op_sel_hi:[1,0,1] neg_lo:[1,0,0]
	v_pk_fma_f32 v[204:205], v[36:37], v[204:205], v[244:245] op_sel:[1,1,0] op_sel_hi:[1,0,1] neg_lo:[1,0,0]
	v_pk_fma_f32 v[206:207], v[38:39], v[206:207], v[254:255] op_sel:[1,1,0] op_sel_hi:[1,0,1] neg_lo:[1,0,0]
	global_load_dwordx4 v[64:67], v238, s[20:21]
	v_add_u32_e32 v238, v238, v243
	s_waitcnt vmcnt(18)
; template <bool FINAL> __device__ __forceinline__ void phase_s5_scan(const Fr& F) {
;     ...
;         for (int sub = 0; sub < 4; ++sub) {
;             const bf16x8 A1 = __builtin_bit_cast(bf16x8, uc[sub]);
; #pragma unroll
;             for (int nt = 0; nt < 8; ++nt) {
;                 f32x4 acc = {0.f, 0.f, 0.f, 0.f};
;                 acc = __builtin_amdgcn_mfma_f32_16x16x32_bf16(A1, B1[nt], acc, 0, 0, 0);
; #pragma unroll
;                 for (int reg = 0; reg < 4; ++reg) BUl[(4 * lq + reg) * 132 + 16 * nt + l15] = acc[reg];
;             }
;             asm volatile("s_waitcnt lgkmcnt(0)" ::: "memory");
; #pragma unroll 4
;             for (int jj = 0; jj < 16; ++jj) {
;                 const float br_ = BUl[jj * 132 + lane], bi_ = BUl[jj * 132 + 64 + lane];
;                 const float nr = ar * xr - ai * xi + br_, ni = ar * xi + ai * xr + bi_; xr = nr; xi = ni;
	v_pk_mov_b32 v[232:233], v[168:169], v[184:185] op_sel:[0,0]
	v_pk_mov_b32 v[234:235], v[172:173], v[188:189] op_sel:[0,0]
	v_pk_mov_b32 v[244:245], v[176:177], v[192:193] op_sel:[0,0]
	v_mfma_f32_16x16x32_bf16 v[136:139], v[72:75], v[0:3], 0
	v_pk_mov_b32 v[254:255], v[180:181], v[196:197] op_sel:[0,0]
	v_pk_fma_f32 v[232:233], v[32:33], v[200:201], v[232:233] op_sel_hi:[0,1,1]
	v_pk_fma_f32 v[234:235], v[34:35], v[202:203], v[234:235] op_sel_hi:[0,1,1]
	v_mfma_f32_16x16x32_bf16 v[140:143], v[72:75], v[4:7], 0
	v_pk_fma_f32 v[244:245], v[36:37], v[204:205], v[244:245] op_sel_hi:[0,1,1]
	v_pk_fma_f32 v[254:255], v[38:39], v[206:207], v[254:255] op_sel_hi:[0,1,1]
	v_pk_fma_f32 v[200:201], v[32:33], v[200:201], v[232:233] op_sel:[1,1,0] op_sel_hi:[1,0,1] neg_lo:[1,0,0]
	v_mfma_f32_16x16x32_bf16 v[144:147], v[72:75], v[8:11], 0
	v_pk_fma_f32 v[202:203], v[34:35], v[202:203], v[234:235] op_sel:[1,1,0] op_sel_hi:[1,0,1] neg_lo:[1,0,0]
	v_pk_fma_f32 v[204:205], v[36:37], v[204:205], v[244:245] op_sel:[1,1,0] op_sel_hi:[1,0,1] neg_lo:[1,0,0]
	v_pk_fma_f32 v[206:207], v[38:39], v[206:207], v[254:255] op_sel:[1,1,0] op_sel_hi:[1,0,1] neg_lo:[1,0,0]
	v_mfma_f32_16x16x32_bf16 v[148:151], v[72:75], v[12:15], 0
	v_pk_mov_b32 v[232:233], v[168:169], v[184:185] op_sel:[1,1]
	v_pk_mov_b32 v[234:235], v[172:173], v[188:189] op_sel:[1,1]
	v_pk_mov_b32 v[244:245], v[176:177], v[192:193] op_sel:[1,1]
	v_mfma_f32_16x16x32_bf16 v[152:155], v[72:75], v[16:19], 0
	v_pk_mov_b32 v[254:255], v[180:181], v[196:197] op_sel:[1,1]
	v_pk_fma_f32 v[232:233], v[32:33], v[200:201], v[232:233] op_sel_hi:[0,1,1]
	v_pk_fma_f32 v[234:235], v[34:35], v[202:203], v[234:235] op_sel_hi:[0,1,1]
	v_mfma_f32_16x16x32_bf16 v[156:159], v[72:75], v[20:23], 0
	v_pk_fma_f32 v[244:245], v[36:37], v[204:205], v[244:245] op_sel_hi:[0,1,1]
	v_pk_fma_f32 v[254:255], v[38:39], v[206:207], v[254:255] op_sel_hi:[0,1,1]
	v_pk_fma_f32 v[200:201], v[32:33], v[200:201], v[232:233] op_sel:[1,1,0] op_sel_hi:[1,0,1] neg_lo:[1,0,0]
	v_mfma_f32_16x16x32_bf16 v[160:163], v[72:75], v[24:27], 0
	v_pk_fma_f32 v[202:203], v[34:35], v[202:203], v[234:235] op_sel:[1,1,0] op_sel_hi:[1,0,1] neg_lo:[1,0,0]
	v_pk_fma_f32 v[204:205], v[36:37], v[204:205], v[244:245] op_sel:[1,1,0] op_sel_hi:[1,0,1] neg_lo:[1,0,0]
	v_pk_fma_f32 v[206:207], v[38:39], v[206:207], v[254:255] op_sel:[1,1,0] op_sel_hi:[1,0,1] neg_lo:[1,0,0]
	v_mfma_f32_16x16x32_bf16 v[164:167], v[72:75], v[28:31], 0
	v_pk_mov_b32 v[232:233], v[170:171], v[186:187] op_sel:[0,0]
	v_pk_mov_b32 v[234:235], v[174:175], v[190:191] op_sel:[0,0]
	v_pk_mov_b32 v[244:245], v[178:179], v[194:195] op_sel:[0,0]
	v_pk_mov_b32 v[254:255], v[182:183], v[198:199] op_sel:[0,0]
	v_pk_fma_f32 v[232:233], v[32:33], v[200:201], v[232:233] op_sel_hi:[0,1,1]
	v_pk_fma_f32 v[234:235], v[34:35], v[202:203], v[234:235] op_sel_hi:[0,1,1]
	v_pk_fma_f32 v[244:245], v[36:37], v[204:205], v[244:245] op_sel_hi:[0,1,1]
	v_pk_fma_f32 v[254:255], v[38:39], v[206:207], v[254:255] op_sel_hi:[0,1,1]
	v_pk_fma_f32 v[200:201], v[32:33], v[200:201], v[232:233] op_sel:[1,1,0] op_sel_hi:[1,0,1] neg_lo:[1,0,0]
	v_pk_fma_f32 v[202:203], v[34:35], v[202:203], v[234:235] op_sel:[1,1,0] op_sel_hi:[1,0,1] neg_lo:[1,0,0]
	v_pk_fma_f32 v[204:205], v[36:37], v[204:205], v[244:245] op_sel:[1,1,0] op_sel_hi:[1,0,1] neg_lo:[1,0,0]
	v_pk_fma_f32 v[206:207], v[38:39], v[206:207], v[254:255] op_sel:[1,1,0] op_sel_hi:[1,0,1] neg_lo:[1,0,0]
	v_pk_mov_b32 v[232:233], v[170:171], v[186:187] op_sel:[1,1]
	v_pk_mov_b32 v[234:235], v[174:175], v[190:191] op_sel:[1,1]
	v_pk_mov_b32 v[244:245], v[178:179], v[194:195] op_sel:[1,1]
	v_pk_mov_b32 v[254:255], v[182:183], v[198:199] op_sel:[1,1]
	v_pk_fma_f32 v[232:233], v[32:33], v[200:201], v[232:233] op_sel_hi:[0,1,1]
	v_pk_fma_f32 v[234:235], v[34:35], v[202:203], v[234:235] op_sel_hi:[0,1,1]
	v_pk_fma_f32 v[244:245], v[36:37], v[204:205], v[244:245] op_sel_hi:[0,1,1]
	v_pk_fma_f32 v[254:255], v[38:39], v[206:207], v[254:255] op_sel_hi:[0,1,1]
	v_pk_fma_f32 v[200:201], v[32:33], v[200:201], v[232:233] op_sel:[1,1,0] op_sel_hi:[1,0,1] neg_lo:[1,0,0]
	v_pk_fma_f32 v[202:203], v[34:35], v[202:203], v[234:235] op_sel:[1,1,0] op_sel_hi:[1,0,1] neg_lo:[1,0,0]
	v_pk_fma_f32 v[204:205], v[36:37], v[204:205], v[244:245] op_sel:[1,1,0] op_sel_hi:[1,0,1] neg_lo:[1,0,0]
	v_pk_fma_f32 v[206:207], v[38:39], v[206:207], v[254:255] op_sel:[1,1,0] op_sel_hi:[1,0,1] neg_lo:[1,0,0]
	global_load_dwordx4 v[68:71], v238, s[20:21]
	v_add_u32_e32 v238, v238, v243
	s_waitcnt vmcnt(18)
; template <bool FINAL> __device__ __forceinline__ void phase_s5_scan(const Fr& F) {
;     ...
;         for (int sub = 0; sub < 4; ++sub) {
;             const bf16x8 A1 = __builtin_bit_cast(bf16x8, uc[sub]);
; #pragma unroll
;             for (int nt = 0; nt < 8; ++nt) {
;                 f32x4 acc = {0.f, 0.f, 0.f, 0.f};
;                 acc = __builtin_amdgcn_mfma_f32_16x16x32_bf16(A1, B1[nt], acc, 0, 0, 0);
; #pragma unroll
;                 for (int reg = 0; reg < 4; ++reg) BUl[(4 * lq + reg) * 132 + 16 * nt + l15] = acc[reg];
;             }
;             asm volatile("s_waitcnt lgkmcnt(0)" ::: "memory");
; #pragma unroll 4
;             for (int jj = 0; jj < 16; ++jj) {
;                 const float br_ = BUl[jj * 132 + lane], bi_ = BUl[jj * 132 + 64 + lane];
;                 const float nr = ar * xr - ai * xi + br_, ni = ar * xi + ai * xr + bi_; xr = nr; xi = ni;
	v_pk_mov_b32 v[232:233], v[136:137], v[152:153] op_sel:[0,0]
	v_pk_mov_b32 v[234:235], v[140:141], v[156:157] op_sel:[0,0]
	v_pk_mov_b32 v[244:245], v[144:145], v[160:161] op_sel:[0,0]
	v_mfma_f32_16x16x32_bf16 v[168:171], v[76:79], v[0:3], 0
	v_pk_mov_b32 v[254:255], v[148:149], v[164:165] op_sel:[0,0]
	v_pk_fma_f32 v[232:233], v[32:33], v[200:201], v[232:233] op_sel_hi:[0,1,1]
	v_pk_fma_f32 v[234:235], v[34:35], v[202:203], v[234:235] op_sel_hi:[0,1,1]
	v_mfma_f32_16x16x32_bf16 v[172:175], v[76:79], v[4:7], 0
	v_pk_fma_f32 v[244:245], v[36:37], v[204:205], v[244:245] op_sel_hi:[0,1,1]
	v_pk_fma_f32 v[254:255], v[38:39], v[206:207], v[254:255] op_sel_hi:[0,1,1]
	v_pk_fma_f32 v[200:201], v[32:33], v[200:201], v[232:233] op_sel:[1,1,0] op_sel_hi:[1,0,1] neg_lo:[1,0,0]
	v_mfma_f32_16x16x32_bf16 v[176:179], v[76:79], v[8:11], 0
	v_pk_fma_f32 v[202:203], v[34:35], v[202:203], v[234:235] op_sel:[1,1,0] op_sel_hi:[1,0,1] neg_lo:[1,0,0]
	v_pk_fma_f32 v[204:205], v[36:37], v[204:205], v[244:245] op_sel:[1,1,0] op_sel_hi:[1,0,1] neg_lo:[1,0,0]
	v_pk_fma_f32 v[206:207], v[38:39], v[206:207], v[254:255] op_sel:[1,1,0] op_sel_hi:[1,0,1] neg_lo:[1,0,0]
	v_mfma_f32_16x16x32_bf16 v[180:183], v[76:79], v[12:15], 0
	v_pk_mov_b32 v[232:233], v[136:137], v[152:153] op_sel:[1,1]
	v_pk_mov_b32 v[234:235], v[140:141], v[156:157] op_sel:[1,1]
	v_pk_mov_b32 v[244:245], v[144:145], v[160:161] op_sel:[1,1]
	v_mfma_f32_16x16x32_bf16 v[184:187], v[76:79], v[16:19], 0
	v_pk_mov_b32 v[254:255], v[148:149], v[164:165] op_sel:[1,1]
	v_pk_fma_f32 v[232:233], v[32:33], v[200:201], v[232:233] op_sel_hi:[0,1,1]
	v_pk_fma_f32 v[234:235], v[34:35], v[202:203], v[234:235] op_sel_hi:[0,1,1]
	v_mfma_f32_16x16x32_bf16 v[188:191], v[76:79], v[20:23], 0
	v_pk_fma_f32 v[244:245], v[36:37], v[204:205], v[244:245] op_sel_hi:[0,1,1]
	v_pk_fma_f32 v[254:255], v[38:39], v[206:207], v[254:255] op_sel_hi:[0,1,1]
	v_pk_fma_f32 v[200:201], v[32:33], v[200:201], v[232:233] op_sel:[1,1,0] op_sel_hi:[1,0,1] neg_lo:[1,0,0]
	v_mfma_f32_16x16x32_bf16 v[192:195], v[76:79], v[24:27], 0
	v_pk_fma_f32 v[202:203], v[34:35], v[202:203], v[234:235] op_sel:[1,1,0] op_sel_hi:[1,0,1] neg_lo:[1,0,0]
	v_pk_fma_f32 v[204:205], v[36:37], v[204:205], v[244:245] op_sel:[1,1,0] op_sel_hi:[1,0,1] neg_lo:[1,0,0]
	v_pk_fma_f32 v[206:207], v[38:39], v[206:207], v[254:255] op_sel:[1,1,0] op_sel_hi:[1,0,1] neg_lo:[1,0,0]
	v_mfma_f32_16x16x32_bf16 v[196:199], v[76:79], v[28:31], 0
	v_pk_mov_b32 v[232:233], v[138:139], v[154:155] op_sel:[0,0]
	v_pk_mov_b32 v[234:235], v[142:143], v[158:159] op_sel:[0,0]
	v_pk_mov_b32 v[244:245], v[146:147], v[162:163] op_sel:[0,0]
	v_pk_mov_b32 v[254:255], v[150:151], v[166:167] op_sel:[0,0]
	v_pk_fma_f32 v[232:233], v[32:33], v[200:201], v[232:233] op_sel_hi:[0,1,1]
	v_pk_fma_f32 v[234:235], v[34:35], v[202:203], v[234:235] op_sel_hi:[0,1,1]
	v_pk_fma_f32 v[244:245], v[36:37], v[204:205], v[244:245] op_sel_hi:[0,1,1]
	v_pk_fma_f32 v[254:255], v[38:39], v[206:207], v[254:255] op_sel_hi:[0,1,1]
	v_pk_fma_f32 v[200:201], v[32:33], v[200:201], v[232:233] op_sel:[1,1,0] op_sel_hi:[1,0,1] neg_lo:[1,0,0]
	v_pk_fma_f32 v[202:203], v[34:35], v[202:203], v[234:235] op_sel:[1,1,0] op_sel_hi:[1,0,1] neg_lo:[1,0,0]
	v_pk_fma_f32 v[204:205], v[36:37], v[204:205], v[244:245] op_sel:[1,1,0] op_sel_hi:[1,0,1] neg_lo:[1,0,0]
	v_pk_fma_f32 v[206:207], v[38:39], v[206:207], v[254:255] op_sel:[1,1,0] op_sel_hi:[1,0,1] neg_lo:[1,0,0]
	v_pk_mov_b32 v[232:233], v[138:139], v[154:155] op_sel:[1,1]
	v_pk_mov_b32 v[234:235], v[142:143], v[158:159] op_sel:[1,1]
	v_pk_mov_b32 v[244:245], v[146:147], v[162:163] op_sel:[1,1]
	v_pk_mov_b32 v[254:255], v[150:151], v[166:167] op_sel:[1,1]
	v_pk_fma_f32 v[232:233], v[32:33], v[200:201], v[232:233] op_sel_hi:[0,1,1]
	v_pk_fma_f32 v[234:235], v[34:35], v[202:203], v[234:235] op_sel_hi:[0,1,1]
	v_pk_fma_f32 v[244:245], v[36:37], v[204:205], v[244:245] op_sel_hi:[0,1,1]
	v_pk_fma_f32 v[254:255], v[38:39], v[206:207], v[254:255] op_sel_hi:[0,1,1]
	v_pk_fma_f32 v[200:201], v[32:33], v[200:201], v[232:233] op_sel:[1,1,0] op_sel_hi:[1,0,1] neg_lo:[1,0,0]
	v_pk_fma_f32 v[202:203], v[34:35], v[202:203], v[234:235] op_sel:[1,1,0] op_sel_hi:[1,0,1] neg_lo:[1,0,0]
	v_pk_fma_f32 v[204:205], v[36:37], v[204:205], v[244:245] op_sel:[1,1,0] op_sel_hi:[1,0,1] neg_lo:[1,0,0]
	v_pk_fma_f32 v[206:207], v[38:39], v[206:207], v[254:255] op_sel:[1,1,0] op_sel_hi:[1,0,1] neg_lo:[1,0,0]
	global_load_dwordx4 v[72:75], v238, s[20:21]
	v_add_u32_e32 v238, v238, v243
	s_waitcnt vmcnt(18)
; template <bool FINAL> __device__ __forceinline__ void phase_s5_scan(const Fr& F) {
;     ...
;         for (int sub = 0; sub < 4; ++sub) {
;             const bf16x8 A1 = __builtin_bit_cast(bf16x8, uc[sub]);
; #pragma unroll
;             for (int nt = 0; nt < 8; ++nt) {
;                 f32x4 acc = {0.f, 0.f, 0.f, 0.f};
;                 acc = __builtin_amdgcn_mfma_f32_16x16x32_bf16(A1, B1[nt], acc, 0, 0, 0);
; #pragma unroll
;                 for (int reg = 0; reg < 4; ++reg) BUl[(4 * lq + reg) * 132 + 16 * nt + l15] = acc[reg];
;             }
;             asm volatile("s_waitcnt lgkmcnt(0)" ::: "memory");
; #pragma unroll 4
;             for (int jj = 0; jj < 16; ++jj) {
;                 const float br_ = BUl[jj * 132 + lane], bi_ = BUl[jj * 132 + 64 + lane];
;                 const float nr = ar * xr - ai * xi + br_, ni = ar * xi + ai * xr + bi_; xr = nr; xi = ni;
	v_pk_mov_b32 v[232:233], v[168:169], v[184:185] op_sel:[0,0]
	v_pk_mov_b32 v[234:235], v[172:173], v[188:189] op_sel:[0,0]
	v_pk_mov_b32 v[244:245], v[176:177], v[192:193] op_sel:[0,0]
	v_mfma_f32_16x16x32_bf16 v[136:139], v[80:83], v[0:3], 0
	v_pk_mov_b32 v[254:255], v[180:181], v[196:197] op_sel:[0,0]
	v_pk_fma_f32 v[232:233], v[32:33], v[200:201], v[232:233] op_sel_hi:[0,1,1]
	v_pk_fma_f32 v[234:235], v[34:35], v[202:203], v[234:235] op_sel_hi:[0,1,1]
	v_mfma_f32_16x16x32_bf16 v[140:143], v[80:83], v[4:7], 0
	v_pk_fma_f32 v[244:245], v[36:37], v[204:205], v[244:245] op_sel_hi:[0,1,1]
	v_pk_fma_f32 v[254:255], v[38:39], v[206:207], v[254:255] op_sel_hi:[0,1,1]
	v_pk_fma_f32 v[200:201], v[32:33], v[200:201], v[232:233] op_sel:[1,1,0] op_sel_hi:[1,0,1] neg_lo:[1,0,0]
	v_mfma_f32_16x16x32_bf16 v[144:147], v[80:83], v[8:11], 0
	v_pk_fma_f32 v[202:203], v[34:35], v[202:203], v[234:235] op_sel:[1,1,0] op_sel_hi:[1,0,1] neg_lo:[1,0,0]
	v_pk_fma_f32 v[204:205], v[36:37], v[204:205], v[244:245] op_sel:[1,1,0] op_sel_hi:[1,0,1] neg_lo:[1,0,0]
	v_pk_fma_f32 v[206:207], v[38:39], v[206:207], v[254:255] op_sel:[1,1,0] op_sel_hi:[1,0,1] neg_lo:[1,0,0]
	v_mfma_f32_16x16x32_bf16 v[148:151], v[80:83], v[12:15], 0
	v_pk_mov_b32 v[232:233], v[168:169], v[184:185] op_sel:[1,1]
	v_pk_mov_b32 v[234:235], v[172:173], v[188:189] op_sel:[1,1]
	v_pk_mov_b32 v[244:245], v[176:177], v[192:193] op_sel:[1,1]
	v_mfma_f32_16x16x32_bf16 v[152:155], v[80:83], v[16:19], 0
	v_pk_mov_b32 v[254:255], v[180:181], v[196:197] op_sel:[1,1]
	v_pk_fma_f32 v[232:233], v[32:33], v[200:201], v[232:233] op_sel_hi:[0,1,1]
	v_pk_fma_f32 v[234:235], v[34:35], v[202:203], v[234:235] op_sel_hi:[0,1,1]
	v_mfma_f32_16x16x32_bf16 v[156:159], v[80:83], v[20:23], 0
	v_pk_fma_f32 v[244:245], v[36:37], v[204:205], v[244:245] op_sel_hi:[0,1,1]
	v_pk_fma_f32 v[254:255], v[38:39], v[206:207], v[254:255] op_sel_hi:[0,1,1]
	v_pk_fma_f32 v[200:201], v[32:33], v[200:201], v[232:233] op_sel:[1,1,0] op_sel_hi:[1,0,1] neg_lo:[1,0,0]
	v_mfma_f32_16x16x32_bf16 v[160:163], v[80:83], v[24:27], 0
	v_pk_fma_f32 v[202:203], v[34:35], v[202:203], v[234:235] op_sel:[1,1,0] op_sel_hi:[1,0,1] neg_lo:[1,0,0]
	v_pk_fma_f32 v[204:205], v[36:37], v[204:205], v[244:245] op_sel:[1,1,0] op_sel_hi:[1,0,1] neg_lo:[1,0,0]
	v_pk_fma_f32 v[206:207], v[38:39], v[206:207], v[254:255] op_sel:[1,1,0] op_sel_hi:[1,0,1] neg_lo:[1,0,0]
	v_mfma_f32_16x16x32_bf16 v[164:167], v[80:83], v[28:31], 0
	v_pk_mov_b32 v[232:233], v[170:171], v[186:187] op_sel:[0,0]
	v_pk_mov_b32 v[234:235], v[174:175], v[190:191] op_sel:[0,0]
	v_pk_mov_b32 v[244:245], v[178:179], v[194:195] op_sel:[0,0]
	v_pk_mov_b32 v[254:255], v[182:183], v[198:199] op_sel:[0,0]
	v_pk_fma_f32 v[232:233], v[32:33], v[200:201], v[232:233] op_sel_hi:[0,1,1]
	v_pk_fma_f32 v[234:235], v[34:35], v[202:203], v[234:235] op_sel_hi:[0,1,1]
	v_pk_fma_f32 v[244:245], v[36:37], v[204:205], v[244:245] op_sel_hi:[0,1,1]
	v_pk_fma_f32 v[254:255], v[38:39], v[206:207], v[254:255] op_sel_hi:[0,1,1]
	v_pk_fma_f32 v[200:201], v[32:33], v[200:201], v[232:233] op_sel:[1,1,0] op_sel_hi:[1,0,1] neg_lo:[1,0,0]
	v_pk_fma_f32 v[202:203], v[34:35], v[202:203], v[234:235] op_sel:[1,1,0] op_sel_hi:[1,0,1] neg_lo:[1,0,0]
	v_pk_fma_f32 v[204:205], v[36:37], v[204:205], v[244:245] op_sel:[1,1,0] op_sel_hi:[1,0,1] neg_lo:[1,0,0]
	v_pk_fma_f32 v[206:207], v[38:39], v[206:207], v[254:255] op_sel:[1,1,0] op_sel_hi:[1,0,1] neg_lo:[1,0,0]
	v_pk_mov_b32 v[232:233], v[170:171], v[186:187] op_sel:[1,1]
	v_pk_mov_b32 v[234:235], v[174:175], v[190:191] op_sel:[1,1]
	v_pk_mov_b32 v[244:245], v[178:179], v[194:195] op_sel:[1,1]
	v_pk_mov_b32 v[254:255], v[182:183], v[198:199] op_sel:[1,1]
	v_pk_fma_f32 v[232:233], v[32:33], v[200:201], v[232:233] op_sel_hi:[0,1,1]
	v_pk_fma_f32 v[234:235], v[34:35], v[202:203], v[234:235] op_sel_hi:[0,1,1]
	v_pk_fma_f32 v[244:245], v[36:37], v[204:205], v[244:245] op_sel_hi:[0,1,1]
	v_pk_fma_f32 v[254:255], v[38:39], v[206:207], v[254:255] op_sel_hi:[0,1,1]
	v_pk_fma_f32 v[200:201], v[32:33], v[200:201], v[232:233] op_sel:[1,1,0] op_sel_hi:[1,0,1] neg_lo:[1,0,0]
	v_pk_fma_f32 v[202:203], v[34:35], v[202:203], v[234:235] op_sel:[1,1,0] op_sel_hi:[1,0,1] neg_lo:[1,0,0]
	v_pk_fma_f32 v[204:205], v[36:37], v[204:205], v[244:245] op_sel:[1,1,0] op_sel_hi:[1,0,1] neg_lo:[1,0,0]
	v_pk_fma_f32 v[206:207], v[38:39], v[206:207], v[254:255] op_sel:[1,1,0] op_sel_hi:[1,0,1] neg_lo:[1,0,0]
	global_load_dwordx4 v[76:79], v238, s[20:21]
	v_add_u32_e32 v238, v238, v243
	s_waitcnt vmcnt(18)
; template <bool FINAL> __device__ __forceinline__ void phase_s5_scan(const Fr& F) {
;     ...
;         for (int sub = 0; sub < 4; ++sub) {
;             const bf16x8 A1 = __builtin_bit_cast(bf16x8, uc[sub]);
; #pragma unroll
;             for (int nt = 0; nt < 8; ++nt) {
;                 f32x4 acc = {0.f, 0.f, 0.f, 0.f};
;                 acc = __builtin_amdgcn_mfma_f32_16x16x32_bf16(A1, B1[nt], acc, 0, 0, 0);
; #pragma unroll
;                 for (int reg = 0; reg < 4; ++reg) BUl[(4 * lq + reg) * 132 + 16 * nt + l15] = acc[reg];
;             }
;             asm volatile("s_waitcnt lgkmcnt(0)" ::: "memory");
; #pragma unroll 4
;             for (int jj = 0; jj < 16; ++jj) {
;                 const float br_ = BUl[jj * 132 + lane], bi_ = BUl[jj * 132 + 64 + lane];
;                 const float nr = ar * xr - ai * xi + br_, ni = ar * xi + ai * xr + bi_; xr = nr; xi = ni;
	v_pk_mov_b32 v[232:233], v[136:137], v[152:153] op_sel:[0,0]
	v_pk_mov_b32 v[234:235], v[140:141], v[156:157] op_sel:[0,0]
	v_pk_mov_b32 v[244:245], v[144:145], v[160:161] op_sel:[0,0]
	v_mfma_f32_16x16x32_bf16 v[168:171], v[84:87], v[0:3], 0
	v_pk_mov_b32 v[254:255], v[148:149], v[164:165] op_sel:[0,0]
	v_pk_fma_f32 v[232:233], v[32:33], v[200:201], v[232:233] op_sel_hi:[0,1,1]
	v_pk_fma_f32 v[234:235], v[34:35], v[202:203], v[234:235] op_sel_hi:[0,1,1]
	v_mfma_f32_16x16x32_bf16 v[172:175], v[84:87], v[4:7], 0
	v_pk_fma_f32 v[244:245], v[36:37], v[204:205], v[244:245] op_sel_hi:[0,1,1]
	v_pk_fma_f32 v[254:255], v[38:39], v[206:207], v[254:255] op_sel_hi:[0,1,1]
	v_pk_fma_f32 v[200:201], v[32:33], v[200:201], v[232:233] op_sel:[1,1,0] op_sel_hi:[1,0,1] neg_lo:[1,0,0]
	v_mfma_f32_16x16x32_bf16 v[176:179], v[84:87], v[8:11], 0
	v_pk_fma_f32 v[202:203], v[34:35], v[202:203], v[234:235] op_sel:[1,1,0] op_sel_hi:[1,0,1] neg_lo:[1,0,0]
	v_pk_fma_f32 v[204:205], v[36:37], v[204:205], v[244:245] op_sel:[1,1,0] op_sel_hi:[1,0,1] neg_lo:[1,0,0]
	v_pk_fma_f32 v[206:207], v[38:39], v[206:207], v[254:255] op_sel:[1,1,0] op_sel_hi:[1,0,1] neg_lo:[1,0,0]
	v_mfma_f32_16x16x32_bf16 v[180:183], v[84:87], v[12:15], 0
	v_pk_mov_b32 v[232:233], v[136:137], v[152:153] op_sel:[1,1]
	v_pk_mov_b32 v[234:235], v[140:141], v[156:157] op_sel:[1,1]
	v_pk_mov_b32 v[244:245], v[144:145], v[160:161] op_sel:[1,1]
	v_mfma_f32_16x16x32_bf16 v[184:187], v[84:87], v[16:19], 0
	v_pk_mov_b32 v[254:255], v[148:149], v[164:165] op_sel:[1,1]
	v_pk_fma_f32 v[232:233], v[32:33], v[200:201], v[232:233] op_sel_hi:[0,1,1]
	v_pk_fma_f32 v[234:235], v[34:35], v[202:203], v[234:235] op_sel_hi:[0,1,1]
	v_mfma_f32_16x16x32_bf16 v[188:191], v[84:87], v[20:23], 0
	v_pk_fma_f32 v[244:245], v[36:37], v[204:205], v[244:245] op_sel_hi:[0,1,1]
	v_pk_fma_f32 v[254:255], v[38:39], v[206:207], v[254:255] op_sel_hi:[0,1,1]
	v_pk_fma_f32 v[200:201], v[32:33], v[200:201], v[232:233] op_sel:[1,1,0] op_sel_hi:[1,0,1] neg_lo:[1,0,0]
	v_mfma_f32_16x16x32_bf16 v[192:195], v[84:87], v[24:27], 0
	v_pk_fma_f32 v[202:203], v[34:35], v[202:203], v[234:235] op_sel:[1,1,0] op_sel_hi:[1,0,1] neg_lo:[1,0,0]
	v_pk_fma_f32 v[204:205], v[36:37], v[204:205], v[244:245] op_sel:[1,1,0] op_sel_hi:[1,0,1] neg_lo:[1,0,0]
	v_pk_fma_f32 v[206:207], v[38:39], v[206:207], v[254:255] op_sel:[1,1,0] op_sel_hi:[1,0,1] neg_lo:[1,0,0]
	v_mfma_f32_16x16x32_bf16 v[196:199], v[84:87], v[28:31], 0
	v_pk_mov_b32 v[232:233], v[138:139], v[154:155] op_sel:[0,0]
	v_pk_mov_b32 v[234:235], v[142:143], v[158:159] op_sel:[0,0]
	v_pk_mov_b32 v[244:245], v[146:147], v[162:163] op_sel:[0,0]
	v_pk_mov_b32 v[254:255], v[150:151], v[166:167] op_sel:[0,0]
	v_pk_fma_f32 v[232:233], v[32:33], v[200:201], v[232:233] op_sel_hi:[0,1,1]
	v_pk_fma_f32 v[234:235], v[34:35], v[202:203], v[234:235] op_sel_hi:[0,1,1]
	v_pk_fma_f32 v[244:245], v[36:37], v[204:205], v[244:245] op_sel_hi:[0,1,1]
	v_pk_fma_f32 v[254:255], v[38:39], v[206:207], v[254:255] op_sel_hi:[0,1,1]
	v_pk_fma_f32 v[200:201], v[32:33], v[200:201], v[232:233] op_sel:[1,1,0] op_sel_hi:[1,0,1] neg_lo:[1,0,0]
	v_pk_fma_f32 v[202:203], v[34:35], v[202:203], v[234:235] op_sel:[1,1,0] op_sel_hi:[1,0,1] neg_lo:[1,0,0]
	v_pk_fma_f32 v[204:205], v[36:37], v[204:205], v[244:245] op_sel:[1,1,0] op_sel_hi:[1,0,1] neg_lo:[1,0,0]
	v_pk_fma_f32 v[206:207], v[38:39], v[206:207], v[254:255] op_sel:[1,1,0] op_sel_hi:[1,0,1] neg_lo:[1,0,0]
	v_pk_mov_b32 v[232:233], v[138:139], v[154:155] op_sel:[1,1]
	v_pk_mov_b32 v[234:235], v[142:143], v[158:159] op_sel:[1,1]
	v_pk_mov_b32 v[244:245], v[146:147], v[162:163] op_sel:[1,1]
	v_pk_mov_b32 v[254:255], v[150:151], v[166:167] op_sel:[1,1]
	v_pk_fma_f32 v[232:233], v[32:33], v[200:201], v[232:233] op_sel_hi:[0,1,1]
	v_pk_fma_f32 v[234:235], v[34:35], v[202:203], v[234:235] op_sel_hi:[0,1,1]
	v_pk_fma_f32 v[244:245], v[36:37], v[204:205], v[244:245] op_sel_hi:[0,1,1]
	v_pk_fma_f32 v[254:255], v[38:39], v[206:207], v[254:255] op_sel_hi:[0,1,1]
	v_pk_fma_f32 v[200:201], v[32:33], v[200:201], v[232:233] op_sel:[1,1,0] op_sel_hi:[1,0,1] neg_lo:[1,0,0]
	v_pk_fma_f32 v[202:203], v[34:35], v[202:203], v[234:235] op_sel:[1,1,0] op_sel_hi:[1,0,1] neg_lo:[1,0,0]
	v_pk_fma_f32 v[204:205], v[36:37], v[204:205], v[244:245] op_sel:[1,1,0] op_sel_hi:[1,0,1] neg_lo:[1,0,0]
	v_pk_fma_f32 v[206:207], v[38:39], v[206:207], v[254:255] op_sel:[1,1,0] op_sel_hi:[1,0,1] neg_lo:[1,0,0]
	global_load_dwordx4 v[80:83], v238, s[20:21]
	v_add_u32_e32 v238, v238, v243
	s_waitcnt vmcnt(18)
; template <bool FINAL> __device__ __forceinline__ void phase_s5_scan(const Fr& F) {
;     ...
;         for (int sub = 0; sub < 4; ++sub) {
;             const bf16x8 A1 = __builtin_bit_cast(bf16x8, uc[sub]);
; #pragma unroll
;             for (int nt = 0; nt < 8; ++nt) {
;                 f32x4 acc = {0.f, 0.f, 0.f, 0.f};
;                 acc = __builtin_amdgcn_mfma_f32_16x16x32_bf16(A1, B1[nt], acc, 0, 0, 0);
; #pragma unroll
;                 for (int reg = 0; reg < 4; ++reg) BUl[(4 * lq + reg) * 132 + 16 * nt + l15] = acc[reg];
;             }
;             asm volatile("s_waitcnt lgkmcnt(0)" ::: "memory");
; #pragma unroll 4
;             for (int jj = 0; jj < 16; ++jj) {
;                 const float br_ = BUl[jj * 132 + lane], bi_ = BUl[jj * 132 + 64 + lane];
;                 const float nr = ar * xr - ai * xi + br_, ni = ar * xi + ai * xr + bi_; xr = nr; xi = ni;
	v_pk_mov_b32 v[232:233], v[168:169], v[184:185] op_sel:[0,0]
	v_pk_mov_b32 v[234:235], v[172:173], v[188:189] op_sel:[0,0]
	v_pk_mov_b32 v[244:245], v[176:177], v[192:193] op_sel:[0,0]
	v_mfma_f32_16x16x32_bf16 v[136:139], v[88:91], v[0:3], 0
	v_pk_mov_b32 v[254:255], v[180:181], v[196:197] op_sel:[0,0]
	v_pk_fma_f32 v[232:233], v[32:33], v[200:201], v[232:233] op_sel_hi:[0,1,1]
	v_pk_fma_f32 v[234:235], v[34:35], v[202:203], v[234:235] op_sel_hi:[0,1,1]
	v_mfma_f32_16x16x32_bf16 v[140:143], v[88:91], v[4:7], 0
	v_pk_fma_f32 v[244:245], v[36:37], v[204:205], v[244:245] op_sel_hi:[0,1,1]
	v_pk_fma_f32 v[254:255], v[38:39], v[206:207], v[254:255] op_sel_hi:[0,1,1]
	v_pk_fma_f32 v[200:201], v[32:33], v[200:201], v[232:233] op_sel:[1,1,0] op_sel_hi:[1,0,1] neg_lo:[1,0,0]
	v_mfma_f32_16x16x32_bf16 v[144:147], v[88:91], v[8:11], 0
	v_pk_fma_f32 v[202:203], v[34:35], v[202:203], v[234:235] op_sel:[1,1,0] op_sel_hi:[1,0,1] neg_lo:[1,0,0]
	v_pk_fma_f32 v[204:205], v[36:37], v[204:205], v[244:245] op_sel:[1,1,0] op_sel_hi:[1,0,1] neg_lo:[1,0,0]
	v_pk_fma_f32 v[206:207], v[38:39], v[206:207], v[254:255] op_sel:[1,1,0] op_sel_hi:[1,0,1] neg_lo:[1,0,0]
	v_mfma_f32_16x16x32_bf16 v[148:151], v[88:91], v[12:15], 0
	v_pk_mov_b32 v[232:233], v[168:169], v[184:185] op_sel:[1,1]
	v_pk_mov_b32 v[234:235], v[172:173], v[188:189] op_sel:[1,1]
	v_pk_mov_b32 v[244:245], v[176:177], v[192:193] op_sel:[1,1]
	v_mfma_f32_16x16x32_bf16 v[152:155], v[88:91], v[16:19], 0
	v_pk_mov_b32 v[254:255], v[180:181], v[196:197] op_sel:[1,1]
	v_pk_fma_f32 v[232:233], v[32:33], v[200:201], v[232:233] op_sel_hi:[0,1,1]
	v_pk_fma_f32 v[234:235], v[34:35], v[202:203], v[234:235] op_sel_hi:[0,1,1]
	v_mfma_f32_16x16x32_bf16 v[156:159], v[88:91], v[20:23], 0
	v_pk_fma_f32 v[244:245], v[36:37], v[204:205], v[244:245] op_sel_hi:[0,1,1]
	v_pk_fma_f32 v[254:255], v[38:39], v[206:207], v[254:255] op_sel_hi:[0,1,1]
	v_pk_fma_f32 v[200:201], v[32:33], v[200:201], v[232:233] op_sel:[1,1,0] op_sel_hi:[1,0,1] neg_lo:[1,0,0]
	v_mfma_f32_16x16x32_bf16 v[160:163], v[88:91], v[24:27], 0
	v_pk_fma_f32 v[202:203], v[34:35], v[202:203], v[234:235] op_sel:[1,1,0] op_sel_hi:[1,0,1] neg_lo:[1,0,0]
	v_pk_fma_f32 v[204:205], v[36:37], v[204:205], v[244:245] op_sel:[1,1,0] op_sel_hi:[1,0,1] neg_lo:[1,0,0]
	v_pk_fma_f32 v[206:207], v[38:39], v[206:207], v[254:255] op_sel:[1,1,0] op_sel_hi:[1,0,1] neg_lo:[1,0,0]
	v_mfma_f32_16x16x32_bf16 v[164:167], v[88:91], v[28:31], 0
	v_pk_mov_b32 v[232:233], v[170:171], v[186:187] op_sel:[0,0]
	v_pk_mov_b32 v[234:235], v[174:175], v[190:191] op_sel:[0,0]
	v_pk_mov_b32 v[244:245], v[178:179], v[194:195] op_sel:[0,0]
	v_pk_mov_b32 v[254:255], v[182:183], v[198:199] op_sel:[0,0]
	v_pk_fma_f32 v[232:233], v[32:33], v[200:201], v[232:233] op_sel_hi:[0,1,1]
	v_pk_fma_f32 v[234:235], v[34:35], v[202:203], v[234:235] op_sel_hi:[0,1,1]
	v_pk_fma_f32 v[244:245], v[36:37], v[204:205], v[244:245] op_sel_hi:[0,1,1]
	v_pk_fma_f32 v[254:255], v[38:39], v[206:207], v[254:255] op_sel_hi:[0,1,1]
	v_pk_fma_f32 v[200:201], v[32:33], v[200:201], v[232:233] op_sel:[1,1,0] op_sel_hi:[1,0,1] neg_lo:[1,0,0]
	v_pk_fma_f32 v[202:203], v[34:35], v[202:203], v[234:235] op_sel:[1,1,0] op_sel_hi:[1,0,1] neg_lo:[1,0,0]
	v_pk_fma_f32 v[204:205], v[36:37], v[204:205], v[244:245] op_sel:[1,1,0] op_sel_hi:[1,0,1] neg_lo:[1,0,0]
	v_pk_fma_f32 v[206:207], v[38:39], v[206:207], v[254:255] op_sel:[1,1,0] op_sel_hi:[1,0,1] neg_lo:[1,0,0]
	v_pk_mov_b32 v[232:233], v[170:171], v[186:187] op_sel:[1,1]
	v_pk_mov_b32 v[234:235], v[174:175], v[190:191] op_sel:[1,1]
	v_pk_mov_b32 v[244:245], v[178:179], v[194:195] op_sel:[1,1]
	v_pk_mov_b32 v[254:255], v[182:183], v[198:199] op_sel:[1,1]
	v_pk_fma_f32 v[232:233], v[32:33], v[200:201], v[232:233] op_sel_hi:[0,1,1]
	v_pk_fma_f32 v[234:235], v[34:35], v[202:203], v[234:235] op_sel_hi:[0,1,1]
	v_pk_fma_f32 v[244:245], v[36:37], v[204:205], v[244:245] op_sel_hi:[0,1,1]
	v_pk_fma_f32 v[254:255], v[38:39], v[206:207], v[254:255] op_sel_hi:[0,1,1]
	v_pk_fma_f32 v[200:201], v[32:33], v[200:201], v[232:233] op_sel:[1,1,0] op_sel_hi:[1,0,1] neg_lo:[1,0,0]
	v_pk_fma_f32 v[202:203], v[34:35], v[202:203], v[234:235] op_sel:[1,1,0] op_sel_hi:[1,0,1] neg_lo:[1,0,0]
	v_pk_fma_f32 v[204:205], v[36:37], v[204:205], v[244:245] op_sel:[1,1,0] op_sel_hi:[1,0,1] neg_lo:[1,0,0]
	v_pk_fma_f32 v[206:207], v[38:39], v[206:207], v[254:255] op_sel:[1,1,0] op_sel_hi:[1,0,1] neg_lo:[1,0,0]
	global_load_dwordx4 v[84:87], v238, s[20:21]
	v_add_u32_e32 v238, v238, v243
	s_waitcnt vmcnt(18)
; template <bool FINAL> __device__ __forceinline__ void phase_s5_scan(const Fr& F) {
;     ...
;         for (int sub = 0; sub < 4; ++sub) {
;             const bf16x8 A1 = __builtin_bit_cast(bf16x8, uc[sub]);
; #pragma unroll
;             for (int nt = 0; nt < 8; ++nt) {
;                 f32x4 acc = {0.f, 0.f, 0.f, 0.f};
;                 acc = __builtin_amdgcn_mfma_f32_16x16x32_bf16(A1, B1[nt], acc, 0, 0, 0);
; #pragma unroll
;                 for (int reg = 0; reg < 4; ++reg) BUl[(4 * lq + reg) * 132 + 16 * nt + l15] = acc[reg];
;             }
;             asm volatile("s_waitcnt lgkmcnt(0)" ::: "memory");
; #pragma unroll 4
;             for (int jj = 0; jj < 16; ++jj) {
;                 const float br_ = BUl[jj * 132 + lane], bi_ = BUl[jj * 132 + 64 + lane];
;                 const float nr = ar * xr - ai * xi + br_, ni = ar * xi + ai * xr + bi_; xr = nr; xi = ni;
	v_pk_mov_b32 v[232:233], v[136:137], v[152:153] op_sel:[0,0]
	v_pk_mov_b32 v[234:235], v[140:141], v[156:157] op_sel:[0,0]
	v_pk_mov_b32 v[244:245], v[144:145], v[160:161] op_sel:[0,0]
	v_mfma_f32_16x16x32_bf16 v[168:171], v[92:95], v[0:3], 0
	v_pk_mov_b32 v[254:255], v[148:149], v[164:165] op_sel:[0,0]
	v_pk_fma_f32 v[232:233], v[32:33], v[200:201], v[232:233] op_sel_hi:[0,1,1]
	v_pk_fma_f32 v[234:235], v[34:35], v[202:203], v[234:235] op_sel_hi:[0,1,1]
	v_mfma_f32_16x16x32_bf16 v[172:175], v[92:95], v[4:7], 0
	v_pk_fma_f32 v[244:245], v[36:37], v[204:205], v[244:245] op_sel_hi:[0,1,1]
	v_pk_fma_f32 v[254:255], v[38:39], v[206:207], v[254:255] op_sel_hi:[0,1,1]
	v_pk_fma_f32 v[200:201], v[32:33], v[200:201], v[232:233] op_sel:[1,1,0] op_sel_hi:[1,0,1] neg_lo:[1,0,0]
	v_mfma_f32_16x16x32_bf16 v[176:179], v[92:95], v[8:11], 0
	v_pk_fma_f32 v[202:203], v[34:35], v[202:203], v[234:235] op_sel:[1,1,0] op_sel_hi:[1,0,1] neg_lo:[1,0,0]
	v_pk_fma_f32 v[204:205], v[36:37], v[204:205], v[244:245] op_sel:[1,1,0] op_sel_hi:[1,0,1] neg_lo:[1,0,0]
	v_pk_fma_f32 v[206:207], v[38:39], v[206:207], v[254:255] op_sel:[1,1,0] op_sel_hi:[1,0,1] neg_lo:[1,0,0]
	v_mfma_f32_16x16x32_bf16 v[180:183], v[92:95], v[12:15], 0
	v_pk_mov_b32 v[232:233], v[136:137], v[152:153] op_sel:[1,1]
	v_pk_mov_b32 v[234:235], v[140:141], v[156:157] op_sel:[1,1]
	v_pk_mov_b32 v[244:245], v[144:145], v[160:161] op_sel:[1,1]
	v_mfma_f32_16x16x32_bf16 v[184:187], v[92:95], v[16:19], 0
	v_pk_mov_b32 v[254:255], v[148:149], v[164:165] op_sel:[1,1]
	v_pk_fma_f32 v[232:233], v[32:33], v[200:201], v[232:233] op_sel_hi:[0,1,1]
	v_pk_fma_f32 v[234:235], v[34:35], v[202:203], v[234:235] op_sel_hi:[0,1,1]
	v_mfma_f32_16x16x32_bf16 v[188:191], v[92:95], v[20:23], 0
	v_pk_fma_f32 v[244:245], v[36:37], v[204:205], v[244:245] op_sel_hi:[0,1,1]
	v_pk_fma_f32 v[254:255], v[38:39], v[206:207], v[254:255] op_sel_hi:[0,1,1]
	v_pk_fma_f32 v[200:201], v[32:33], v[200:201], v[232:233] op_sel:[1,1,0] op_sel_hi:[1,0,1] neg_lo:[1,0,0]
	v_mfma_f32_16x16x32_bf16 v[192:195], v[92:95], v[24:27], 0
	v_pk_fma_f32 v[202:203], v[34:35], v[202:203], v[234:235] op_sel:[1,1,0] op_sel_hi:[1,0,1] neg_lo:[1,0,0]
	v_pk_fma_f32 v[204:205], v[36:37], v[204:205], v[244:245] op_sel:[1,1,0] op_sel_hi:[1,0,1] neg_lo:[1,0,0]
	v_pk_fma_f32 v[206:207], v[38:39], v[206:207], v[254:255] op_sel:[1,1,0] op_sel_hi:[1,0,1] neg_lo:[1,0,0]
	v_mfma_f32_16x16x32_bf16 v[196:199], v[92:95], v[28:31], 0
	v_pk_mov_b32 v[232:233], v[138:139], v[154:155] op_sel:[0,0]
	v_pk_mov_b32 v[234:235], v[142:143], v[158:159] op_sel:[0,0]
	v_pk_mov_b32 v[244:245], v[146:147], v[162:163] op_sel:[0,0]
	v_pk_mov_b32 v[254:255], v[150:151], v[166:167] op_sel:[0,0]
	v_pk_fma_f32 v[232:233], v[32:33], v[200:201], v[232:233] op_sel_hi:[0,1,1]
	v_pk_fma_f32 v[234:235], v[34:35], v[202:203], v[234:235] op_sel_hi:[0,1,1]
	v_pk_fma_f32 v[244:245], v[36:37], v[204:205], v[244:245] op_sel_hi:[0,1,1]
	v_pk_fma_f32 v[254:255], v[38:39], v[206:207], v[254:255] op_sel_hi:[0,1,1]
	v_pk_fma_f32 v[200:201], v[32:33], v[200:201], v[232:233] op_sel:[1,1,0] op_sel_hi:[1,0,1] neg_lo:[1,0,0]
	v_pk_fma_f32 v[202:203], v[34:35], v[202:203], v[234:235] op_sel:[1,1,0] op_sel_hi:[1,0,1] neg_lo:[1,0,0]
	v_pk_fma_f32 v[204:205], v[36:37], v[204:205], v[244:245] op_sel:[1,1,0] op_sel_hi:[1,0,1] neg_lo:[1,0,0]
	v_pk_fma_f32 v[206:207], v[38:39], v[206:207], v[254:255] op_sel:[1,1,0] op_sel_hi:[1,0,1] neg_lo:[1,0,0]
	v_pk_mov_b32 v[232:233], v[138:139], v[154:155] op_sel:[1,1]
	v_pk_mov_b32 v[234:235], v[142:143], v[158:159] op_sel:[1,1]
	v_pk_mov_b32 v[244:245], v[146:147], v[162:163] op_sel:[1,1]
	v_pk_mov_b32 v[254:255], v[150:151], v[166:167] op_sel:[1,1]
	v_pk_fma_f32 v[232:233], v[32:33], v[200:201], v[232:233] op_sel_hi:[0,1,1]
	v_pk_fma_f32 v[234:235], v[34:35], v[202:203], v[234:235] op_sel_hi:[0,1,1]
	v_pk_fma_f32 v[244:245], v[36:37], v[204:205], v[244:245] op_sel_hi:[0,1,1]
	v_pk_fma_f32 v[254:255], v[38:39], v[206:207], v[254:255] op_sel_hi:[0,1,1]
	v_pk_fma_f32 v[200:201], v[32:33], v[200:201], v[232:233] op_sel:[1,1,0] op_sel_hi:[1,0,1] neg_lo:[1,0,0]
	v_pk_fma_f32 v[202:203], v[34:35], v[202:203], v[234:235] op_sel:[1,1,0] op_sel_hi:[1,0,1] neg_lo:[1,0,0]
	v_pk_fma_f32 v[204:205], v[36:37], v[204:205], v[244:245] op_sel:[1,1,0] op_sel_hi:[1,0,1] neg_lo:[1,0,0]
	v_pk_fma_f32 v[206:207], v[38:39], v[206:207], v[254:255] op_sel:[1,1,0] op_sel_hi:[1,0,1] neg_lo:[1,0,0]
	global_load_dwordx4 v[88:91], v238, s[20:21]
	v_add_u32_e32 v238, v238, v243
	s_waitcnt vmcnt(18)
; template <bool FINAL> __device__ __forceinline__ void phase_s5_scan(const Fr& F) {
;     ...
;         for (int sub = 0; sub < 4; ++sub) {
;             const bf16x8 A1 = __builtin_bit_cast(bf16x8, uc[sub]);
; #pragma unroll
;             for (int nt = 0; nt < 8; ++nt) {
;                 f32x4 acc = {0.f, 0.f, 0.f, 0.f};
;                 acc = __builtin_amdgcn_mfma_f32_16x16x32_bf16(A1, B1[nt], acc, 0, 0, 0);
; #pragma unroll
;                 for (int reg = 0; reg < 4; ++reg) BUl[(4 * lq + reg) * 132 + 16 * nt + l15] = acc[reg];
;             }
;             asm volatile("s_waitcnt lgkmcnt(0)" ::: "memory");
; #pragma unroll 4
;             for (int jj = 0; jj < 16; ++jj) {
;                 const float br_ = BUl[jj * 132 + lane], bi_ = BUl[jj * 132 + 64 + lane];
;                 const float nr = ar * xr - ai * xi + br_, ni = ar * xi + ai * xr + bi_; xr = nr; xi = ni;
	v_pk_mov_b32 v[232:233], v[168:169], v[184:185] op_sel:[0,0]
	v_pk_mov_b32 v[234:235], v[172:173], v[188:189] op_sel:[0,0]
	v_pk_mov_b32 v[244:245], v[176:177], v[192:193] op_sel:[0,0]
	v_mfma_f32_16x16x32_bf16 v[136:139], v[96:99], v[0:3], 0
	v_pk_mov_b32 v[254:255], v[180:181], v[196:197] op_sel:[0,0]
	v_pk_fma_f32 v[232:233], v[32:33], v[200:201], v[232:233] op_sel_hi:[0,1,1]
	v_pk_fma_f32 v[234:235], v[34:35], v[202:203], v[234:235] op_sel_hi:[0,1,1]
	v_mfma_f32_16x16x32_bf16 v[140:143], v[96:99], v[4:7], 0
	v_pk_fma_f32 v[244:245], v[36:37], v[204:205], v[244:245] op_sel_hi:[0,1,1]
	v_pk_fma_f32 v[254:255], v[38:39], v[206:207], v[254:255] op_sel_hi:[0,1,1]
	v_pk_fma_f32 v[200:201], v[32:33], v[200:201], v[232:233] op_sel:[1,1,0] op_sel_hi:[1,0,1] neg_lo:[1,0,0]
	v_mfma_f32_16x16x32_bf16 v[144:147], v[96:99], v[8:11], 0
	v_pk_fma_f32 v[202:203], v[34:35], v[202:203], v[234:235] op_sel:[1,1,0] op_sel_hi:[1,0,1] neg_lo:[1,0,0]
	v_pk_fma_f32 v[204:205], v[36:37], v[204:205], v[244:245] op_sel:[1,1,0] op_sel_hi:[1,0,1] neg_lo:[1,0,0]
	v_pk_fma_f32 v[206:207], v[38:39], v[206:207], v[254:255] op_sel:[1,1,0] op_sel_hi:[1,0,1] neg_lo:[1,0,0]
	v_mfma_f32_16x16x32_bf16 v[148:151], v[96:99], v[12:15], 0
	v_pk_mov_b32 v[232:233], v[168:169], v[184:185] op_sel:[1,1]
	v_pk_mov_b32 v[234:235], v[172:173], v[188:189] op_sel:[1,1]
	v_pk_mov_b32 v[244:245], v[176:177], v[192:193] op_sel:[1,1]
	v_mfma_f32_16x16x32_bf16 v[152:155], v[96:99], v[16:19], 0
	v_pk_mov_b32 v[254:255], v[180:181], v[196:197] op_sel:[1,1]
	v_pk_fma_f32 v[232:233], v[32:33], v[200:201], v[232:233] op_sel_hi:[0,1,1]
	v_pk_fma_f32 v[234:235], v[34:35], v[202:203], v[234:235] op_sel_hi:[0,1,1]
	v_mfma_f32_16x16x32_bf16 v[156:159], v[96:99], v[20:23], 0
	v_pk_fma_f32 v[244:245], v[36:37], v[204:205], v[244:245] op_sel_hi:[0,1,1]
	v_pk_fma_f32 v[254:255], v[38:39], v[206:207], v[254:255] op_sel_hi:[0,1,1]
	v_pk_fma_f32 v[200:201], v[32:33], v[200:201], v[232:233] op_sel:[1,1,0] op_sel_hi:[1,0,1] neg_lo:[1,0,0]
	v_mfma_f32_16x16x32_bf16 v[160:163], v[96:99], v[24:27], 0
	v_pk_fma_f32 v[202:203], v[34:35], v[202:203], v[234:235] op_sel:[1,1,0] op_sel_hi:[1,0,1] neg_lo:[1,0,0]
	v_pk_fma_f32 v[204:205], v[36:37], v[204:205], v[244:245] op_sel:[1,1,0] op_sel_hi:[1,0,1] neg_lo:[1,0,0]
	v_pk_fma_f32 v[206:207], v[38:39], v[206:207], v[254:255] op_sel:[1,1,0] op_sel_hi:[1,0,1] neg_lo:[1,0,0]
	v_mfma_f32_16x16x32_bf16 v[164:167], v[96:99], v[28:31], 0
	v_pk_mov_b32 v[232:233], v[170:171], v[186:187] op_sel:[0,0]
	v_pk_mov_b32 v[234:235], v[174:175], v[190:191] op_sel:[0,0]
	v_pk_mov_b32 v[244:245], v[178:179], v[194:195] op_sel:[0,0]
	v_pk_mov_b32 v[254:255], v[182:183], v[198:199] op_sel:[0,0]
	v_pk_fma_f32 v[232:233], v[32:33], v[200:201], v[232:233] op_sel_hi:[0,1,1]
	v_pk_fma_f32 v[234:235], v[34:35], v[202:203], v[234:235] op_sel_hi:[0,1,1]
	v_pk_fma_f32 v[244:245], v[36:37], v[204:205], v[244:245] op_sel_hi:[0,1,1]
	v_pk_fma_f32 v[254:255], v[38:39], v[206:207], v[254:255] op_sel_hi:[0,1,1]
	v_pk_fma_f32 v[200:201], v[32:33], v[200:201], v[232:233] op_sel:[1,1,0] op_sel_hi:[1,0,1] neg_lo:[1,0,0]
	v_pk_fma_f32 v[202:203], v[34:35], v[202:203], v[234:235] op_sel:[1,1,0] op_sel_hi:[1,0,1] neg_lo:[1,0,0]
	v_pk_fma_f32 v[204:205], v[36:37], v[204:205], v[244:245] op_sel:[1,1,0] op_sel_hi:[1,0,1] neg_lo:[1,0,0]
	v_pk_fma_f32 v[206:207], v[38:39], v[206:207], v[254:255] op_sel:[1,1,0] op_sel_hi:[1,0,1] neg_lo:[1,0,0]
	v_pk_mov_b32 v[232:233], v[170:171], v[186:187] op_sel:[1,1]
	v_pk_mov_b32 v[234:235], v[174:175], v[190:191] op_sel:[1,1]
	v_pk_mov_b32 v[244:245], v[178:179], v[194:195] op_sel:[1,1]
	v_pk_mov_b32 v[254:255], v[182:183], v[198:199] op_sel:[1,1]
	v_pk_fma_f32 v[232:233], v[32:33], v[200:201], v[232:233] op_sel_hi:[0,1,1]
	v_pk_fma_f32 v[234:235], v[34:35], v[202:203], v[234:235] op_sel_hi:[0,1,1]
	v_pk_fma_f32 v[244:245], v[36:37], v[204:205], v[244:245] op_sel_hi:[0,1,1]
	v_pk_fma_f32 v[254:255], v[38:39], v[206:207], v[254:255] op_sel_hi:[0,1,1]
	v_pk_fma_f32 v[200:201], v[32:33], v[200:201], v[232:233] op_sel:[1,1,0] op_sel_hi:[1,0,1] neg_lo:[1,0,0]
	v_pk_fma_f32 v[202:203], v[34:35], v[202:203], v[234:235] op_sel:[1,1,0] op_sel_hi:[1,0,1] neg_lo:[1,0,0]
	v_pk_fma_f32 v[204:205], v[36:37], v[204:205], v[244:245] op_sel:[1,1,0] op_sel_hi:[1,0,1] neg_lo:[1,0,0]
	v_pk_fma_f32 v[206:207], v[38:39], v[206:207], v[254:255] op_sel:[1,1,0] op_sel_hi:[1,0,1] neg_lo:[1,0,0]
	global_load_dwordx4 v[92:95], v238, s[20:21]
	v_add_u32_e32 v238, v238, v243
	s_waitcnt vmcnt(18)
; template <bool FINAL> __device__ __forceinline__ void phase_s5_scan(const Fr& F) {
;     ...
;         for (int sub = 0; sub < 4; ++sub) {
;             const bf16x8 A1 = __builtin_bit_cast(bf16x8, uc[sub]);
; #pragma unroll
;             for (int nt = 0; nt < 8; ++nt) {
;                 f32x4 acc = {0.f, 0.f, 0.f, 0.f};
;                 acc = __builtin_amdgcn_mfma_f32_16x16x32_bf16(A1, B1[nt], acc, 0, 0, 0);
; #pragma unroll
;                 for (int reg = 0; reg < 4; ++reg) BUl[(4 * lq + reg) * 132 + 16 * nt + l15] = acc[reg];
;             }
;             asm volatile("s_waitcnt lgkmcnt(0)" ::: "memory");
; #pragma unroll 4
;             for (int jj = 0; jj < 16; ++jj) {
;                 const float br_ = BUl[jj * 132 + lane], bi_ = BUl[jj * 132 + 64 + lane];
;                 const float nr = ar * xr - ai * xi + br_, ni = ar * xi + ai * xr + bi_; xr = nr; xi = ni;
	v_pk_mov_b32 v[232:233], v[136:137], v[152:153] op_sel:[0,0]
	v_pk_mov_b32 v[234:235], v[140:141], v[156:157] op_sel:[0,0]
	v_pk_mov_b32 v[244:245], v[144:145], v[160:161] op_sel:[0,0]
	v_mfma_f32_16x16x32_bf16 v[168:171], v[100:103], v[0:3], 0
	v_pk_mov_b32 v[254:255], v[148:149], v[164:165] op_sel:[0,0]
	v_pk_fma_f32 v[232:233], v[32:33], v[200:201], v[232:233] op_sel_hi:[0,1,1]
	v_pk_fma_f32 v[234:235], v[34:35], v[202:203], v[234:235] op_sel_hi:[0,1,1]
	v_mfma_f32_16x16x32_bf16 v[172:175], v[100:103], v[4:7], 0
	v_pk_fma_f32 v[244:245], v[36:37], v[204:205], v[244:245] op_sel_hi:[0,1,1]
	v_pk_fma_f32 v[254:255], v[38:39], v[206:207], v[254:255] op_sel_hi:[0,1,1]
	v_pk_fma_f32 v[200:201], v[32:33], v[200:201], v[232:233] op_sel:[1,1,0] op_sel_hi:[1,0,1] neg_lo:[1,0,0]
	v_mfma_f32_16x16x32_bf16 v[176:179], v[100:103], v[8:11], 0
	v_pk_fma_f32 v[202:203], v[34:35], v[202:203], v[234:235] op_sel:[1,1,0] op_sel_hi:[1,0,1] neg_lo:[1,0,0]
	v_pk_fma_f32 v[204:205], v[36:37], v[204:205], v[244:245] op_sel:[1,1,0] op_sel_hi:[1,0,1] neg_lo:[1,0,0]
	v_pk_fma_f32 v[206:207], v[38:39], v[206:207], v[254:255] op_sel:[1,1,0] op_sel_hi:[1,0,1] neg_lo:[1,0,0]
	v_mfma_f32_16x16x32_bf16 v[180:183], v[100:103], v[12:15], 0
	v_pk_mov_b32 v[232:233], v[136:137], v[152:153] op_sel:[1,1]
	v_pk_mov_b32 v[234:235], v[140:141], v[156:157] op_sel:[1,1]
	v_pk_mov_b32 v[244:245], v[144:145], v[160:161] op_sel:[1,1]
	v_mfma_f32_16x16x32_bf16 v[184:187], v[100:103], v[16:19], 0
	v_pk_mov_b32 v[254:255], v[148:149], v[164:165] op_sel:[1,1]
	v_pk_fma_f32 v[232:233], v[32:33], v[200:201], v[232:233] op_sel_hi:[0,1,1]
	v_pk_fma_f32 v[234:235], v[34:35], v[202:203], v[234:235] op_sel_hi:[0,1,1]
	v_mfma_f32_16x16x32_bf16 v[188:191], v[100:103], v[20:23], 0
	v_pk_fma_f32 v[244:245], v[36:37], v[204:205], v[244:245] op_sel_hi:[0,1,1]
	v_pk_fma_f32 v[254:255], v[38:39], v[206:207], v[254:255] op_sel_hi:[0,1,1]
	v_pk_fma_f32 v[200:201], v[32:33], v[200:201], v[232:233] op_sel:[1,1,0] op_sel_hi:[1,0,1] neg_lo:[1,0,0]
	v_mfma_f32_16x16x32_bf16 v[192:195], v[100:103], v[24:27], 0
	v_pk_fma_f32 v[202:203], v[34:35], v[202:203], v[234:235] op_sel:[1,1,0] op_sel_hi:[1,0,1] neg_lo:[1,0,0]
	v_pk_fma_f32 v[204:205], v[36:37], v[204:205], v[244:245] op_sel:[1,1,0] op_sel_hi:[1,0,1] neg_lo:[1,0,0]
	v_pk_fma_f32 v[206:207], v[38:39], v[206:207], v[254:255] op_sel:[1,1,0] op_sel_hi:[1,0,1] neg_lo:[1,0,0]
	v_mfma_f32_16x16x32_bf16 v[196:199], v[100:103], v[28:31], 0
	v_pk_mov_b32 v[232:233], v[138:139], v[154:155] op_sel:[0,0]
	v_pk_mov_b32 v[234:235], v[142:143], v[158:159] op_sel:[0,0]
	v_pk_mov_b32 v[244:245], v[146:147], v[162:163] op_sel:[0,0]
	v_pk_mov_b32 v[254:255], v[150:151], v[166:167] op_sel:[0,0]
	v_pk_fma_f32 v[232:233], v[32:33], v[200:201], v[232:233] op_sel_hi:[0,1,1]
	v_pk_fma_f32 v[234:235], v[34:35], v[202:203], v[234:235] op_sel_hi:[0,1,1]
	v_pk_fma_f32 v[244:245], v[36:37], v[204:205], v[244:245] op_sel_hi:[0,1,1]
	v_pk_fma_f32 v[254:255], v[38:39], v[206:207], v[254:255] op_sel_hi:[0,1,1]
	v_pk_fma_f32 v[200:201], v[32:33], v[200:201], v[232:233] op_sel:[1,1,0] op_sel_hi:[1,0,1] neg_lo:[1,0,0]
	v_pk_fma_f32 v[202:203], v[34:35], v[202:203], v[234:235] op_sel:[1,1,0] op_sel_hi:[1,0,1] neg_lo:[1,0,0]
	v_pk_fma_f32 v[204:205], v[36:37], v[204:205], v[244:245] op_sel:[1,1,0] op_sel_hi:[1,0,1] neg_lo:[1,0,0]
	v_pk_fma_f32 v[206:207], v[38:39], v[206:207], v[254:255] op_sel:[1,1,0] op_sel_hi:[1,0,1] neg_lo:[1,0,0]
	v_pk_mov_b32 v[232:233], v[138:139], v[154:155] op_sel:[1,1]
	v_pk_mov_b32 v[234:235], v[142:143], v[158:159] op_sel:[1,1]
	v_pk_mov_b32 v[244:245], v[146:147], v[162:163] op_sel:[1,1]
	v_pk_mov_b32 v[254:255], v[150:151], v[166:167] op_sel:[1,1]
	v_pk_fma_f32 v[232:233], v[32:33], v[200:201], v[232:233] op_sel_hi:[0,1,1]
	v_pk_fma_f32 v[234:235], v[34:35], v[202:203], v[234:235] op_sel_hi:[0,1,1]
	v_pk_fma_f32 v[244:245], v[36:37], v[204:205], v[244:245] op_sel_hi:[0,1,1]
	v_pk_fma_f32 v[254:255], v[38:39], v[206:207], v[254:255] op_sel_hi:[0,1,1]
	v_pk_fma_f32 v[200:201], v[32:33], v[200:201], v[232:233] op_sel:[1,1,0] op_sel_hi:[1,0,1] neg_lo:[1,0,0]
	v_pk_fma_f32 v[202:203], v[34:35], v[202:203], v[234:235] op_sel:[1,1,0] op_sel_hi:[1,0,1] neg_lo:[1,0,0]
	v_pk_fma_f32 v[204:205], v[36:37], v[204:205], v[244:245] op_sel:[1,1,0] op_sel_hi:[1,0,1] neg_lo:[1,0,0]
	v_pk_fma_f32 v[206:207], v[38:39], v[206:207], v[254:255] op_sel:[1,1,0] op_sel_hi:[1,0,1] neg_lo:[1,0,0]
	global_load_dwordx4 v[96:99], v238, s[20:21]
	v_add_u32_e32 v238, v238, v243
	s_waitcnt vmcnt(18)
; template <bool FINAL> __device__ __forceinline__ void phase_s5_scan(const Fr& F) {
;     ...
;         for (int sub = 0; sub < 4; ++sub) {
;             const bf16x8 A1 = __builtin_bit_cast(bf16x8, uc[sub]);
; #pragma unroll
;             for (int nt = 0; nt < 8; ++nt) {
;                 f32x4 acc = {0.f, 0.f, 0.f, 0.f};
;                 acc = __builtin_amdgcn_mfma_f32_16x16x32_bf16(A1, B1[nt], acc, 0, 0, 0);
; #pragma unroll
;                 for (int reg = 0; reg < 4; ++reg) BUl[(4 * lq + reg) * 132 + 16 * nt + l15] = acc[reg];
;             }
;             asm volatile("s_waitcnt lgkmcnt(0)" ::: "memory");
; #pragma unroll 4
;             for (int jj = 0; jj < 16; ++jj) {
;                 const float br_ = BUl[jj * 132 + lane], bi_ = BUl[jj * 132 + 64 + lane];
;                 const float nr = ar * xr - ai * xi + br_, ni = ar * xi + ai * xr + bi_; xr = nr; xi = ni;
	v_pk_mov_b32 v[232:233], v[168:169], v[184:185] op_sel:[0,0]
	v_pk_mov_b32 v[234:235], v[172:173], v[188:189] op_sel:[0,0]
	v_pk_mov_b32 v[244:245], v[176:177], v[192:193] op_sel:[0,0]
	v_mfma_f32_16x16x32_bf16 v[136:139], v[104:107], v[0:3], 0
	v_pk_mov_b32 v[254:255], v[180:181], v[196:197] op_sel:[0,0]
	v_pk_fma_f32 v[232:233], v[32:33], v[200:201], v[232:233] op_sel_hi:[0,1,1]
	v_pk_fma_f32 v[234:235], v[34:35], v[202:203], v[234:235] op_sel_hi:[0,1,1]
	v_mfma_f32_16x16x32_bf16 v[140:143], v[104:107], v[4:7], 0
	v_pk_fma_f32 v[244:245], v[36:37], v[204:205], v[244:245] op_sel_hi:[0,1,1]
	v_pk_fma_f32 v[254:255], v[38:39], v[206:207], v[254:255] op_sel_hi:[0,1,1]
	v_pk_fma_f32 v[200:201], v[32:33], v[200:201], v[232:233] op_sel:[1,1,0] op_sel_hi:[1,0,1] neg_lo:[1,0,0]
	v_mfma_f32_16x16x32_bf16 v[144:147], v[104:107], v[8:11], 0
	v_pk_fma_f32 v[202:203], v[34:35], v[202:203], v[234:235] op_sel:[1,1,0] op_sel_hi:[1,0,1] neg_lo:[1,0,0]
	v_pk_fma_f32 v[204:205], v[36:37], v[204:205], v[244:245] op_sel:[1,1,0] op_sel_hi:[1,0,1] neg_lo:[1,0,0]
	v_pk_fma_f32 v[206:207], v[38:39], v[206:207], v[254:255] op_sel:[1,1,0] op_sel_hi:[1,0,1] neg_lo:[1,0,0]
	v_mfma_f32_16x16x32_bf16 v[148:151], v[104:107], v[12:15], 0
	v_pk_mov_b32 v[232:233], v[168:169], v[184:185] op_sel:[1,1]
	v_pk_mov_b32 v[234:235], v[172:173], v[188:189] op_sel:[1,1]
	v_pk_mov_b32 v[244:245], v[176:177], v[192:193] op_sel:[1,1]
	v_mfma_f32_16x16x32_bf16 v[152:155], v[104:107], v[16:19], 0
	v_pk_mov_b32 v[254:255], v[180:181], v[196:197] op_sel:[1,1]
	v_pk_fma_f32 v[232:233], v[32:33], v[200:201], v[232:233] op_sel_hi:[0,1,1]
	v_pk_fma_f32 v[234:235], v[34:35], v[202:203], v[234:235] op_sel_hi:[0,1,1]
	v_mfma_f32_16x16x32_bf16 v[156:159], v[104:107], v[20:23], 0
	v_pk_fma_f32 v[244:245], v[36:37], v[204:205], v[244:245] op_sel_hi:[0,1,1]
	v_pk_fma_f32 v[254:255], v[38:39], v[206:207], v[254:255] op_sel_hi:[0,1,1]
	v_pk_fma_f32 v[200:201], v[32:33], v[200:201], v[232:233] op_sel:[1,1,0] op_sel_hi:[1,0,1] neg_lo:[1,0,0]
	v_mfma_f32_16x16x32_bf16 v[160:163], v[104:107], v[24:27], 0
	v_pk_fma_f32 v[202:203], v[34:35], v[202:203], v[234:235] op_sel:[1,1,0] op_sel_hi:[1,0,1] neg_lo:[1,0,0]
	v_pk_fma_f32 v[204:205], v[36:37], v[204:205], v[244:245] op_sel:[1,1,0] op_sel_hi:[1,0,1] neg_lo:[1,0,0]
	v_pk_fma_f32 v[206:207], v[38:39], v[206:207], v[254:255] op_sel:[1,1,0] op_sel_hi:[1,0,1] neg_lo:[1,0,0]
	v_mfma_f32_16x16x32_bf16 v[164:167], v[104:107], v[28:31], 0
	v_pk_mov_b32 v[232:233], v[170:171], v[186:187] op_sel:[0,0]
	v_pk_mov_b32 v[234:235], v[174:175], v[190:191] op_sel:[0,0]
	v_pk_mov_b32 v[244:245], v[178:179], v[194:195] op_sel:[0,0]
	v_pk_mov_b32 v[254:255], v[182:183], v[198:199] op_sel:[0,0]
	v_pk_fma_f32 v[232:233], v[32:33], v[200:201], v[232:233] op_sel_hi:[0,1,1]
	v_pk_fma_f32 v[234:235], v[34:35], v[202:203], v[234:235] op_sel_hi:[0,1,1]
	v_pk_fma_f32 v[244:245], v[36:37], v[204:205], v[244:245] op_sel_hi:[0,1,1]
	v_pk_fma_f32 v[254:255], v[38:39], v[206:207], v[254:255] op_sel_hi:[0,1,1]
	v_pk_fma_f32 v[200:201], v[32:33], v[200:201], v[232:233] op_sel:[1,1,0] op_sel_hi:[1,0,1] neg_lo:[1,0,0]
	v_pk_fma_f32 v[202:203], v[34:35], v[202:203], v[234:235] op_sel:[1,1,0] op_sel_hi:[1,0,1] neg_lo:[1,0,0]
	v_pk_fma_f32 v[204:205], v[36:37], v[204:205], v[244:245] op_sel:[1,1,0] op_sel_hi:[1,0,1] neg_lo:[1,0,0]
	v_pk_fma_f32 v[206:207], v[38:39], v[206:207], v[254:255] op_sel:[1,1,0] op_sel_hi:[1,0,1] neg_lo:[1,0,0]
	v_pk_mov_b32 v[232:233], v[170:171], v[186:187] op_sel:[1,1]
	v_pk_mov_b32 v[234:235], v[174:175], v[190:191] op_sel:[1,1]
	v_pk_mov_b32 v[244:245], v[178:179], v[194:195] op_sel:[1,1]
	v_pk_mov_b32 v[254:255], v[182:183], v[198:199] op_sel:[1,1]
	v_pk_fma_f32 v[232:233], v[32:33], v[200:201], v[232:233] op_sel_hi:[0,1,1]
	v_pk_fma_f32 v[234:235], v[34:35], v[202:203], v[234:235] op_sel_hi:[0,1,1]
	v_pk_fma_f32 v[244:245], v[36:37], v[204:205], v[244:245] op_sel_hi:[0,1,1]
	v_pk_fma_f32 v[254:255], v[38:39], v[206:207], v[254:255] op_sel_hi:[0,1,1]
	v_pk_fma_f32 v[200:201], v[32:33], v[200:201], v[232:233] op_sel:[1,1,0] op_sel_hi:[1,0,1] neg_lo:[1,0,0]
	v_pk_fma_f32 v[202:203], v[34:35], v[202:203], v[234:235] op_sel:[1,1,0] op_sel_hi:[1,0,1] neg_lo:[1,0,0]
	v_pk_fma_f32 v[204:205], v[36:37], v[204:205], v[244:245] op_sel:[1,1,0] op_sel_hi:[1,0,1] neg_lo:[1,0,0]
	v_pk_fma_f32 v[206:207], v[38:39], v[206:207], v[254:255] op_sel:[1,1,0] op_sel_hi:[1,0,1] neg_lo:[1,0,0]
	global_load_dwordx4 v[100:103], v238, s[20:21]
	v_add_u32_e32 v238, v238, v243
	s_waitcnt vmcnt(18)
; template <bool FINAL> __device__ __forceinline__ void phase_s5_scan(const Fr& F) {
;     ...
;         for (int sub = 0; sub < 4; ++sub) {
;             const bf16x8 A1 = __builtin_bit_cast(bf16x8, uc[sub]);
; #pragma unroll
;             for (int nt = 0; nt < 8; ++nt) {
;                 f32x4 acc = {0.f, 0.f, 0.f, 0.f};
;                 acc = __builtin_amdgcn_mfma_f32_16x16x32_bf16(A1, B1[nt], acc, 0, 0, 0);
; #pragma unroll
;                 for (int reg = 0; reg < 4; ++reg) BUl[(4 * lq + reg) * 132 + 16 * nt + l15] = acc[reg];
;             }
;             asm volatile("s_waitcnt lgkmcnt(0)" ::: "memory");
; #pragma unroll 4
;             for (int jj = 0; jj < 16; ++jj) {
;                 const float br_ = BUl[jj * 132 + lane], bi_ = BUl[jj * 132 + 64 + lane];
;                 const float nr = ar * xr - ai * xi + br_, ni = ar * xi + ai * xr + bi_; xr = nr; xi = ni;
	v_pk_mov_b32 v[232:233], v[136:137], v[152:153] op_sel:[0,0]
	v_pk_mov_b32 v[234:235], v[140:141], v[156:157] op_sel:[0,0]
	v_pk_mov_b32 v[244:245], v[144:145], v[160:161] op_sel:[0,0]
	v_mfma_f32_16x16x32_bf16 v[168:171], v[108:111], v[0:3], 0
	v_pk_mov_b32 v[254:255], v[148:149], v[164:165] op_sel:[0,0]
	v_pk_fma_f32 v[232:233], v[32:33], v[200:201], v[232:233] op_sel_hi:[0,1,1]
	v_pk_fma_f32 v[234:235], v[34:35], v[202:203], v[234:235] op_sel_hi:[0,1,1]
	v_mfma_f32_16x16x32_bf16 v[172:175], v[108:111], v[4:7], 0
	v_pk_fma_f32 v[244:245], v[36:37], v[204:205], v[244:245] op_sel_hi:[0,1,1]
	v_pk_fma_f32 v[254:255], v[38:39], v[206:207], v[254:255] op_sel_hi:[0,1,1]
	v_pk_fma_f32 v[200:201], v[32:33], v[200:201], v[232:233] op_sel:[1,1,0] op_sel_hi:[1,0,1] neg_lo:[1,0,0]
	v_mfma_f32_16x16x32_bf16 v[176:179], v[108:111], v[8:11], 0
	v_pk_fma_f32 v[202:203], v[34:35], v[202:203], v[234:235] op_sel:[1,1,0] op_sel_hi:[1,0,1] neg_lo:[1,0,0]
	v_pk_fma_f32 v[204:205], v[36:37], v[204:205], v[244:245] op_sel:[1,1,0] op_sel_hi:[1,0,1] neg_lo:[1,0,0]
	v_pk_fma_f32 v[206:207], v[38:39], v[206:207], v[254:255] op_sel:[1,1,0] op_sel_hi:[1,0,1] neg_lo:[1,0,0]
	v_mfma_f32_16x16x32_bf16 v[180:183], v[108:111], v[12:15], 0
	v_pk_mov_b32 v[232:233], v[136:137], v[152:153] op_sel:[1,1]
	v_pk_mov_b32 v[234:235], v[140:141], v[156:157] op_sel:[1,1]
	v_pk_mov_b32 v[244:245], v[144:145], v[160:161] op_sel:[1,1]
	v_mfma_f32_16x16x32_bf16 v[184:187], v[108:111], v[16:19], 0
	v_pk_mov_b32 v[254:255], v[148:149], v[164:165] op_sel:[1,1]
	v_pk_fma_f32 v[232:233], v[32:33], v[200:201], v[232:233] op_sel_hi:[0,1,1]
	v_pk_fma_f32 v[234:235], v[34:35], v[202:203], v[234:235] op_sel_hi:[0,1,1]
	v_mfma_f32_16x16x32_bf16 v[188:191], v[108:111], v[20:23], 0
	v_pk_fma_f32 v[244:245], v[36:37], v[204:205], v[244:245] op_sel_hi:[0,1,1]
	v_pk_fma_f32 v[254:255], v[38:39], v[206:207], v[254:255] op_sel_hi:[0,1,1]
	v_pk_fma_f32 v[200:201], v[32:33], v[200:201], v[232:233] op_sel:[1,1,0] op_sel_hi:[1,0,1] neg_lo:[1,0,0]
	v_mfma_f32_16x16x32_bf16 v[192:195], v[108:111], v[24:27], 0
	v_pk_fma_f32 v[202:203], v[34:35], v[202:203], v[234:235] op_sel:[1,1,0] op_sel_hi:[1,0,1] neg_lo:[1,0,0]
	v_pk_fma_f32 v[204:205], v[36:37], v[204:205], v[244:245] op_sel:[1,1,0] op_sel_hi:[1,0,1] neg_lo:[1,0,0]
	v_pk_fma_f32 v[206:207], v[38:39], v[206:207], v[254:255] op_sel:[1,1,0] op_sel_hi:[1,0,1] neg_lo:[1,0,0]
	v_mfma_f32_16x16x32_bf16 v[196:199], v[108:111], v[28:31], 0
	v_pk_mov_b32 v[232:233], v[138:139], v[154:155] op_sel:[0,0]
	v_pk_mov_b32 v[234:235], v[142:143], v[158:159] op_sel:[0,0]
	v_pk_mov_b32 v[244:245], v[146:147], v[162:163] op_sel:[0,0]
	v_pk_mov_b32 v[254:255], v[150:151], v[166:167] op_sel:[0,0]
	v_pk_fma_f32 v[232:233], v[32:33], v[200:201], v[232:233] op_sel_hi:[0,1,1]
	v_pk_fma_f32 v[234:235], v[34:35], v[202:203], v[234:235] op_sel_hi:[0,1,1]
	v_pk_fma_f32 v[244:245], v[36:37], v[204:205], v[244:245] op_sel_hi:[0,1,1]
	v_pk_fma_f32 v[254:255], v[38:39], v[206:207], v[254:255] op_sel_hi:[0,1,1]
	v_pk_fma_f32 v[200:201], v[32:33], v[200:201], v[232:233] op_sel:[1,1,0] op_sel_hi:[1,0,1] neg_lo:[1,0,0]
	v_pk_fma_f32 v[202:203], v[34:35], v[202:203], v[234:235] op_sel:[1,1,0] op_sel_hi:[1,0,1] neg_lo:[1,0,0]
	v_pk_fma_f32 v[204:205], v[36:37], v[204:205], v[244:245] op_sel:[1,1,0] op_sel_hi:[1,0,1] neg_lo:[1,0,0]
	v_pk_fma_f32 v[206:207], v[38:39], v[206:207], v[254:255] op_sel:[1,1,0] op_sel_hi:[1,0,1] neg_lo:[1,0,0]
	v_pk_mov_b32 v[232:233], v[138:139], v[154:155] op_sel:[1,1]
	v_pk_mov_b32 v[234:235], v[142:143], v[158:159] op_sel:[1,1]
	v_pk_mov_b32 v[244:245], v[146:147], v[162:163] op_sel:[1,1]
	v_pk_mov_b32 v[254:255], v[150:151], v[166:167] op_sel:[1,1]
	v_pk_fma_f32 v[232:233], v[32:33], v[200:201], v[232:233] op_sel_hi:[0,1,1]
	v_pk_fma_f32 v[234:235], v[34:35], v[202:203], v[234:235] op_sel_hi:[0,1,1]
	v_pk_fma_f32 v[244:245], v[36:37], v[204:205], v[244:245] op_sel_hi:[0,1,1]
	v_pk_fma_f32 v[254:255], v[38:39], v[206:207], v[254:255] op_sel_hi:[0,1,1]
	v_pk_fma_f32 v[200:201], v[32:33], v[200:201], v[232:233] op_sel:[1,1,0] op_sel_hi:[1,0,1] neg_lo:[1,0,0]
	v_pk_fma_f32 v[202:203], v[34:35], v[202:203], v[234:235] op_sel:[1,1,0] op_sel_hi:[1,0,1] neg_lo:[1,0,0]
	v_pk_fma_f32 v[204:205], v[36:37], v[204:205], v[244:245] op_sel:[1,1,0] op_sel_hi:[1,0,1] neg_lo:[1,0,0]
	v_pk_fma_f32 v[206:207], v[38:39], v[206:207], v[254:255] op_sel:[1,1,0] op_sel_hi:[1,0,1] neg_lo:[1,0,0]
	global_load_dwordx4 v[104:107], v238, s[20:21]
	v_add_u32_e32 v238, v238, v243
	s_waitcnt vmcnt(18)
; template <bool FINAL> __device__ __forceinline__ void phase_s5_scan(const Fr& F) {
;     ...
;         for (int sub = 0; sub < 4; ++sub) {
;             const bf16x8 A1 = __builtin_bit_cast(bf16x8, uc[sub]);
; #pragma unroll
;             for (int nt = 0; nt < 8; ++nt) {
;                 f32x4 acc = {0.f, 0.f, 0.f, 0.f};
;                 acc = __builtin_amdgcn_mfma_f32_16x16x32_bf16(A1, B1[nt], acc, 0, 0, 0);
; #pragma unroll
;                 for (int reg = 0; reg < 4; ++reg) BUl[(4 * lq + reg) * 132 + 16 * nt + l15] = acc[reg];
;             }
;             asm volatile("s_waitcnt lgkmcnt(0)" ::: "memory");
; #pragma unroll 4
;             for (int jj = 0; jj < 16; ++jj) {
;                 const float br_ = BUl[jj * 132 + lane], bi_ = BUl[jj * 132 + 64 + lane];
;                 const float nr = ar * xr - ai * xi + br_, ni = ar * xi + ai * xr + bi_; xr = nr; xi = ni;
	v_pk_mov_b32 v[232:233], v[168:169], v[184:185] op_sel:[0,0]
	v_pk_mov_b32 v[234:235], v[172:173], v[188:189] op_sel:[0,0]
	v_pk_mov_b32 v[244:245], v[176:177], v[192:193] op_sel:[0,0]
	v_mfma_f32_16x16x32_bf16 v[136:139], v[112:115], v[0:3], 0
	v_pk_mov_b32 v[254:255], v[180:181], v[196:197] op_sel:[0,0]
	v_pk_fma_f32 v[232:233], v[32:33], v[200:201], v[232:233] op_sel_hi:[0,1,1]
	v_pk_fma_f32 v[234:235], v[34:35], v[202:203], v[234:235] op_sel_hi:[0,1,1]
	v_mfma_f32_16x16x32_bf16 v[140:143], v[112:115], v[4:7], 0
	v_pk_fma_f32 v[244:245], v[36:37], v[204:205], v[244:245] op_sel_hi:[0,1,1]
	v_pk_fma_f32 v[254:255], v[38:39], v[206:207], v[254:255] op_sel_hi:[0,1,1]
	v_pk_fma_f32 v[200:201], v[32:33], v[200:201], v[232:233] op_sel:[1,1,0] op_sel_hi:[1,0,1] neg_lo:[1,0,0]
	v_mfma_f32_16x16x32_bf16 v[144:147], v[112:115], v[8:11], 0
	v_pk_fma_f32 v[202:203], v[34:35], v[202:203], v[234:235] op_sel:[1,1,0] op_sel_hi:[1,0,1] neg_lo:[1,0,0]
	v_pk_fma_f32 v[204:205], v[36:37], v[204:205], v[244:245] op_sel:[1,1,0] op_sel_hi:[1,0,1] neg_lo:[1,0,0]
	v_pk_fma_f32 v[206:207], v[38:39], v[206:207], v[254:255] op_sel:[1,1,0] op_sel_hi:[1,0,1] neg_lo:[1,0,0]
	v_mfma_f32_16x16x32_bf16 v[148:151], v[112:115], v[12:15], 0
	v_pk_mov_b32 v[232:233], v[168:169], v[184:185] op_sel:[1,1]
	v_pk_mov_b32 v[234:235], v[172:173], v[188:189] op_sel:[1,1]
	v_pk_mov_b32 v[244:245], v[176:177], v[192:193] op_sel:[1,1]
	v_mfma_f32_16x16x32_bf16 v[152:155], v[112:115], v[16:19], 0
	v_pk_mov_b32 v[254:255], v[180:181], v[196:197] op_sel:[1,1]
	v_pk_fma_f32 v[232:233], v[32:33], v[200:201], v[232:233] op_sel_hi:[0,1,1]
	v_pk_fma_f32 v[234:235], v[34:35], v[202:203], v[234:235] op_sel_hi:[0,1,1]
	v_mfma_f32_16x16x32_bf16 v[156:159], v[112:115], v[20:23], 0
	v_pk_fma_f32 v[244:245], v[36:37], v[204:205], v[244:245] op_sel_hi:[0,1,1]
	v_pk_fma_f32 v[254:255], v[38:39], v[206:207], v[254:255] op_sel_hi:[0,1,1]
	v_pk_fma_f32 v[200:201], v[32:33], v[200:201], v[232:233] op_sel:[1,1,0] op_sel_hi:[1,0,1] neg_lo:[1,0,0]
	v_mfma_f32_16x16x32_bf16 v[160:163], v[112:115], v[24:27], 0
	v_pk_fma_f32 v[202:203], v[34:35], v[202:203], v[234:235] op_sel:[1,1,0] op_sel_hi:[1,0,1] neg_lo:[1,0,0]
	v_pk_fma_f32 v[204:205], v[36:37], v[204:205], v[244:245] op_sel:[1,1,0] op_sel_hi:[1,0,1] neg_lo:[1,0,0]
	v_pk_fma_f32 v[206:207], v[38:39], v[206:207], v[254:255] op_sel:[1,1,0] op_sel_hi:[1,0,1] neg_lo:[1,0,0]
	v_mfma_f32_16x16x32_bf16 v[164:167], v[112:115], v[28:31], 0
	v_pk_mov_b32 v[232:233], v[170:171], v[186:187] op_sel:[0,0]
	v_pk_mov_b32 v[234:235], v[174:175], v[190:191] op_sel:[0,0]
	v_pk_mov_b32 v[244:245], v[178:179], v[194:195] op_sel:[0,0]
	v_pk_mov_b32 v[254:255], v[182:183], v[198:199] op_sel:[0,0]
	v_pk_fma_f32 v[232:233], v[32:33], v[200:201], v[232:233] op_sel_hi:[0,1,1]
	v_pk_fma_f32 v[234:235], v[34:35], v[202:203], v[234:235] op_sel_hi:[0,1,1]
	v_pk_fma_f32 v[244:245], v[36:37], v[204:205], v[244:245] op_sel_hi:[0,1,1]
	v_pk_fma_f32 v[254:255], v[38:39], v[206:207], v[254:255] op_sel_hi:[0,1,1]
	v_pk_fma_f32 v[200:201], v[32:33], v[200:201], v[232:233] op_sel:[1,1,0] op_sel_hi:[1,0,1] neg_lo:[1,0,0]
	v_pk_fma_f32 v[202:203], v[34:35], v[202:203], v[234:235] op_sel:[1,1,0] op_sel_hi:[1,0,1] neg_lo:[1,0,0]
	v_pk_fma_f32 v[204:205], v[36:37], v[204:205], v[244:245] op_sel:[1,1,0] op_sel_hi:[1,0,1] neg_lo:[1,0,0]
	v_pk_fma_f32 v[206:207], v[38:39], v[206:207], v[254:255] op_sel:[1,1,0] op_sel_hi:[1,0,1] neg_lo:[1,0,0]
	v_pk_mov_b32 v[232:233], v[170:171], v[186:187] op_sel:[1,1]
	v_pk_mov_b32 v[234:235], v[174:175], v[190:191] op_sel:[1,1]
	v_pk_mov_b32 v[244:245], v[178:179], v[194:195] op_sel:[1,1]
	v_pk_mov_b32 v[254:255], v[182:183], v[198:199] op_sel:[1,1]
	v_pk_fma_f32 v[232:233], v[32:33], v[200:201], v[232:233] op_sel_hi:[0,1,1]
	v_pk_fma_f32 v[234:235], v[34:35], v[202:203], v[234:235] op_sel_hi:[0,1,1]
	v_pk_fma_f32 v[244:245], v[36:37], v[204:205], v[244:245] op_sel_hi:[0,1,1]
	v_pk_fma_f32 v[254:255], v[38:39], v[206:207], v[254:255] op_sel_hi:[0,1,1]
	v_pk_fma_f32 v[200:201], v[32:33], v[200:201], v[232:233] op_sel:[1,1,0] op_sel_hi:[1,0,1] neg_lo:[1,0,0]
	v_pk_fma_f32 v[202:203], v[34:35], v[202:203], v[234:235] op_sel:[1,1,0] op_sel_hi:[1,0,1] neg_lo:[1,0,0]
	v_pk_fma_f32 v[204:205], v[36:37], v[204:205], v[244:245] op_sel:[1,1,0] op_sel_hi:[1,0,1] neg_lo:[1,0,0]
	v_pk_fma_f32 v[206:207], v[38:39], v[206:207], v[254:255] op_sel:[1,1,0] op_sel_hi:[1,0,1] neg_lo:[1,0,0]
	global_load_dwordx4 v[108:111], v238, s[20:21]
	v_add_u32_e32 v238, v238, v243
	s_waitcnt vmcnt(18)
; template <bool FINAL> __device__ __forceinline__ void phase_s5_scan(const Fr& F) {
;     ...
;         for (int sub = 0; sub < 4; ++sub) {
;             const bf16x8 A1 = __builtin_bit_cast(bf16x8, uc[sub]);
; #pragma unroll
;             for (int nt = 0; nt < 8; ++nt) {
;                 f32x4 acc = {0.f, 0.f, 0.f, 0.f};
;                 acc = __builtin_amdgcn_mfma_f32_16x16x32_bf16(A1, B1[nt], acc, 0, 0, 0);
; #pragma unroll
;                 for (int reg = 0; reg < 4; ++reg) BUl[(4 * lq + reg) * 132 + 16 * nt + l15] = acc[reg];
;             }
;             asm volatile("s_waitcnt lgkmcnt(0)" ::: "memory");
; #pragma unroll 4
;             for (int jj = 0; jj < 16; ++jj) {
;                 const float br_ = BUl[jj * 132 + lane], bi_ = BUl[jj * 132 + 64 + lane];
;                 const float nr = ar * xr - ai * xi + br_, ni = ar * xi + ai * xr + bi_; xr = nr; xi = ni;
	v_pk_mov_b32 v[232:233], v[136:137], v[152:153] op_sel:[0,0]
	v_pk_mov_b32 v[234:235], v[140:141], v[156:157] op_sel:[0,0]
	v_pk_mov_b32 v[244:245], v[144:145], v[160:161] op_sel:[0,0]
	v_mfma_f32_16x16x32_bf16 v[168:171], v[116:119], v[0:3], 0
	v_pk_mov_b32 v[254:255], v[148:149], v[164:165] op_sel:[0,0]
	v_pk_fma_f32 v[232:233], v[32:33], v[200:201], v[232:233] op_sel_hi:[0,1,1]
	v_pk_fma_f32 v[234:235], v[34:35], v[202:203], v[234:235] op_sel_hi:[0,1,1]
	v_mfma_f32_16x16x32_bf16 v[172:175], v[116:119], v[4:7], 0
	v_pk_fma_f32 v[244:245], v[36:37], v[204:205], v[244:245] op_sel_hi:[0,1,1]
	v_pk_fma_f32 v[254:255], v[38:39], v[206:207], v[254:255] op_sel_hi:[0,1,1]
	v_pk_fma_f32 v[200:201], v[32:33], v[200:201], v[232:233] op_sel:[1,1,0] op_sel_hi:[1,0,1] neg_lo:[1,0,0]
	v_mfma_f32_16x16x32_bf16 v[176:179], v[116:119], v[8:11], 0
	v_pk_fma_f32 v[202:203], v[34:35], v[202:203], v[234:235] op_sel:[1,1,0] op_sel_hi:[1,0,1] neg_lo:[1,0,0]
	v_pk_fma_f32 v[204:205], v[36:37], v[204:205], v[244:245] op_sel:[1,1,0] op_sel_hi:[1,0,1] neg_lo:[1,0,0]
	v_pk_fma_f32 v[206:207], v[38:39], v[206:207], v[254:255] op_sel:[1,1,0] op_sel_hi:[1,0,1] neg_lo:[1,0,0]
	v_mfma_f32_16x16x32_bf16 v[180:183], v[116:119], v[12:15], 0
	v_pk_mov_b32 v[232:233], v[136:137], v[152:153] op_sel:[1,1]
	v_pk_mov_b32 v[234:235], v[140:141], v[156:157] op_sel:[1,1]
	v_pk_mov_b32 v[244:245], v[144:145], v[160:161] op_sel:[1,1]
	v_mfma_f32_16x16x32_bf16 v[184:187], v[116:119], v[16:19], 0
	v_pk_mov_b32 v[254:255], v[148:149], v[164:165] op_sel:[1,1]
	v_pk_fma_f32 v[232:233], v[32:33], v[200:201], v[232:233] op_sel_hi:[0,1,1]
	v_pk_fma_f32 v[234:235], v[34:35], v[202:203], v[234:235] op_sel_hi:[0,1,1]
	v_mfma_f32_16x16x32_bf16 v[188:191], v[116:119], v[20:23], 0
	v_pk_fma_f32 v[244:245], v[36:37], v[204:205], v[244:245] op_sel_hi:[0,1,1]
	v_pk_fma_f32 v[254:255], v[38:39], v[206:207], v[254:255] op_sel_hi:[0,1,1]
	v_pk_fma_f32 v[200:201], v[32:33], v[200:201], v[232:233] op_sel:[1,1,0] op_sel_hi:[1,0,1] neg_lo:[1,0,0]
	v_mfma_f32_16x16x32_bf16 v[192:195], v[116:119], v[24:27], 0
	v_pk_fma_f32 v[202:203], v[34:35], v[202:203], v[234:235] op_sel:[1,1,0] op_sel_hi:[1,0,1] neg_lo:[1,0,0]
	v_pk_fma_f32 v[204:205], v[36:37], v[204:205], v[244:245] op_sel:[1,1,0] op_sel_hi:[1,0,1] neg_lo:[1,0,0]
	v_pk_fma_f32 v[206:207], v[38:39], v[206:207], v[254:255] op_sel:[1,1,0] op_sel_hi:[1,0,1] neg_lo:[1,0,0]
	v_mfma_f32_16x16x32_bf16 v[196:199], v[116:119], v[28:31], 0
	v_pk_mov_b32 v[232:233], v[138:139], v[154:155] op_sel:[0,0]
	v_pk_mov_b32 v[234:235], v[142:143], v[158:159] op_sel:[0,0]
	v_pk_mov_b32 v[244:245], v[146:147], v[162:163] op_sel:[0,0]
	v_pk_mov_b32 v[254:255], v[150:151], v[166:167] op_sel:[0,0]
	v_pk_fma_f32 v[232:233], v[32:33], v[200:201], v[232:233] op_sel_hi:[0,1,1]
	v_pk_fma_f32 v[234:235], v[34:35], v[202:203], v[234:235] op_sel_hi:[0,1,1]
	v_pk_fma_f32 v[244:245], v[36:37], v[204:205], v[244:245] op_sel_hi:[0,1,1]
	v_pk_fma_f32 v[254:255], v[38:39], v[206:207], v[254:255] op_sel_hi:[0,1,1]
	v_pk_fma_f32 v[200:201], v[32:33], v[200:201], v[232:233] op_sel:[1,1,0] op_sel_hi:[1,0,1] neg_lo:[1,0,0]
	v_pk_fma_f32 v[202:203], v[34:35], v[202:203], v[234:235] op_sel:[1,1,0] op_sel_hi:[1,0,1] neg_lo:[1,0,0]
	v_pk_fma_f32 v[204:205], v[36:37], v[204:205], v[244:245] op_sel:[1,1,0] op_sel_hi:[1,0,1] neg_lo:[1,0,0]
	v_pk_fma_f32 v[206:207], v[38:39], v[206:207], v[254:255] op_sel:[1,1,0] op_sel_hi:[1,0,1] neg_lo:[1,0,0]
	v_pk_mov_b32 v[232:233], v[138:139], v[154:155] op_sel:[1,1]
	v_pk_mov_b32 v[234:235], v[142:143], v[158:159] op_sel:[1,1]
	v_pk_mov_b32 v[244:245], v[146:147], v[162:163] op_sel:[1,1]
	v_pk_mov_b32 v[254:255], v[150:151], v[166:167] op_sel:[1,1]
	v_pk_fma_f32 v[232:233], v[32:33], v[200:201], v[232:233] op_sel_hi:[0,1,1]
	v_pk_fma_f32 v[234:235], v[34:35], v[202:203], v[234:235] op_sel_hi:[0,1,1]
	v_pk_fma_f32 v[244:245], v[36:37], v[204:205], v[244:245] op_sel_hi:[0,1,1]
	v_pk_fma_f32 v[254:255], v[38:39], v[206:207], v[254:255] op_sel_hi:[0,1,1]
	v_pk_fma_f32 v[200:201], v[32:33], v[200:201], v[232:233] op_sel:[1,1,0] op_sel_hi:[1,0,1] neg_lo:[1,0,0]
	v_pk_fma_f32 v[202:203], v[34:35], v[202:203], v[234:235] op_sel:[1,1,0] op_sel_hi:[1,0,1] neg_lo:[1,0,0]
	v_pk_fma_f32 v[204:205], v[36:37], v[204:205], v[244:245] op_sel:[1,1,0] op_sel_hi:[1,0,1] neg_lo:[1,0,0]
	v_pk_fma_f32 v[206:207], v[38:39], v[206:207], v[254:255] op_sel:[1,1,0] op_sel_hi:[1,0,1] neg_lo:[1,0,0]
; __device__ __forceinline__ unsigned f2bf(float f) { unsigned u = __builtin_bit_cast(unsigned, f); return (u + 0x7fffu + ((u >> 16) & 1u)) >> 16; }
; __device__ __forceinline__ bf16x8 pack8(const float (&f)[8]) { u32x4 h; h.x = pk2(f[0], f[1]); h.y = pk2(f[2], f[3]); h.z = pk2(f[4], f[5]); h.w = pk2(f[6], f[7]); return __builtin_bit_cast(bf16x8, h); }
; template <bool FINAL> __device__ __forceinline__ void phase_s5_scan(const Fr& F) {
;     ...
;         for (int sub = 0; sub < 4; ++sub) {
;             const bf16x8 A1 = __builtin_bit_cast(bf16x8, uc[sub]);
; #pragma unroll
;             for (int nt = 0; nt < 8; ++nt) {
;                 f32x4 acc = {0.f, 0.f, 0.f, 0.f};
;                 acc = __builtin_amdgcn_mfma_f32_16x16x32_bf16(A1, B1[nt], acc, 0, 0, 0);
; #pragma unroll
;                 for (int reg = 0; reg < 4; ++reg) BUl[(4 * lq + reg) * 132 + 16 * nt + l15] = acc[reg];
;             }
;             asm volatile("s_waitcnt lgkmcnt(0)" ::: "memory");
; #pragma unroll 4
;             for (int jj = 0; jj < 16; ++jj) {
;                 const float br_ = BUl[jj * 132 + lane], bi_ = BUl[jj * 132 + 64 + lane];
;                 const float nr = ar * xr - ai * xi + br_, ni = ar * xi + ai * xr + bi_; xr = nr; xi = ni;
;                 if (FINAL) { BUl[jj * 132 + lane] = xr; BUl[jj * 132 + 64 + lane] = xi; }
;             }
;             if (FINAL) {
;                 asm volatile("s_waitcnt lgkmcnt(0)" ::: "memory");
;                 f32x4 acc = {0.f, 0.f, 0.f, 0.f};
; #pragma unroll
;                 for (int ks = 0; ks < 4; ++ks) {
;                     const f32x4 t0 = *(const f32x4*)(BUl + l15 * 132 + 32 * ks + 8 * lq), t1 = *(const f32x4*)(BUl + l15 * 132 + 32 * ks + 8 * lq + 4);
;                     const float xf[8] = {t0.x, t0.y, t0.z, t0.w, t1.x, t1.y, t1.z, t1.w};
;                     acc = __builtin_amdgcn_mfma_f32_16x16x32_bf16(pack8(xf), Chi[ks], acc, 0, 0, 0);
;                 }
; #pragma unroll
;                 for (int reg = 0; reg < 4; ++reg) { const int tok = tokof(s, chunk * 64 + sub * 16 + 4 * lq + reg);
;                     Yb[((size_t)b * TB + tok) * D + g * 16 + l15] = (bf16)f2bf(acc[reg]); }
;                 asm volatile("s_waitcnt lgkmcnt(0)" ::: "memory");
;             }
;         }
;         if (!FINAL) { float* e = E + ((size_t)task * 64 + lane) * 2; e[0] = xr; e[1] = xi; }
;     }
	global_load_dwordx4 v[112:115], v238, s[20:21]
	v_add_u32_e32 v238, v238, v243
	v_pk_mov_b32 v[232:233], v[168:169], v[184:185] op_sel:[0,0]
	v_pk_mov_b32 v[234:235], v[172:173], v[188:189] op_sel:[0,0]
	v_pk_mov_b32 v[244:245], v[176:177], v[192:193] op_sel:[0,0]
	v_pk_mov_b32 v[254:255], v[180:181], v[196:197] op_sel:[0,0]
	v_pk_fma_f32 v[232:233], v[32:33], v[200:201], v[232:233] op_sel_hi:[0,1,1]
	v_pk_fma_f32 v[234:235], v[34:35], v[202:203], v[234:235] op_sel_hi:[0,1,1]
	v_pk_fma_f32 v[244:245], v[36:37], v[204:205], v[244:245] op_sel_hi:[0,1,1]
	v_pk_fma_f32 v[254:255], v[38:39], v[206:207], v[254:255] op_sel_hi:[0,1,1]
	v_pk_fma_f32 v[200:201], v[32:33], v[200:201], v[232:233] op_sel:[1,1,0] op_sel_hi:[1,0,1] neg_lo:[1,0,0]
	v_pk_fma_f32 v[202:203], v[34:35], v[202:203], v[234:235] op_sel:[1,1,0] op_sel_hi:[1,0,1] neg_lo:[1,0,0]
	v_pk_fma_f32 v[204:205], v[36:37], v[204:205], v[244:245] op_sel:[1,1,0] op_sel_hi:[1,0,1] neg_lo:[1,0,0]
	v_pk_fma_f32 v[206:207], v[38:39], v[206:207], v[254:255] op_sel:[1,1,0] op_sel_hi:[1,0,1] neg_lo:[1,0,0]
	v_pk_mov_b32 v[232:233], v[168:169], v[184:185] op_sel:[1,1]
	v_pk_mov_b32 v[234:235], v[172:173], v[188:189] op_sel:[1,1]
	v_pk_mov_b32 v[244:245], v[176:177], v[192:193] op_sel:[1,1]
	v_pk_mov_b32 v[254:255], v[180:181], v[196:197] op_sel:[1,1]
	v_pk_fma_f32 v[232:233], v[32:33], v[200:201], v[232:233] op_sel_hi:[0,1,1]
	v_pk_fma_f32 v[234:235], v[34:35], v[202:203], v[234:235] op_sel_hi:[0,1,1]
	v_pk_fma_f32 v[244:245], v[36:37], v[204:205], v[244:245] op_sel_hi:[0,1,1]
	v_pk_fma_f32 v[254:255], v[38:39], v[206:207], v[254:255] op_sel_hi:[0,1,1]
	v_pk_fma_f32 v[200:201], v[32:33], v[200:201], v[232:233] op_sel:[1,1,0] op_sel_hi:[1,0,1] neg_lo:[1,0,0]
	v_pk_fma_f32 v[202:203], v[34:35], v[202:203], v[234:235] op_sel:[1,1,0] op_sel_hi:[1,0,1] neg_lo:[1,0,0]
	v_pk_fma_f32 v[204:205], v[36:37], v[204:205], v[244:245] op_sel:[1,1,0] op_sel_hi:[1,0,1] neg_lo:[1,0,0]
	v_pk_fma_f32 v[206:207], v[38:39], v[206:207], v[254:255] op_sel:[1,1,0] op_sel_hi:[1,0,1] neg_lo:[1,0,0]
	v_pk_mov_b32 v[232:233], v[170:171], v[186:187] op_sel:[0,0]
	v_pk_mov_b32 v[234:235], v[174:175], v[190:191] op_sel:[0,0]
	v_pk_mov_b32 v[244:245], v[178:179], v[194:195] op_sel:[0,0]
	v_pk_mov_b32 v[254:255], v[182:183], v[198:199] op_sel:[0,0]
	v_pk_fma_f32 v[232:233], v[32:33], v[200:201], v[232:233] op_sel_hi:[0,1,1]
	v_pk_fma_f32 v[234:235], v[34:35], v[202:203], v[234:235] op_sel_hi:[0,1,1]
	v_pk_fma_f32 v[244:245], v[36:37], v[204:205], v[244:245] op_sel_hi:[0,1,1]
	v_pk_fma_f32 v[254:255], v[38:39], v[206:207], v[254:255] op_sel_hi:[0,1,1]
	v_pk_fma_f32 v[200:201], v[32:33], v[200:201], v[232:233] op_sel:[1,1,0] op_sel_hi:[1,0,1] neg_lo:[1,0,0]
	v_pk_fma_f32 v[202:203], v[34:35], v[202:203], v[234:235] op_sel:[1,1,0] op_sel_hi:[1,0,1] neg_lo:[1,0,0]
	v_pk_fma_f32 v[204:205], v[36:37], v[204:205], v[244:245] op_sel:[1,1,0] op_sel_hi:[1,0,1] neg_lo:[1,0,0]
	v_pk_fma_f32 v[206:207], v[38:39], v[206:207], v[254:255] op_sel:[1,1,0] op_sel_hi:[1,0,1] neg_lo:[1,0,0]
	v_pk_mov_b32 v[232:233], v[170:171], v[186:187] op_sel:[1,1]
	v_pk_mov_b32 v[234:235], v[174:175], v[190:191] op_sel:[1,1]
	v_pk_mov_b32 v[244:245], v[178:179], v[194:195] op_sel:[1,1]
	v_pk_mov_b32 v[254:255], v[182:183], v[198:199] op_sel:[1,1]
	v_pk_fma_f32 v[232:233], v[32:33], v[200:201], v[232:233] op_sel_hi:[0,1,1]
	v_pk_fma_f32 v[234:235], v[34:35], v[202:203], v[234:235] op_sel_hi:[0,1,1]
	v_pk_fma_f32 v[244:245], v[36:37], v[204:205], v[244:245] op_sel_hi:[0,1,1]
	v_pk_fma_f32 v[254:255], v[38:39], v[206:207], v[254:255] op_sel_hi:[0,1,1]
	v_pk_fma_f32 v[200:201], v[32:33], v[200:201], v[232:233] op_sel:[1,1,0] op_sel_hi:[1,0,1] neg_lo:[1,0,0]
	v_pk_fma_f32 v[202:203], v[34:35], v[202:203], v[234:235] op_sel:[1,1,0] op_sel_hi:[1,0,1] neg_lo:[1,0,0]
	v_pk_fma_f32 v[204:205], v[36:37], v[204:205], v[244:245] op_sel:[1,1,0] op_sel_hi:[1,0,1] neg_lo:[1,0,0]
	v_pk_fma_f32 v[206:207], v[38:39], v[206:207], v[254:255] op_sel:[1,1,0] op_sel_hi:[1,0,1] neg_lo:[1,0,0]
	global_load_dwordx4 v[116:119], v238, s[20:21]
	v_add_u32_e32 v238, v238, v243
	global_store_dwordx2 v240, v[200:201], s[22:23] offset:0
	global_store_dwordx2 v240, v[202:203], s[22:23] offset:128
	global_store_dwordx2 v240, v[204:205], s[22:23] offset:256
	global_store_dwordx2 v240, v[206:207], s[22:23] offset:384
	s_add_i32 s14, s14, 16
	s_add_i32 s19, s19, 1
	s_cmp_lt_u32 s19, s56
	s_cbranch_scc1 .Ls5a_grp
	s_waitcnt vmcnt(0) lgkmcnt(0)

; template <bool FINAL> __device__ __forceinline__ void phase_s5_scan(const Fr& F) {
;     ...
;     {   const int ti = F.gw & 15, b = ti / 68, chunk = ti - b * 68;
; #pragma unroll
;         for (int sb = 0; sb < 4; ++sb) ua[sb] = lq < 2 ? *(const u32x4*)(U + ((size_t)b * TB + tokof(s, chunk * 64 + sb * 16 + l15)) * D + g * 16 + 8 * lq) : (u32x4){0u, 0u, 0u, 0u};
;         if (FINAL) { const float* e = E + ((size_t)(((s * 4 + b) * 64 + g) * 68 + chunk) * 64 + lane) * 2; e0 = e[0]; e1 = e[1]; } }
;     for (int ti = (F.gw & 15); ti < NB * 68; ti += 16) {
;         const int b = ti / 68, chunk = ti - b * 68, sbg = (s * 4 + b) * 64 + g, task = sbg * 68 + chunk;
;         float xr = FINAL ? e0 : 0.f, xi = FINAL ? e1 : 0.f;
;         bf16* Yb = F.R(4 + s);
;         u32x4 uc[4];
; #pragma unroll
;         for (int sb = 0; sb < 4; ++sb) uc[sb] = ua[sb];
;         if (ti + 16 < NB * 68) {
;             const int tn = ti + 16, bn = tn / 68, cn = tn - bn * 68;
; #pragma unroll
;             for (int sb = 0; sb < 4; ++sb) ua[sb] = lq < 2 ? *(const u32x4*)(U + ((size_t)bn * TB + tokof(s, cn * 64 + sb * 16 + l15)) * D + g * 16 + 8 * lq) : (u32x4){0u, 0u, 0u, 0u};
;             if (FINAL) { const float* e = E + ((size_t)(((s * 4 + bn) * 64 + g) * 68 + cn) * 64 + lane) * 2; e0 = e[0]; e1 = e[1]; }
;         }
; #pragma unroll
;         for (int sub = 0; sub < 4; ++sub) {
;             const bf16x8 A1 = __builtin_bit_cast(bf16x8, uc[sub]);
; #pragma unroll
;             for (int nt = 0; nt < 8; ++nt) {
;                 f32x4 acc = {0.f, 0.f, 0.f, 0.f};
;                 acc = __builtin_amdgcn_mfma_f32_16x16x32_bf16(A1, B1[nt], acc, 0, 0, 0);
; #pragma unroll
;                 for (int reg = 0; reg < 4; ++reg) BUl[(4 * lq + reg) * 132 + 16 * nt + l15] = acc[reg];
;             }
;             asm volatile("s_waitcnt lgkmcnt(0)" ::: "memory");
; #pragma unroll 4
;             for (int jj = 0; jj < 16; ++jj) {
;                 const float br_ = BUl[jj * 132 + lane], bi_ = BUl[jj * 132 + 64 + lane];
;                 const float nr = ar * xr - ai * xi + br_, ni = ar * xi + ai * xr + bi_; xr = nr; xi = ni;
;                 if (FINAL) { BUl[jj * 132 + lane] = xr; BUl[jj * 132 + 64 + lane] = xi; }
;             }
;             if (FINAL) {
;                 asm volatile("s_waitcnt lgkmcnt(0)" ::: "memory");
;                 f32x4 acc = {0.f, 0.f, 0.f, 0.f};
; #pragma unroll
.Ls5b_grp:
	s_lshl_b32 s15, s14, 2
	v_lshrrev_b32_e32 v244, 2, v236
	v_add_u32_e32 v244, s15, v244
	v_mul_u32_u24_e32 v245, 0xf1, v244
	v_lshrrev_b32_e32 v245, 14, v245
	v_mul_u32_u24_e32 v232, 68, v245
	v_sub_u32_e32 v244, v244, v232
	v_and_b32_e32 v232, 3, v236
	v_lshl_add_u32 v232, v244, 6, v232
	v_mov_b32_e32 v233, 0x11ff
	v_mov_b32_e32 v234, 0xff
	v_cmp_gt_u32_e32 vcc, 4, v244
	s_nop 1
	v_cndmask_b32_e32 v233, v233, v234, vcc
	v_sub_u32_e32 v233, v233, v232
	s_cmp_eq_u32 s9, 0
	s_cselect_b64 vcc, -1, 0
	s_nop 1
	v_cndmask_b32_e32 v232, v233, v232, vcc
	v_mul_u32_u24_e32 v245, 0x1100, v245
	v_add_u32_e32 v232, v232, v245
	s_lshl_b32 s16, s8, 5
	v_and_b32_e32 v233, 1, v237
	v_lshl_add_u32 v233, v233, 4, s16
	v_lshl_add_u32 v235, v232, 11, v233
	v_lshl_add_u32 v233, v237, 3, s16
	v_lshl_add_u32 v239, v232, 11, v233
	s_add_i32 s54, s14, 16
	s_lshl_b32 s15, s54, 2
	v_lshrrev_b32_e32 v244, 2, v236
	v_add_u32_e32 v244, s15, v244
	v_mul_u32_u24_e32 v245, 0xf1, v244
	v_lshrrev_b32_e32 v245, 14, v245
	v_mul_u32_u24_e32 v232, 68, v245
	v_sub_u32_e32 v244, v244, v232
	v_and_b32_e32 v232, 3, v236
	v_lshl_add_u32 v232, v244, 6, v232
	v_mov_b32_e32 v233, 0x11ff
	v_mov_b32_e32 v234, 0xff
	v_cmp_gt_u32_e32 vcc, 4, v244
	s_nop 1
	v_cndmask_b32_e32 v233, v233, v234, vcc
	v_sub_u32_e32 v233, v233, v232
	s_cmp_eq_u32 s9, 0
	s_cselect_b64 vcc, -1, 0
	s_nop 1
	v_cndmask_b32_e32 v232, v233, v232, vcc
	v_mul_u32_u24_e32 v245, 0x1100, v245
	v_add_u32_e32 v232, v232, v245
	s_lshl_b32 s16, s8, 5
	v_and_b32_e32 v233, 1, v237
	v_lshl_add_u32 v233, v233, 4, s16
	v_lshl_add_u32 v238, v232, 11, v233
	v_add_u32_e32 v244, s15, v237
	v_mul_u32_u24_e32 v245, 0xf1, v244
	v_lshrrev_b32_e32 v245, 14, v245
	v_mul_u32_u24_e32 v232, 68, v245
	v_sub_u32_e32 v244, v244, v232
	s_lshl_b32 s17, s9, 2
	v_add_u32_e32 v245, s17, v245
	v_lshl_add_u32 v245, v245, 6, s8
	v_mul_u32_u24_e32 v245, 68, v245
	v_add_u32_e32 v245, v245, v244
	v_lshl_add_u32 v245, v245, 6, v236
	v_lshlrev_b32_e32 v240, 3, v245
	s_waitcnt vmcnt(31)
	v_mov_b32_e32 v200, v246
	v_mov_b32_e32 v201, v247
	v_mov_b32_e32 v202, v248
	v_mov_b32_e32 v203, v249
	v_mov_b32_e32 v204, v250
	v_mov_b32_e32 v205, v251
	v_mov_b32_e32 v206, v252
	v_mov_b32_e32 v207, v253
	s_nop 0
	global_load_dwordx2 v[246:247], v240, s[22:23] offset:0
	global_load_dwordx2 v[248:249], v240, s[22:23] offset:128
	global_load_dwordx2 v[250:251], v240, s[22:23] offset:256
	global_load_dwordx2 v[252:253], v240, s[22:23] offset:384
	v_mfma_f32_16x16x32_bf16 v[136:139], v[56:59], v[0:3], 0
	v_mfma_f32_16x16x32_bf16 v[140:143], v[56:59], v[4:7], 0
	v_mfma_f32_16x16x32_bf16 v[144:147], v[56:59], v[8:11], 0
	v_mfma_f32_16x16x32_bf16 v[148:151], v[56:59], v[12:15], 0
	v_mfma_f32_16x16x32_bf16 v[152:155], v[56:59], v[16:19], 0
	v_mfma_f32_16x16x32_bf16 v[156:159], v[56:59], v[20:23], 0
	v_mfma_f32_16x16x32_bf16 v[160:163], v[56:59], v[24:27], 0
	v_mfma_f32_16x16x32_bf16 v[164:167], v[56:59], v[28:31], 0
	s_waitcnt vmcnt(33)
	v_pk_mov_b32 v[232:233], v[136:137], v[152:153] op_sel:[0,0]
	v_pk_mov_b32 v[234:235], v[140:141], v[156:157] op_sel:[0,0]
	v_pk_mov_b32 v[244:245], v[144:145], v[160:161] op_sel:[0,0]
	v_pk_mov_b32 v[254:255], v[148:149], v[164:165] op_sel:[0,0]
	v_mfma_f32_16x16x32_bf16 v[168:171], v[60:63], v[0:3], 0
	v_pk_fma_f32 v[232:233], v[32:33], v[200:201], v[232:233] op_sel_hi:[0,1,1]
	v_pk_fma_f32 v[234:235], v[34:35], v[202:203], v[234:235] op_sel_hi:[0,1,1]
	v_pk_fma_f32 v[244:245], v[36:37], v[204:205], v[244:245] op_sel_hi:[0,1,1]
	v_pk_fma_f32 v[254:255], v[38:39], v[206:207], v[254:255] op_sel_hi:[0,1,1]
	v_mfma_f32_16x16x32_bf16 v[172:175], v[60:63], v[4:7], 0
	v_pk_fma_f32 v[200:201], v[32:33], v[200:201], v[232:233] op_sel:[1,1,0] op_sel_hi:[1,0,1] neg_lo:[1,0,0]
	v_pk_fma_f32 v[202:203], v[34:35], v[202:203], v[234:235] op_sel:[1,1,0] op_sel_hi:[1,0,1] neg_lo:[1,0,0]
	v_pk_fma_f32 v[204:205], v[36:37], v[204:205], v[244:245] op_sel:[1,1,0] op_sel_hi:[1,0,1] neg_lo:[1,0,0]
	v_pk_fma_f32 v[206:207], v[38:39], v[206:207], v[254:255] op_sel:[1,1,0] op_sel_hi:[1,0,1] neg_lo:[1,0,0]
	v_mfma_f32_16x16x32_bf16 v[176:179], v[60:63], v[8:11], 0
	v_cvt_pk_bf16_f32 v124, v200, v201
	v_cvt_pk_bf16_f32 v125, v202, v203
	v_cvt_pk_bf16_f32 v126, v204, v205
	v_cvt_pk_bf16_f32 v127, v206, v207
	v_mfma_f32_16x16x32_bf16 v[180:183], v[60:63], v[12:15], 0
	ds_write_b128 v241, v[124:127] offset:0
	v_pk_mov_b32 v[232:233], v[136:137], v[152:153] op_sel:[1,1]
	v_pk_mov_b32 v[234:235], v[140:141], v[156:157] op_sel:[1,1]
	v_pk_mov_b32 v[244:245], v[144:145], v[160:161] op_sel:[1,1]
	v_mfma_f32_16x16x32_bf16 v[184:187], v[60:63], v[16:19], 0
	v_pk_mov_b32 v[254:255], v[148:149], v[164:165] op_sel:[1,1]
	v_pk_fma_f32 v[232:233], v[32:33], v[200:201], v[232:233] op_sel_hi:[0,1,1]
	v_pk_fma_f32 v[234:235], v[34:35], v[202:203], v[234:235] op_sel_hi:[0,1,1]
	v_pk_fma_f32 v[244:245], v[36:37], v[204:205], v[244:245] op_sel_hi:[0,1,1]
	v_mfma_f32_16x16x32_bf16 v[188:191], v[60:63], v[20:23], 0
	v_pk_fma_f32 v[254:255], v[38:39], v[206:207], v[254:255] op_sel_hi:[0,1,1]
	v_pk_fma_f32 v[200:201], v[32:33], v[200:201], v[232:233] op_sel:[1,1,0] op_sel_hi:[1,0,1] neg_lo:[1,0,0]
	v_pk_fma_f32 v[202:203], v[34:35], v[202:203], v[234:235] op_sel:[1,1,0] op_sel_hi:[1,0,1] neg_lo:[1,0,0]
	v_pk_fma_f32 v[204:205], v[36:37], v[204:205], v[244:245] op_sel:[1,1,0] op_sel_hi:[1,0,1] neg_lo:[1,0,0]
	v_mfma_f32_16x16x32_bf16 v[192:195], v[60:63], v[24:27], 0
	v_pk_fma_f32 v[206:207], v[38:39], v[206:207], v[254:255] op_sel:[1,1,0] op_sel_hi:[1,0,1] neg_lo:[1,0,0]
	v_cvt_pk_bf16_f32 v124, v200, v201
	v_cvt_pk_bf16_f32 v125, v202, v203
	v_cvt_pk_bf16_f32 v126, v204, v205
; __device__ __forceinline__ unsigned f2bf(float f) { unsigned u = __builtin_bit_cast(unsigned, f); return (u + 0x7fffu + ((u >> 16) & 1u)) >> 16; }
; __device__ __forceinline__ bf16x8 pack8(const float (&f)[8]) { u32x4 h; h.x = pk2(f[0], f[1]); h.y = pk2(f[2], f[3]); h.z = pk2(f[4], f[5]); h.w = pk2(f[6], f[7]); return __builtin_bit_cast(bf16x8, h); }
; template <bool FINAL> __device__ __forceinline__ void phase_s5_scan(const Fr& F) {
;     ...
;         for (int sub = 0; sub < 4; ++sub) {
;             const bf16x8 A1 = __builtin_bit_cast(bf16x8, uc[sub]);
; #pragma unroll
;             for (int nt = 0; nt < 8; ++nt) {
;                 f32x4 acc = {0.f, 0.f, 0.f, 0.f};
;                 acc = __builtin_amdgcn_mfma_f32_16x16x32_bf16(A1, B1[nt], acc, 0, 0, 0);
; #pragma unroll
;                 for (int reg = 0; reg < 4; ++reg) BUl[(4 * lq + reg) * 132 + 16 * nt + l15] = acc[reg];
;             }
;             asm volatile("s_waitcnt lgkmcnt(0)" ::: "memory");
; #pragma unroll 4
;             for (int jj = 0; jj < 16; ++jj) {
;                 const float br_ = BUl[jj * 132 + lane], bi_ = BUl[jj * 132 + 64 + lane];
;                 const float nr = ar * xr - ai * xi + br_, ni = ar * xi + ai * xr + bi_; xr = nr; xi = ni;
;                 if (FINAL) { BUl[jj * 132 + lane] = xr; BUl[jj * 132 + 64 + lane] = xi; }
;             }
;             if (FINAL) {
;                 asm volatile("s_waitcnt lgkmcnt(0)" ::: "memory");
;                 f32x4 acc = {0.f, 0.f, 0.f, 0.f};
; #pragma unroll
;                 for (int ks = 0; ks < 4; ++ks) {
;                     const f32x4 t0 = *(const f32x4*)(BUl + l15 * 132 + 32 * ks + 8 * lq), t1 = *(const f32x4*)(BUl + l15 * 132 + 32 * ks + 8 * lq + 4);
;                     const float xf[8] = {t0.x, t0.y, t0.z, t0.w, t1.x, t1.y, t1.z, t1.w};
;                     acc = __builtin_amdgcn_mfma_f32_16x16x32_bf16(pack8(xf), Chi[ks], acc, 0, 0, 0);
;                 }
; #pragma unroll
;                 for (int reg = 0; reg < 4; ++reg) { const int tok = tokof(s, chunk * 64 + sub * 16 + 4 * lq + reg);
;                     Yb[((size_t)b * TB + tok) * D + g * 16 + l15] = (bf16)f2bf(acc[reg]); }
;                 asm volatile("s_waitcnt lgkmcnt(0)" ::: "memory");
;             }
;         }
	v_mfma_f32_16x16x32_bf16 v[196:199], v[60:63], v[28:31], 0
	v_cvt_pk_bf16_f32 v127, v206, v207
	ds_write_b128 v241, v[124:127] offset:256
	v_pk_mov_b32 v[232:233], v[138:139], v[154:155] op_sel:[0,0]
	v_pk_mov_b32 v[234:235], v[142:143], v[158:159] op_sel:[0,0]
	v_pk_mov_b32 v[244:245], v[146:147], v[162:163] op_sel:[0,0]
	v_pk_mov_b32 v[254:255], v[150:151], v[166:167] op_sel:[0,0]
	v_pk_fma_f32 v[232:233], v[32:33], v[200:201], v[232:233] op_sel_hi:[0,1,1]
	v_pk_fma_f32 v[234:235], v[34:35], v[202:203], v[234:235] op_sel_hi:[0,1,1]
	v_pk_fma_f32 v[244:245], v[36:37], v[204:205], v[244:245] op_sel_hi:[0,1,1]
	v_pk_fma_f32 v[254:255], v[38:39], v[206:207], v[254:255] op_sel_hi:[0,1,1]
	v_pk_fma_f32 v[200:201], v[32:33], v[200:201], v[232:233] op_sel:[1,1,0] op_sel_hi:[1,0,1] neg_lo:[1,0,0]
	v_pk_fma_f32 v[202:203], v[34:35], v[202:203], v[234:235] op_sel:[1,1,0] op_sel_hi:[1,0,1] neg_lo:[1,0,0]
	v_pk_fma_f32 v[204:205], v[36:37], v[204:205], v[244:245] op_sel:[1,1,0] op_sel_hi:[1,0,1] neg_lo:[1,0,0]
	v_pk_fma_f32 v[206:207], v[38:39], v[206:207], v[254:255] op_sel:[1,1,0] op_sel_hi:[1,0,1] neg_lo:[1,0,0]
	v_cvt_pk_bf16_f32 v124, v200, v201
	v_cvt_pk_bf16_f32 v125, v202, v203
	v_cvt_pk_bf16_f32 v126, v204, v205
	v_cvt_pk_bf16_f32 v127, v206, v207
	ds_write_b128 v241, v[124:127] offset:512
	v_pk_mov_b32 v[232:233], v[138:139], v[154:155] op_sel:[1,1]
	v_pk_mov_b32 v[234:235], v[142:143], v[158:159] op_sel:[1,1]
	v_pk_mov_b32 v[244:245], v[146:147], v[162:163] op_sel:[1,1]
	v_pk_mov_b32 v[254:255], v[150:151], v[166:167] op_sel:[1,1]
	v_pk_fma_f32 v[232:233], v[32:33], v[200:201], v[232:233] op_sel_hi:[0,1,1]
	v_pk_fma_f32 v[234:235], v[34:35], v[202:203], v[234:235] op_sel_hi:[0,1,1]
	v_pk_fma_f32 v[244:245], v[36:37], v[204:205], v[244:245] op_sel_hi:[0,1,1]
	v_pk_fma_f32 v[254:255], v[38:39], v[206:207], v[254:255] op_sel_hi:[0,1,1]
	v_pk_fma_f32 v[200:201], v[32:33], v[200:201], v[232:233] op_sel:[1,1,0] op_sel_hi:[1,0,1] neg_lo:[1,0,0]
	v_pk_fma_f32 v[202:203], v[34:35], v[202:203], v[234:235] op_sel:[1,1,0] op_sel_hi:[1,0,1] neg_lo:[1,0,0]
	v_pk_fma_f32 v[204:205], v[36:37], v[204:205], v[244:245] op_sel:[1,1,0] op_sel_hi:[1,0,1] neg_lo:[1,0,0]
	v_pk_fma_f32 v[206:207], v[38:39], v[206:207], v[254:255] op_sel:[1,1,0] op_sel_hi:[1,0,1] neg_lo:[1,0,0]
	v_cvt_pk_bf16_f32 v124, v200, v201
	v_cvt_pk_bf16_f32 v125, v202, v203
	v_cvt_pk_bf16_f32 v126, v204, v205
	v_cvt_pk_bf16_f32 v127, v206, v207
	ds_write_b128 v241, v[124:127] offset:768
	global_load_dwordx4 v[56:59], v238, s[20:21]
	v_add_u32_e32 v238, v238, v243
	s_waitcnt vmcnt(33)
	ds_read_b128 v[216:219], v242 offset:0
	ds_read_b128 v[220:223], v242 offset:64
	ds_read_b128 v[224:227], v242 offset:128
	ds_read_b128 v[228:231], v242 offset:192
	v_pk_mov_b32 v[232:233], v[168:169], v[184:185] op_sel:[0,0]
	v_pk_mov_b32 v[234:235], v[172:173], v[188:189] op_sel:[0,0]
	v_pk_mov_b32 v[244:245], v[176:177], v[192:193] op_sel:[0,0]
	v_pk_mov_b32 v[254:255], v[180:181], v[196:197] op_sel:[0,0]
	v_mfma_f32_16x16x32_bf16 v[136:139], v[64:67], v[0:3], 0
	v_pk_fma_f32 v[232:233], v[32:33], v[200:201], v[232:233] op_sel_hi:[0,1,1]
	v_pk_fma_f32 v[234:235], v[34:35], v[202:203], v[234:235] op_sel_hi:[0,1,1]
	v_pk_fma_f32 v[244:245], v[36:37], v[204:205], v[244:245] op_sel_hi:[0,1,1]
	v_pk_fma_f32 v[254:255], v[38:39], v[206:207], v[254:255] op_sel_hi:[0,1,1]
	v_mfma_f32_16x16x32_bf16 v[140:143], v[64:67], v[4:7], 0
	v_pk_fma_f32 v[200:201], v[32:33], v[200:201], v[232:233] op_sel:[1,1,0] op_sel_hi:[1,0,1] neg_lo:[1,0,0]
	v_pk_fma_f32 v[202:203], v[34:35], v[202:203], v[234:235] op_sel:[1,1,0] op_sel_hi:[1,0,1] neg_lo:[1,0,0]
	v_pk_fma_f32 v[204:205], v[36:37], v[204:205], v[244:245] op_sel:[1,1,0] op_sel_hi:[1,0,1] neg_lo:[1,0,0]
	v_pk_fma_f32 v[206:207], v[38:39], v[206:207], v[254:255] op_sel:[1,1,0] op_sel_hi:[1,0,1] neg_lo:[1,0,0]
	v_mfma_f32_16x16x32_bf16 v[144:147], v[64:67], v[8:11], 0
	v_cvt_pk_bf16_f32 v124, v200, v201
	v_cvt_pk_bf16_f32 v125, v202, v203
	v_cvt_pk_bf16_f32 v126, v204, v205
	v_cvt_pk_bf16_f32 v127, v206, v207
	v_mfma_f32_16x16x32_bf16 v[148:151], v[64:67], v[12:15], 0
	ds_write_b128 v241, v[124:127] offset:4096
	v_pk_mov_b32 v[232:233], v[168:169], v[184:185] op_sel:[1,1]
	v_pk_mov_b32 v[234:235], v[172:173], v[188:189] op_sel:[1,1]
	v_pk_mov_b32 v[244:245], v[176:177], v[192:193] op_sel:[1,1]
	v_mfma_f32_16x16x32_bf16 v[152:155], v[64:67], v[16:19], 0
	v_pk_mov_b32 v[254:255], v[180:181], v[196:197] op_sel:[1,1]
	v_pk_fma_f32 v[232:233], v[32:33], v[200:201], v[232:233] op_sel_hi:[0,1,1]
	v_pk_fma_f32 v[234:235], v[34:35], v[202:203], v[234:235] op_sel_hi:[0,1,1]
	v_pk_fma_f32 v[244:245], v[36:37], v[204:205], v[244:245] op_sel_hi:[0,1,1]
	v_mfma_f32_16x16x32_bf16 v[156:159], v[64:67], v[20:23], 0
	v_pk_fma_f32 v[254:255], v[38:39], v[206:207], v[254:255] op_sel_hi:[0,1,1]
	v_pk_fma_f32 v[200:201], v[32:33], v[200:201], v[232:233] op_sel:[1,1,0] op_sel_hi:[1,0,1] neg_lo:[1,0,0]
	v_pk_fma_f32 v[202:203], v[34:35], v[202:203], v[234:235] op_sel:[1,1,0] op_sel_hi:[1,0,1] neg_lo:[1,0,0]
	v_pk_fma_f32 v[204:205], v[36:37], v[204:205], v[244:245] op_sel:[1,1,0] op_sel_hi:[1,0,1] neg_lo:[1,0,0]
	v_mfma_f32_16x16x32_bf16 v[160:163], v[64:67], v[24:27], 0
	v_pk_fma_f32 v[206:207], v[38:39], v[206:207], v[254:255] op_sel:[1,1,0] op_sel_hi:[1,0,1] neg_lo:[1,0,0]
	v_cvt_pk_bf16_f32 v124, v200, v201
	v_cvt_pk_bf16_f32 v125, v202, v203
	v_cvt_pk_bf16_f32 v126, v204, v205
	v_mfma_f32_16x16x32_bf16 v[164:167], v[64:67], v[28:31], 0
	v_cvt_pk_bf16_f32 v127, v206, v207
	ds_write_b128 v241, v[124:127] offset:4352
	s_waitcnt lgkmcnt(2)
; __device__ __forceinline__ unsigned f2bf(float f) { unsigned u = __builtin_bit_cast(unsigned, f); return (u + 0x7fffu + ((u >> 16) & 1u)) >> 16; }
; __device__ __forceinline__ bf16x8 pack8(const float (&f)[8]) { u32x4 h; h.x = pk2(f[0], f[1]); h.y = pk2(f[2], f[3]); h.z = pk2(f[4], f[5]); h.w = pk2(f[6], f[7]); return __builtin_bit_cast(bf16x8, h); }
; template <bool FINAL> __device__ __forceinline__ void phase_s5_scan(const Fr& F) {
;     ...
;         for (int sub = 0; sub < 4; ++sub) {
;             const bf16x8 A1 = __builtin_bit_cast(bf16x8, uc[sub]);
; #pragma unroll
;             for (int nt = 0; nt < 8; ++nt) {
;                 f32x4 acc = {0.f, 0.f, 0.f, 0.f};
;                 acc = __builtin_amdgcn_mfma_f32_16x16x32_bf16(A1, B1[nt], acc, 0, 0, 0);
; #pragma unroll
;                 for (int reg = 0; reg < 4; ++reg) BUl[(4 * lq + reg) * 132 + 16 * nt + l15] = acc[reg];
;             }
;             asm volatile("s_waitcnt lgkmcnt(0)" ::: "memory");
; #pragma unroll 4
;             for (int jj = 0; jj < 16; ++jj) {
;                 const float br_ = BUl[jj * 132 + lane], bi_ = BUl[jj * 132 + 64 + lane];
;                 const float nr = ar * xr - ai * xi + br_, ni = ar * xi + ai * xr + bi_; xr = nr; xi = ni;
;                 if (FINAL) { BUl[jj * 132 + lane] = xr; BUl[jj * 132 + 64 + lane] = xi; }
;             }
;             if (FINAL) {
;                 asm volatile("s_waitcnt lgkmcnt(0)" ::: "memory");
;                 f32x4 acc = {0.f, 0.f, 0.f, 0.f};
; #pragma unroll
;                 for (int ks = 0; ks < 4; ++ks) {
;                     const f32x4 t0 = *(const f32x4*)(BUl + l15 * 132 + 32 * ks + 8 * lq), t1 = *(const f32x4*)(BUl + l15 * 132 + 32 * ks + 8 * lq + 4);
;                     const float xf[8] = {t0.x, t0.y, t0.z, t0.w, t1.x, t1.y, t1.z, t1.w};
;                     acc = __builtin_amdgcn_mfma_f32_16x16x32_bf16(pack8(xf), Chi[ks], acc, 0, 0, 0);
;                 }
; #pragma unroll
;                 for (int reg = 0; reg < 4; ++reg) { const int tok = tokof(s, chunk * 64 + sub * 16 + 4 * lq + reg);
;                     Yb[((size_t)b * TB + tok) * D + g * 16 + l15] = (bf16)f2bf(acc[reg]); }
;                 asm volatile("s_waitcnt lgkmcnt(0)" ::: "memory");
;             }
;         }
	v_pk_mov_b32 v[232:233], v[170:171], v[186:187] op_sel:[0,0]
	v_pk_mov_b32 v[234:235], v[174:175], v[190:191] op_sel:[0,0]
	v_pk_mov_b32 v[244:245], v[178:179], v[194:195] op_sel:[0,0]
	v_pk_mov_b32 v[254:255], v[182:183], v[198:199] op_sel:[0,0]
	v_mfma_f32_16x16x32_bf16 v[120:123], v[40:43], v[216:219], 0
	v_pk_fma_f32 v[232:233], v[32:33], v[200:201], v[232:233] op_sel_hi:[0,1,1]
	v_pk_fma_f32 v[234:235], v[34:35], v[202:203], v[234:235] op_sel_hi:[0,1,1]
	v_pk_fma_f32 v[244:245], v[36:37], v[204:205], v[244:245] op_sel_hi:[0,1,1]
	v_pk_fma_f32 v[254:255], v[38:39], v[206:207], v[254:255] op_sel_hi:[0,1,1]
	v_mfma_f32_16x16x32_bf16 v[120:123], v[44:47], v[220:223], v[120:123]
	v_pk_fma_f32 v[200:201], v[32:33], v[200:201], v[232:233] op_sel:[1,1,0] op_sel_hi:[1,0,1] neg_lo:[1,0,0]
	v_pk_fma_f32 v[202:203], v[34:35], v[202:203], v[234:235] op_sel:[1,1,0] op_sel_hi:[1,0,1] neg_lo:[1,0,0]
	v_pk_fma_f32 v[204:205], v[36:37], v[204:205], v[244:245] op_sel:[1,1,0] op_sel_hi:[1,0,1] neg_lo:[1,0,0]
	v_pk_fma_f32 v[206:207], v[38:39], v[206:207], v[254:255] op_sel:[1,1,0] op_sel_hi:[1,0,1] neg_lo:[1,0,0]
	v_mfma_f32_16x16x32_bf16 v[120:123], v[48:51], v[224:227], v[120:123]
	v_cvt_pk_bf16_f32 v124, v200, v201
	v_cvt_pk_bf16_f32 v125, v202, v203
	v_cvt_pk_bf16_f32 v126, v204, v205
	v_cvt_pk_bf16_f32 v127, v206, v207
	v_mfma_f32_16x16x32_bf16 v[120:123], v[52:55], v[228:231], v[120:123]
	ds_write_b128 v241, v[124:127] offset:4608
	v_pk_mov_b32 v[232:233], v[170:171], v[186:187] op_sel:[1,1]
	v_pk_mov_b32 v[234:235], v[174:175], v[190:191] op_sel:[1,1]
	v_pk_mov_b32 v[244:245], v[178:179], v[194:195] op_sel:[1,1]
	v_pk_mov_b32 v[254:255], v[182:183], v[198:199] op_sel:[1,1]
	v_pk_fma_f32 v[232:233], v[32:33], v[200:201], v[232:233] op_sel_hi:[0,1,1]
	v_pk_fma_f32 v[234:235], v[34:35], v[202:203], v[234:235] op_sel_hi:[0,1,1]
	v_pk_fma_f32 v[244:245], v[36:37], v[204:205], v[244:245] op_sel_hi:[0,1,1]
	v_pk_fma_f32 v[254:255], v[38:39], v[206:207], v[254:255] op_sel_hi:[0,1,1]
	v_pk_fma_f32 v[200:201], v[32:33], v[200:201], v[232:233] op_sel:[1,1,0] op_sel_hi:[1,0,1] neg_lo:[1,0,0]
	v_pk_fma_f32 v[202:203], v[34:35], v[202:203], v[234:235] op_sel:[1,1,0] op_sel_hi:[1,0,1] neg_lo:[1,0,0]
	v_pk_fma_f32 v[204:205], v[36:37], v[204:205], v[244:245] op_sel:[1,1,0] op_sel_hi:[1,0,1] neg_lo:[1,0,0]
	v_pk_fma_f32 v[206:207], v[38:39], v[206:207], v[254:255] op_sel:[1,1,0] op_sel_hi:[1,0,1] neg_lo:[1,0,0]
	v_cvt_pk_bf16_f32 v124, v200, v201
	v_cvt_pk_bf16_f32 v125, v202, v203
	v_cvt_pk_bf16_f32 v126, v204, v205
	v_cvt_pk_bf16_f32 v127, v206, v207
	ds_write_b128 v241, v[124:127] offset:4864
	global_load_dwordx4 v[60:63], v238, s[20:21]
	v_add_u32_e32 v238, v238, v243
	v_cvt_pk_bf16_f32 v124, v120, v121
	v_cvt_pk_bf16_f32 v125, v122, v123
	s_nop 0
	global_store_dwordx2 v239, v[124:125], s[24:25]
	v_add_u32_e32 v239, v239, v243
	s_waitcnt vmcnt(33)
	ds_read_b128 v[216:219], v242 offset:4096
	ds_read_b128 v[220:223], v242 offset:4160
	ds_read_b128 v[224:227], v242 offset:4224
	ds_read_b128 v[228:231], v242 offset:4288
	v_pk_mov_b32 v[232:233], v[136:137], v[152:153] op_sel:[0,0]
	v_pk_mov_b32 v[234:235], v[140:141], v[156:157] op_sel:[0,0]
	v_pk_mov_b32 v[244:245], v[144:145], v[160:161] op_sel:[0,0]
	v_pk_mov_b32 v[254:255], v[148:149], v[164:165] op_sel:[0,0]
	v_mfma_f32_16x16x32_bf16 v[168:171], v[68:71], v[0:3], 0
	v_pk_fma_f32 v[232:233], v[32:33], v[200:201], v[232:233] op_sel_hi:[0,1,1]
	v_pk_fma_f32 v[234:235], v[34:35], v[202:203], v[234:235] op_sel_hi:[0,1,1]
	v_pk_fma_f32 v[244:245], v[36:37], v[204:205], v[244:245] op_sel_hi:[0,1,1]
	v_pk_fma_f32 v[254:255], v[38:39], v[206:207], v[254:255] op_sel_hi:[0,1,1]
	v_mfma_f32_16x16x32_bf16 v[172:175], v[68:71], v[4:7], 0
	v_pk_fma_f32 v[200:201], v[32:33], v[200:201], v[232:233] op_sel:[1,1,0] op_sel_hi:[1,0,1] neg_lo:[1,0,0]
	v_pk_fma_f32 v[202:203], v[34:35], v[202:203], v[234:235] op_sel:[1,1,0] op_sel_hi:[1,0,1] neg_lo:[1,0,0]
	v_pk_fma_f32 v[204:205], v[36:37], v[204:205], v[244:245] op_sel:[1,1,0] op_sel_hi:[1,0,1] neg_lo:[1,0,0]
	v_pk_fma_f32 v[206:207], v[38:39], v[206:207], v[254:255] op_sel:[1,1,0] op_sel_hi:[1,0,1] neg_lo:[1,0,0]
	v_mfma_f32_16x16x32_bf16 v[176:179], v[68:71], v[8:11], 0
	v_cvt_pk_bf16_f32 v124, v200, v201
	v_cvt_pk_bf16_f32 v125, v202, v203
	v_cvt_pk_bf16_f32 v126, v204, v205
	v_cvt_pk_bf16_f32 v127, v206, v207
	v_mfma_f32_16x16x32_bf16 v[180:183], v[68:71], v[12:15], 0
	ds_write_b128 v241, v[124:127] offset:0
	v_pk_mov_b32 v[232:233], v[136:137], v[152:153] op_sel:[1,1]
	v_pk_mov_b32 v[234:235], v[140:141], v[156:157] op_sel:[1,1]
	v_pk_mov_b32 v[244:245], v[144:145], v[160:161] op_sel:[1,1]
	v_mfma_f32_16x16x32_bf16 v[184:187], v[68:71], v[16:19], 0
	v_pk_mov_b32 v[254:255], v[148:149], v[164:165] op_sel:[1,1]
	v_pk_fma_f32 v[232:233], v[32:33], v[200:201], v[232:233] op_sel_hi:[0,1,1]
	v_pk_fma_f32 v[234:235], v[34:35], v[202:203], v[234:235] op_sel_hi:[0,1,1]
	v_pk_fma_f32 v[244:245], v[36:37], v[204:205], v[244:245] op_sel_hi:[0,1,1]
	v_mfma_f32_16x16x32_bf16 v[188:191], v[68:71], v[20:23], 0
	v_pk_fma_f32 v[254:255], v[38:39], v[206:207], v[254:255] op_sel_hi:[0,1,1]
	v_pk_fma_f32 v[200:201], v[32:33], v[200:201], v[232:233] op_sel:[1,1,0] op_sel_hi:[1,0,1] neg_lo:[1,0,0]
	v_pk_fma_f32 v[202:203], v[34:35], v[202:203], v[234:235] op_sel:[1,1,0] op_sel_hi:[1,0,1] neg_lo:[1,0,0]
	v_pk_fma_f32 v[204:205], v[36:37], v[204:205], v[244:245] op_sel:[1,1,0] op_sel_hi:[1,0,1] neg_lo:[1,0,0]
	v_mfma_f32_16x16x32_bf16 v[192:195], v[68:71], v[24:27], 0
	v_pk_fma_f32 v[206:207], v[38:39], v[206:207], v[254:255] op_sel:[1,1,0] op_sel_hi:[1,0,1] neg_lo:[1,0,0]
	v_cvt_pk_bf16_f32 v124, v200, v201
	v_cvt_pk_bf16_f32 v125, v202, v203
	v_cvt_pk_bf16_f32 v126, v204, v205
	v_mfma_f32_16x16x32_bf16 v[196:199], v[68:71], v[28:31], 0
	v_cvt_pk_bf16_f32 v127, v206, v207
	ds_write_b128 v241, v[124:127] offset:256
	s_waitcnt lgkmcnt(2)
; __device__ __forceinline__ unsigned f2bf(float f) { unsigned u = __builtin_bit_cast(unsigned, f); return (u + 0x7fffu + ((u >> 16) & 1u)) >> 16; }
; __device__ __forceinline__ bf16x8 pack8(const float (&f)[8]) { u32x4 h; h.x = pk2(f[0], f[1]); h.y = pk2(f[2], f[3]); h.z = pk2(f[4], f[5]); h.w = pk2(f[6], f[7]); return __builtin_bit_cast(bf16x8, h); }
; template <bool FINAL> __device__ __forceinline__ void phase_s5_scan(const Fr& F) {
;     ...
;         for (int sub = 0; sub < 4; ++sub) {
;             const bf16x8 A1 = __builtin_bit_cast(bf16x8, uc[sub]);
; #pragma unroll
;             for (int nt = 0; nt < 8; ++nt) {
;                 f32x4 acc = {0.f, 0.f, 0.f, 0.f};
;                 acc = __builtin_amdgcn_mfma_f32_16x16x32_bf16(A1, B1[nt], acc, 0, 0, 0);
; #pragma unroll
;                 for (int reg = 0; reg < 4; ++reg) BUl[(4 * lq + reg) * 132 + 16 * nt + l15] = acc[reg];
;             }
;             asm volatile("s_waitcnt lgkmcnt(0)" ::: "memory");
; #pragma unroll 4
;             for (int jj = 0; jj < 16; ++jj) {
;                 const float br_ = BUl[jj * 132 + lane], bi_ = BUl[jj * 132 + 64 + lane];
;                 const float nr = ar * xr - ai * xi + br_, ni = ar * xi + ai * xr + bi_; xr = nr; xi = ni;
;                 if (FINAL) { BUl[jj * 132 + lane] = xr; BUl[jj * 132 + 64 + lane] = xi; }
;             }
;             if (FINAL) {
;                 asm volatile("s_waitcnt lgkmcnt(0)" ::: "memory");
;                 f32x4 acc = {0.f, 0.f, 0.f, 0.f};
; #pragma unroll
;                 for (int ks = 0; ks < 4; ++ks) {
;                     const f32x4 t0 = *(const f32x4*)(BUl + l15 * 132 + 32 * ks + 8 * lq), t1 = *(const f32x4*)(BUl + l15 * 132 + 32 * ks + 8 * lq + 4);
;                     const float xf[8] = {t0.x, t0.y, t0.z, t0.w, t1.x, t1.y, t1.z, t1.w};
;                     acc = __builtin_amdgcn_mfma_f32_16x16x32_bf16(pack8(xf), Chi[ks], acc, 0, 0, 0);
;                 }
; #pragma unroll
;                 for (int reg = 0; reg < 4; ++reg) { const int tok = tokof(s, chunk * 64 + sub * 16 + 4 * lq + reg);
;                     Yb[((size_t)b * TB + tok) * D + g * 16 + l15] = (bf16)f2bf(acc[reg]); }
;                 asm volatile("s_waitcnt lgkmcnt(0)" ::: "memory");
;             }
;         }
	v_pk_mov_b32 v[232:233], v[138:139], v[154:155] op_sel:[0,0]
	v_pk_mov_b32 v[234:235], v[142:143], v[158:159] op_sel:[0,0]
	v_pk_mov_b32 v[244:245], v[146:147], v[162:163] op_sel:[0,0]
	v_pk_mov_b32 v[254:255], v[150:151], v[166:167] op_sel:[0,0]
	v_mfma_f32_16x16x32_bf16 v[120:123], v[40:43], v[216:219], 0
	v_pk_fma_f32 v[232:233], v[32:33], v[200:201], v[232:233] op_sel_hi:[0,1,1]
	v_pk_fma_f32 v[234:235], v[34:35], v[202:203], v[234:235] op_sel_hi:[0,1,1]
	v_pk_fma_f32 v[244:245], v[36:37], v[204:205], v[244:245] op_sel_hi:[0,1,1]
	v_pk_fma_f32 v[254:255], v[38:39], v[206:207], v[254:255] op_sel_hi:[0,1,1]
	v_mfma_f32_16x16x32_bf16 v[120:123], v[44:47], v[220:223], v[120:123]
	v_pk_fma_f32 v[200:201], v[32:33], v[200:201], v[232:233] op_sel:[1,1,0] op_sel_hi:[1,0,1] neg_lo:[1,0,0]
	v_pk_fma_f32 v[202:203], v[34:35], v[202:203], v[234:235] op_sel:[1,1,0] op_sel_hi:[1,0,1] neg_lo:[1,0,0]
	v_pk_fma_f32 v[204:205], v[36:37], v[204:205], v[244:245] op_sel:[1,1,0] op_sel_hi:[1,0,1] neg_lo:[1,0,0]
	v_pk_fma_f32 v[206:207], v[38:39], v[206:207], v[254:255] op_sel:[1,1,0] op_sel_hi:[1,0,1] neg_lo:[1,0,0]
	v_mfma_f32_16x16x32_bf16 v[120:123], v[48:51], v[224:227], v[120:123]
	v_cvt_pk_bf16_f32 v124, v200, v201
	v_cvt_pk_bf16_f32 v125, v202, v203
	v_cvt_pk_bf16_f32 v126, v204, v205
	v_cvt_pk_bf16_f32 v127, v206, v207
	v_mfma_f32_16x16x32_bf16 v[120:123], v[52:55], v[228:231], v[120:123]
	ds_write_b128 v241, v[124:127] offset:512
	v_pk_mov_b32 v[232:233], v[138:139], v[154:155] op_sel:[1,1]
	v_pk_mov_b32 v[234:235], v[142:143], v[158:159] op_sel:[1,1]
	v_pk_mov_b32 v[244:245], v[146:147], v[162:163] op_sel:[1,1]
	v_pk_mov_b32 v[254:255], v[150:151], v[166:167] op_sel:[1,1]
	v_pk_fma_f32 v[232:233], v[32:33], v[200:201], v[232:233] op_sel_hi:[0,1,1]
	v_pk_fma_f32 v[234:235], v[34:35], v[202:203], v[234:235] op_sel_hi:[0,1,1]
	v_pk_fma_f32 v[244:245], v[36:37], v[204:205], v[244:245] op_sel_hi:[0,1,1]
	v_pk_fma_f32 v[254:255], v[38:39], v[206:207], v[254:255] op_sel_hi:[0,1,1]
	v_pk_fma_f32 v[200:201], v[32:33], v[200:201], v[232:233] op_sel:[1,1,0] op_sel_hi:[1,0,1] neg_lo:[1,0,0]
	v_pk_fma_f32 v[202:203], v[34:35], v[202:203], v[234:235] op_sel:[1,1,0] op_sel_hi:[1,0,1] neg_lo:[1,0,0]
	v_pk_fma_f32 v[204:205], v[36:37], v[204:205], v[244:245] op_sel:[1,1,0] op_sel_hi:[1,0,1] neg_lo:[1,0,0]
	v_pk_fma_f32 v[206:207], v[38:39], v[206:207], v[254:255] op_sel:[1,1,0] op_sel_hi:[1,0,1] neg_lo:[1,0,0]
	v_cvt_pk_bf16_f32 v124, v200, v201
	v_cvt_pk_bf16_f32 v125, v202, v203
	v_cvt_pk_bf16_f32 v126, v204, v205
	v_cvt_pk_bf16_f32 v127, v206, v207
	ds_write_b128 v241, v[124:127] offset:768
	global_load_dwordx4 v[64:67], v238, s[20:21]
	v_add_u32_e32 v238, v238, v243
	v_cvt_pk_bf16_f32 v124, v120, v121
	v_cvt_pk_bf16_f32 v125, v122, v123
	s_nop 0
	global_store_dwordx2 v239, v[124:125], s[24:25]
	v_add_u32_e32 v239, v239, v243
	s_waitcnt vmcnt(33)
	ds_read_b128 v[216:219], v242 offset:0
	ds_read_b128 v[220:223], v242 offset:64
	ds_read_b128 v[224:227], v242 offset:128
	ds_read_b128 v[228:231], v242 offset:192
	v_pk_mov_b32 v[232:233], v[168:169], v[184:185] op_sel:[0,0]
	v_pk_mov_b32 v[234:235], v[172:173], v[188:189] op_sel:[0,0]
	v_pk_mov_b32 v[244:245], v[176:177], v[192:193] op_sel:[0,0]
	v_pk_mov_b32 v[254:255], v[180:181], v[196:197] op_sel:[0,0]
	v_mfma_f32_16x16x32_bf16 v[136:139], v[72:75], v[0:3], 0
	v_pk_fma_f32 v[232:233], v[32:33], v[200:201], v[232:233] op_sel_hi:[0,1,1]
	v_pk_fma_f32 v[234:235], v[34:35], v[202:203], v[234:235] op_sel_hi:[0,1,1]
	v_pk_fma_f32 v[244:245], v[36:37], v[204:205], v[244:245] op_sel_hi:[0,1,1]
	v_pk_fma_f32 v[254:255], v[38:39], v[206:207], v[254:255] op_sel_hi:[0,1,1]
	v_mfma_f32_16x16x32_bf16 v[140:143], v[72:75], v[4:7], 0
	v_pk_fma_f32 v[200:201], v[32:33], v[200:201], v[232:233] op_sel:[1,1,0] op_sel_hi:[1,0,1] neg_lo:[1,0,0]
	v_pk_fma_f32 v[202:203], v[34:35], v[202:203], v[234:235] op_sel:[1,1,0] op_sel_hi:[1,0,1] neg_lo:[1,0,0]
	v_pk_fma_f32 v[204:205], v[36:37], v[204:205], v[244:245] op_sel:[1,1,0] op_sel_hi:[1,0,1] neg_lo:[1,0,0]
	v_pk_fma_f32 v[206:207], v[38:39], v[206:207], v[254:255] op_sel:[1,1,0] op_sel_hi:[1,0,1] neg_lo:[1,0,0]
	v_mfma_f32_16x16x32_bf16 v[144:147], v[72:75], v[8:11], 0
	v_cvt_pk_bf16_f32 v124, v200, v201
	v_cvt_pk_bf16_f32 v125, v202, v203
	v_cvt_pk_bf16_f32 v126, v204, v205
	v_cvt_pk_bf16_f32 v127, v206, v207
	v_mfma_f32_16x16x32_bf16 v[148:151], v[72:75], v[12:15], 0
	ds_write_b128 v241, v[124:127] offset:4096
	v_pk_mov_b32 v[232:233], v[168:169], v[184:185] op_sel:[1,1]
	v_pk_mov_b32 v[234:235], v[172:173], v[188:189] op_sel:[1,1]
	v_pk_mov_b32 v[244:245], v[176:177], v[192:193] op_sel:[1,1]
	v_mfma_f32_16x16x32_bf16 v[152:155], v[72:75], v[16:19], 0
	v_pk_mov_b32 v[254:255], v[180:181], v[196:197] op_sel:[1,1]
	v_pk_fma_f32 v[232:233], v[32:33], v[200:201], v[232:233] op_sel_hi:[0,1,1]
	v_pk_fma_f32 v[234:235], v[34:35], v[202:203], v[234:235] op_sel_hi:[0,1,1]
	v_pk_fma_f32 v[244:245], v[36:37], v[204:205], v[244:245] op_sel_hi:[0,1,1]
	v_mfma_f32_16x16x32_bf16 v[156:159], v[72:75], v[20:23], 0
	v_pk_fma_f32 v[254:255], v[38:39], v[206:207], v[254:255] op_sel_hi:[0,1,1]
	v_pk_fma_f32 v[200:201], v[32:33], v[200:201], v[232:233] op_sel:[1,1,0] op_sel_hi:[1,0,1] neg_lo:[1,0,0]
	v_pk_fma_f32 v[202:203], v[34:35], v[202:203], v[234:235] op_sel:[1,1,0] op_sel_hi:[1,0,1] neg_lo:[1,0,0]
	v_pk_fma_f32 v[204:205], v[36:37], v[204:205], v[244:245] op_sel:[1,1,0] op_sel_hi:[1,0,1] neg_lo:[1,0,0]
	v_mfma_f32_16x16x32_bf16 v[160:163], v[72:75], v[24:27], 0
	v_pk_fma_f32 v[206:207], v[38:39], v[206:207], v[254:255] op_sel:[1,1,0] op_sel_hi:[1,0,1] neg_lo:[1,0,0]
	v_cvt_pk_bf16_f32 v124, v200, v201
	v_cvt_pk_bf16_f32 v125, v202, v203
	v_cvt_pk_bf16_f32 v126, v204, v205
	v_mfma_f32_16x16x32_bf16 v[164:167], v[72:75], v[28:31], 0
	v_cvt_pk_bf16_f32 v127, v206, v207
	ds_write_b128 v241, v[124:127] offset:4352
	s_waitcnt lgkmcnt(2)
; __device__ __forceinline__ unsigned f2bf(float f) { unsigned u = __builtin_bit_cast(unsigned, f); return (u + 0x7fffu + ((u >> 16) & 1u)) >> 16; }
; __device__ __forceinline__ bf16x8 pack8(const float (&f)[8]) { u32x4 h; h.x = pk2(f[0], f[1]); h.y = pk2(f[2], f[3]); h.z = pk2(f[4], f[5]); h.w = pk2(f[6], f[7]); return __builtin_bit_cast(bf16x8, h); }
; template <bool FINAL> __device__ __forceinline__ void phase_s5_scan(const Fr& F) {
;     ...
;         for (int sub = 0; sub < 4; ++sub) {
;             const bf16x8 A1 = __builtin_bit_cast(bf16x8, uc[sub]);
; #pragma unroll
;             for (int nt = 0; nt < 8; ++nt) {
;                 f32x4 acc = {0.f, 0.f, 0.f, 0.f};
;                 acc = __builtin_amdgcn_mfma_f32_16x16x32_bf16(A1, B1[nt], acc, 0, 0, 0);
; #pragma unroll
;                 for (int reg = 0; reg < 4; ++reg) BUl[(4 * lq + reg) * 132 + 16 * nt + l15] = acc[reg];
;             }
;             asm volatile("s_waitcnt lgkmcnt(0)" ::: "memory");
; #pragma unroll 4
;             for (int jj = 0; jj < 16; ++jj) {
;                 const float br_ = BUl[jj * 132 + lane], bi_ = BUl[jj * 132 + 64 + lane];
;                 const float nr = ar * xr - ai * xi + br_, ni = ar * xi + ai * xr + bi_; xr = nr; xi = ni;
;                 if (FINAL) { BUl[jj * 132 + lane] = xr; BUl[jj * 132 + 64 + lane] = xi; }
;             }
;             if (FINAL) {
;                 asm volatile("s_waitcnt lgkmcnt(0)" ::: "memory");
;                 f32x4 acc = {0.f, 0.f, 0.f, 0.f};
; #pragma unroll
;                 for (int ks = 0; ks < 4; ++ks) {
;                     const f32x4 t0 = *(const f32x4*)(BUl + l15 * 132 + 32 * ks + 8 * lq), t1 = *(const f32x4*)(BUl + l15 * 132 + 32 * ks + 8 * lq + 4);
;                     const float xf[8] = {t0.x, t0.y, t0.z, t0.w, t1.x, t1.y, t1.z, t1.w};
;                     acc = __builtin_amdgcn_mfma_f32_16x16x32_bf16(pack8(xf), Chi[ks], acc, 0, 0, 0);
;                 }
; #pragma unroll
;                 for (int reg = 0; reg < 4; ++reg) { const int tok = tokof(s, chunk * 64 + sub * 16 + 4 * lq + reg);
;                     Yb[((size_t)b * TB + tok) * D + g * 16 + l15] = (bf16)f2bf(acc[reg]); }
;                 asm volatile("s_waitcnt lgkmcnt(0)" ::: "memory");
;             }
;         }
	v_pk_mov_b32 v[232:233], v[170:171], v[186:187] op_sel:[0,0]
	v_pk_mov_b32 v[234:235], v[174:175], v[190:191] op_sel:[0,0]
	v_pk_mov_b32 v[244:245], v[178:179], v[194:195] op_sel:[0,0]
	v_pk_mov_b32 v[254:255], v[182:183], v[198:199] op_sel:[0,0]
	v_mfma_f32_16x16x32_bf16 v[120:123], v[40:43], v[216:219], 0
	v_pk_fma_f32 v[232:233], v[32:33], v[200:201], v[232:233] op_sel_hi:[0,1,1]
	v_pk_fma_f32 v[234:235], v[34:35], v[202:203], v[234:235] op_sel_hi:[0,1,1]
	v_pk_fma_f32 v[244:245], v[36:37], v[204:205], v[244:245] op_sel_hi:[0,1,1]
	v_pk_fma_f32 v[254:255], v[38:39], v[206:207], v[254:255] op_sel_hi:[0,1,1]
	v_mfma_f32_16x16x32_bf16 v[120:123], v[44:47], v[220:223], v[120:123]
	v_pk_fma_f32 v[200:201], v[32:33], v[200:201], v[232:233] op_sel:[1,1,0] op_sel_hi:[1,0,1] neg_lo:[1,0,0]
	v_pk_fma_f32 v[202:203], v[34:35], v[202:203], v[234:235] op_sel:[1,1,0] op_sel_hi:[1,0,1] neg_lo:[1,0,0]
	v_pk_fma_f32 v[204:205], v[36:37], v[204:205], v[244:245] op_sel:[1,1,0] op_sel_hi:[1,0,1] neg_lo:[1,0,0]
	v_pk_fma_f32 v[206:207], v[38:39], v[206:207], v[254:255] op_sel:[1,1,0] op_sel_hi:[1,0,1] neg_lo:[1,0,0]
	v_mfma_f32_16x16x32_bf16 v[120:123], v[48:51], v[224:227], v[120:123]
	v_cvt_pk_bf16_f32 v124, v200, v201
	v_cvt_pk_bf16_f32 v125, v202, v203
	v_cvt_pk_bf16_f32 v126, v204, v205
	v_cvt_pk_bf16_f32 v127, v206, v207
	v_mfma_f32_16x16x32_bf16 v[120:123], v[52:55], v[228:231], v[120:123]
	ds_write_b128 v241, v[124:127] offset:4608
	v_pk_mov_b32 v[232:233], v[170:171], v[186:187] op_sel:[1,1]
	v_pk_mov_b32 v[234:235], v[174:175], v[190:191] op_sel:[1,1]
	v_pk_mov_b32 v[244:245], v[178:179], v[194:195] op_sel:[1,1]
	v_pk_mov_b32 v[254:255], v[182:183], v[198:199] op_sel:[1,1]
	v_pk_fma_f32 v[232:233], v[32:33], v[200:201], v[232:233] op_sel_hi:[0,1,1]
	v_pk_fma_f32 v[234:235], v[34:35], v[202:203], v[234:235] op_sel_hi:[0,1,1]
	v_pk_fma_f32 v[244:245], v[36:37], v[204:205], v[244:245] op_sel_hi:[0,1,1]
	v_pk_fma_f32 v[254:255], v[38:39], v[206:207], v[254:255] op_sel_hi:[0,1,1]
	v_pk_fma_f32 v[200:201], v[32:33], v[200:201], v[232:233] op_sel:[1,1,0] op_sel_hi:[1,0,1] neg_lo:[1,0,0]
	v_pk_fma_f32 v[202:203], v[34:35], v[202:203], v[234:235] op_sel:[1,1,0] op_sel_hi:[1,0,1] neg_lo:[1,0,0]
	v_pk_fma_f32 v[204:205], v[36:37], v[204:205], v[244:245] op_sel:[1,1,0] op_sel_hi:[1,0,1] neg_lo:[1,0,0]
	v_pk_fma_f32 v[206:207], v[38:39], v[206:207], v[254:255] op_sel:[1,1,0] op_sel_hi:[1,0,1] neg_lo:[1,0,0]
	v_cvt_pk_bf16_f32 v124, v200, v201
	v_cvt_pk_bf16_f32 v125, v202, v203
	v_cvt_pk_bf16_f32 v126, v204, v205
	v_cvt_pk_bf16_f32 v127, v206, v207
	ds_write_b128 v241, v[124:127] offset:4864
	global_load_dwordx4 v[68:71], v238, s[20:21]
	v_add_u32_e32 v238, v238, v243
	v_cvt_pk_bf16_f32 v124, v120, v121
	v_cvt_pk_bf16_f32 v125, v122, v123
	s_nop 0
	global_store_dwordx2 v239, v[124:125], s[24:25]
	v_add_u32_e32 v239, v239, v243
	s_waitcnt vmcnt(33)
	ds_read_b128 v[216:219], v242 offset:4096
	ds_read_b128 v[220:223], v242 offset:4160
	ds_read_b128 v[224:227], v242 offset:4224
	ds_read_b128 v[228:231], v242 offset:4288
	v_pk_mov_b32 v[232:233], v[136:137], v[152:153] op_sel:[0,0]
	v_pk_mov_b32 v[234:235], v[140:141], v[156:157] op_sel:[0,0]
	v_pk_mov_b32 v[244:245], v[144:145], v[160:161] op_sel:[0,0]
	v_pk_mov_b32 v[254:255], v[148:149], v[164:165] op_sel:[0,0]
	v_mfma_f32_16x16x32_bf16 v[168:171], v[76:79], v[0:3], 0
	v_pk_fma_f32 v[232:233], v[32:33], v[200:201], v[232:233] op_sel_hi:[0,1,1]
	v_pk_fma_f32 v[234:235], v[34:35], v[202:203], v[234:235] op_sel_hi:[0,1,1]
	v_pk_fma_f32 v[244:245], v[36:37], v[204:205], v[244:245] op_sel_hi:[0,1,1]
	v_pk_fma_f32 v[254:255], v[38:39], v[206:207], v[254:255] op_sel_hi:[0,1,1]
	v_mfma_f32_16x16x32_bf16 v[172:175], v[76:79], v[4:7], 0
	v_pk_fma_f32 v[200:201], v[32:33], v[200:201], v[232:233] op_sel:[1,1,0] op_sel_hi:[1,0,1] neg_lo:[1,0,0]
	v_pk_fma_f32 v[202:203], v[34:35], v[202:203], v[234:235] op_sel:[1,1,0] op_sel_hi:[1,0,1] neg_lo:[1,0,0]
	v_pk_fma_f32 v[204:205], v[36:37], v[204:205], v[244:245] op_sel:[1,1,0] op_sel_hi:[1,0,1] neg_lo:[1,0,0]
	v_pk_fma_f32 v[206:207], v[38:39], v[206:207], v[254:255] op_sel:[1,1,0] op_sel_hi:[1,0,1] neg_lo:[1,0,0]
	v_mfma_f32_16x16x32_bf16 v[176:179], v[76:79], v[8:11], 0
	v_cvt_pk_bf16_f32 v124, v200, v201
	v_cvt_pk_bf16_f32 v125, v202, v203
	v_cvt_pk_bf16_f32 v126, v204, v205
	v_cvt_pk_bf16_f32 v127, v206, v207
	v_mfma_f32_16x16x32_bf16 v[180:183], v[76:79], v[12:15], 0
	ds_write_b128 v241, v[124:127] offset:0
	v_pk_mov_b32 v[232:233], v[136:137], v[152:153] op_sel:[1,1]
	v_pk_mov_b32 v[234:235], v[140:141], v[156:157] op_sel:[1,1]
	v_pk_mov_b32 v[244:245], v[144:145], v[160:161] op_sel:[1,1]
	v_mfma_f32_16x16x32_bf16 v[184:187], v[76:79], v[16:19], 0
	v_pk_mov_b32 v[254:255], v[148:149], v[164:165] op_sel:[1,1]
	v_pk_fma_f32 v[232:233], v[32:33], v[200:201], v[232:233] op_sel_hi:[0,1,1]
	v_pk_fma_f32 v[234:235], v[34:35], v[202:203], v[234:235] op_sel_hi:[0,1,1]
	v_pk_fma_f32 v[244:245], v[36:37], v[204:205], v[244:245] op_sel_hi:[0,1,1]
	v_mfma_f32_16x16x32_bf16 v[188:191], v[76:79], v[20:23], 0
	v_pk_fma_f32 v[254:255], v[38:39], v[206:207], v[254:255] op_sel_hi:[0,1,1]
	v_pk_fma_f32 v[200:201], v[32:33], v[200:201], v[232:233] op_sel:[1,1,0] op_sel_hi:[1,0,1] neg_lo:[1,0,0]
	v_pk_fma_f32 v[202:203], v[34:35], v[202:203], v[234:235] op_sel:[1,1,0] op_sel_hi:[1,0,1] neg_lo:[1,0,0]
	v_pk_fma_f32 v[204:205], v[36:37], v[204:205], v[244:245] op_sel:[1,1,0] op_sel_hi:[1,0,1] neg_lo:[1,0,0]
	v_mfma_f32_16x16x32_bf16 v[192:195], v[76:79], v[24:27], 0
	v_pk_fma_f32 v[206:207], v[38:39], v[206:207], v[254:255] op_sel:[1,1,0] op_sel_hi:[1,0,1] neg_lo:[1,0,0]
	v_cvt_pk_bf16_f32 v124, v200, v201
	v_cvt_pk_bf16_f32 v125, v202, v203
	v_cvt_pk_bf16_f32 v126, v204, v205
	v_mfma_f32_16x16x32_bf16 v[196:199], v[76:79], v[28:31], 0
	v_cvt_pk_bf16_f32 v127, v206, v207
	ds_write_b128 v241, v[124:127] offset:256
	s_waitcnt lgkmcnt(2)
; __device__ __forceinline__ unsigned f2bf(float f) { unsigned u = __builtin_bit_cast(unsigned, f); return (u + 0x7fffu + ((u >> 16) & 1u)) >> 16; }
; __device__ __forceinline__ bf16x8 pack8(const float (&f)[8]) { u32x4 h; h.x = pk2(f[0], f[1]); h.y = pk2(f[2], f[3]); h.z = pk2(f[4], f[5]); h.w = pk2(f[6], f[7]); return __builtin_bit_cast(bf16x8, h); }
; template <bool FINAL> __device__ __forceinline__ void phase_s5_scan(const Fr& F) {
;     ...
;         for (int sub = 0; sub < 4; ++sub) {
;             const bf16x8 A1 = __builtin_bit_cast(bf16x8, uc[sub]);
; #pragma unroll
;             for (int nt = 0; nt < 8; ++nt) {
;                 f32x4 acc = {0.f, 0.f, 0.f, 0.f};
;                 acc = __builtin_amdgcn_mfma_f32_16x16x32_bf16(A1, B1[nt], acc, 0, 0, 0);
; #pragma unroll
;                 for (int reg = 0; reg < 4; ++reg) BUl[(4 * lq + reg) * 132 + 16 * nt + l15] = acc[reg];
;             }
;             asm volatile("s_waitcnt lgkmcnt(0)" ::: "memory");
; #pragma unroll 4
;             for (int jj = 0; jj < 16; ++jj) {
;                 const float br_ = BUl[jj * 132 + lane], bi_ = BUl[jj * 132 + 64 + lane];
;                 const float nr = ar * xr - ai * xi + br_, ni = ar * xi + ai * xr + bi_; xr = nr; xi = ni;
;                 if (FINAL) { BUl[jj * 132 + lane] = xr; BUl[jj * 132 + 64 + lane] = xi; }
;             }
;             if (FINAL) {
;                 asm volatile("s_waitcnt lgkmcnt(0)" ::: "memory");
;                 f32x4 acc = {0.f, 0.f, 0.f, 0.f};
; #pragma unroll
;                 for (int ks = 0; ks < 4; ++ks) {
;                     const f32x4 t0 = *(const f32x4*)(BUl + l15 * 132 + 32 * ks + 8 * lq), t1 = *(const f32x4*)(BUl + l15 * 132 + 32 * ks + 8 * lq + 4);
;                     const float xf[8] = {t0.x, t0.y, t0.z, t0.w, t1.x, t1.y, t1.z, t1.w};
;                     acc = __builtin_amdgcn_mfma_f32_16x16x32_bf16(pack8(xf), Chi[ks], acc, 0, 0, 0);
;                 }
; #pragma unroll
;                 for (int reg = 0; reg < 4; ++reg) { const int tok = tokof(s, chunk * 64 + sub * 16 + 4 * lq + reg);
;                     Yb[((size_t)b * TB + tok) * D + g * 16 + l15] = (bf16)f2bf(acc[reg]); }
;                 asm volatile("s_waitcnt lgkmcnt(0)" ::: "memory");
;             }
;         }
	v_pk_mov_b32 v[232:233], v[138:139], v[154:155] op_sel:[0,0]
	v_pk_mov_b32 v[234:235], v[142:143], v[158:159] op_sel:[0,0]
	v_pk_mov_b32 v[244:245], v[146:147], v[162:163] op_sel:[0,0]
	v_pk_mov_b32 v[254:255], v[150:151], v[166:167] op_sel:[0,0]
	v_mfma_f32_16x16x32_bf16 v[120:123], v[40:43], v[216:219], 0
	v_pk_fma_f32 v[232:233], v[32:33], v[200:201], v[232:233] op_sel_hi:[0,1,1]
	v_pk_fma_f32 v[234:235], v[34:35], v[202:203], v[234:235] op_sel_hi:[0,1,1]
	v_pk_fma_f32 v[244:245], v[36:37], v[204:205], v[244:245] op_sel_hi:[0,1,1]
	v_pk_fma_f32 v[254:255], v[38:39], v[206:207], v[254:255] op_sel_hi:[0,1,1]
	v_mfma_f32_16x16x32_bf16 v[120:123], v[44:47], v[220:223], v[120:123]
	v_pk_fma_f32 v[200:201], v[32:33], v[200:201], v[232:233] op_sel:[1,1,0] op_sel_hi:[1,0,1] neg_lo:[1,0,0]
	v_pk_fma_f32 v[202:203], v[34:35], v[202:203], v[234:235] op_sel:[1,1,0] op_sel_hi:[1,0,1] neg_lo:[1,0,0]
	v_pk_fma_f32 v[204:205], v[36:37], v[204:205], v[244:245] op_sel:[1,1,0] op_sel_hi:[1,0,1] neg_lo:[1,0,0]
	v_pk_fma_f32 v[206:207], v[38:39], v[206:207], v[254:255] op_sel:[1,1,0] op_sel_hi:[1,0,1] neg_lo:[1,0,0]
	v_mfma_f32_16x16x32_bf16 v[120:123], v[48:51], v[224:227], v[120:123]
	v_cvt_pk_bf16_f32 v124, v200, v201
	v_cvt_pk_bf16_f32 v125, v202, v203
	v_cvt_pk_bf16_f32 v126, v204, v205
	v_cvt_pk_bf16_f32 v127, v206, v207
	v_mfma_f32_16x16x32_bf16 v[120:123], v[52:55], v[228:231], v[120:123]
	ds_write_b128 v241, v[124:127] offset:512
	v_pk_mov_b32 v[232:233], v[138:139], v[154:155] op_sel:[1,1]
	v_pk_mov_b32 v[234:235], v[142:143], v[158:159] op_sel:[1,1]
	v_pk_mov_b32 v[244:245], v[146:147], v[162:163] op_sel:[1,1]
	v_pk_mov_b32 v[254:255], v[150:151], v[166:167] op_sel:[1,1]
	v_pk_fma_f32 v[232:233], v[32:33], v[200:201], v[232:233] op_sel_hi:[0,1,1]
	v_pk_fma_f32 v[234:235], v[34:35], v[202:203], v[234:235] op_sel_hi:[0,1,1]
	v_pk_fma_f32 v[244:245], v[36:37], v[204:205], v[244:245] op_sel_hi:[0,1,1]
	v_pk_fma_f32 v[254:255], v[38:39], v[206:207], v[254:255] op_sel_hi:[0,1,1]
	v_pk_fma_f32 v[200:201], v[32:33], v[200:201], v[232:233] op_sel:[1,1,0] op_sel_hi:[1,0,1] neg_lo:[1,0,0]
	v_pk_fma_f32 v[202:203], v[34:35], v[202:203], v[234:235] op_sel:[1,1,0] op_sel_hi:[1,0,1] neg_lo:[1,0,0]
	v_pk_fma_f32 v[204:205], v[36:37], v[204:205], v[244:245] op_sel:[1,1,0] op_sel_hi:[1,0,1] neg_lo:[1,0,0]
	v_pk_fma_f32 v[206:207], v[38:39], v[206:207], v[254:255] op_sel:[1,1,0] op_sel_hi:[1,0,1] neg_lo:[1,0,0]
	v_cvt_pk_bf16_f32 v124, v200, v201
	v_cvt_pk_bf16_f32 v125, v202, v203
	v_cvt_pk_bf16_f32 v126, v204, v205
	v_cvt_pk_bf16_f32 v127, v206, v207
	ds_write_b128 v241, v[124:127] offset:768
	global_load_dwordx4 v[72:75], v238, s[20:21]
	v_add_u32_e32 v238, v238, v243
	v_cvt_pk_bf16_f32 v124, v120, v121
	v_cvt_pk_bf16_f32 v125, v122, v123
	s_nop 0
	global_store_dwordx2 v239, v[124:125], s[24:25]
	v_add_u32_e32 v239, v239, v243
	s_waitcnt vmcnt(33)
	ds_read_b128 v[216:219], v242 offset:0
	ds_read_b128 v[220:223], v242 offset:64
	ds_read_b128 v[224:227], v242 offset:128
	ds_read_b128 v[228:231], v242 offset:192
	v_pk_mov_b32 v[232:233], v[168:169], v[184:185] op_sel:[0,0]
	v_pk_mov_b32 v[234:235], v[172:173], v[188:189] op_sel:[0,0]
	v_pk_mov_b32 v[244:245], v[176:177], v[192:193] op_sel:[0,0]
	v_pk_mov_b32 v[254:255], v[180:181], v[196:197] op_sel:[0,0]
	v_mfma_f32_16x16x32_bf16 v[136:139], v[80:83], v[0:3], 0
	v_pk_fma_f32 v[232:233], v[32:33], v[200:201], v[232:233] op_sel_hi:[0,1,1]
	v_pk_fma_f32 v[234:235], v[34:35], v[202:203], v[234:235] op_sel_hi:[0,1,1]
	v_pk_fma_f32 v[244:245], v[36:37], v[204:205], v[244:245] op_sel_hi:[0,1,1]
	v_pk_fma_f32 v[254:255], v[38:39], v[206:207], v[254:255] op_sel_hi:[0,1,1]
	v_mfma_f32_16x16x32_bf16 v[140:143], v[80:83], v[4:7], 0
	v_pk_fma_f32 v[200:201], v[32:33], v[200:201], v[232:233] op_sel:[1,1,0] op_sel_hi:[1,0,1] neg_lo:[1,0,0]
	v_pk_fma_f32 v[202:203], v[34:35], v[202:203], v[234:235] op_sel:[1,1,0] op_sel_hi:[1,0,1] neg_lo:[1,0,0]
	v_pk_fma_f32 v[204:205], v[36:37], v[204:205], v[244:245] op_sel:[1,1,0] op_sel_hi:[1,0,1] neg_lo:[1,0,0]
	v_pk_fma_f32 v[206:207], v[38:39], v[206:207], v[254:255] op_sel:[1,1,0] op_sel_hi:[1,0,1] neg_lo:[1,0,0]
	v_mfma_f32_16x16x32_bf16 v[144:147], v[80:83], v[8:11], 0
	v_cvt_pk_bf16_f32 v124, v200, v201
	v_cvt_pk_bf16_f32 v125, v202, v203
	v_cvt_pk_bf16_f32 v126, v204, v205
	v_cvt_pk_bf16_f32 v127, v206, v207
	v_mfma_f32_16x16x32_bf16 v[148:151], v[80:83], v[12:15], 0
	ds_write_b128 v241, v[124:127] offset:4096
	v_pk_mov_b32 v[232:233], v[168:169], v[184:185] op_sel:[1,1]
	v_pk_mov_b32 v[234:235], v[172:173], v[188:189] op_sel:[1,1]
	v_pk_mov_b32 v[244:245], v[176:177], v[192:193] op_sel:[1,1]
	v_mfma_f32_16x16x32_bf16 v[152:155], v[80:83], v[16:19], 0
	v_pk_mov_b32 v[254:255], v[180:181], v[196:197] op_sel:[1,1]
	v_pk_fma_f32 v[232:233], v[32:33], v[200:201], v[232:233] op_sel_hi:[0,1,1]
	v_pk_fma_f32 v[234:235], v[34:35], v[202:203], v[234:235] op_sel_hi:[0,1,1]
	v_pk_fma_f32 v[244:245], v[36:37], v[204:205], v[244:245] op_sel_hi:[0,1,1]
	v_mfma_f32_16x16x32_bf16 v[156:159], v[80:83], v[20:23], 0
	v_pk_fma_f32 v[254:255], v[38:39], v[206:207], v[254:255] op_sel_hi:[0,1,1]
	v_pk_fma_f32 v[200:201], v[32:33], v[200:201], v[232:233] op_sel:[1,1,0] op_sel_hi:[1,0,1] neg_lo:[1,0,0]
	v_pk_fma_f32 v[202:203], v[34:35], v[202:203], v[234:235] op_sel:[1,1,0] op_sel_hi:[1,0,1] neg_lo:[1,0,0]
	v_pk_fma_f32 v[204:205], v[36:37], v[204:205], v[244:245] op_sel:[1,1,0] op_sel_hi:[1,0,1] neg_lo:[1,0,0]
	v_mfma_f32_16x16x32_bf16 v[160:163], v[80:83], v[24:27], 0
	v_pk_fma_f32 v[206:207], v[38:39], v[206:207], v[254:255] op_sel:[1,1,0] op_sel_hi:[1,0,1] neg_lo:[1,0,0]
	v_cvt_pk_bf16_f32 v124, v200, v201
	v_cvt_pk_bf16_f32 v125, v202, v203
	v_cvt_pk_bf16_f32 v126, v204, v205
	v_mfma_f32_16x16x32_bf16 v[164:167], v[80:83], v[28:31], 0
	v_cvt_pk_bf16_f32 v127, v206, v207
	ds_write_b128 v241, v[124:127] offset:4352
	s_waitcnt lgkmcnt(2)
; __device__ __forceinline__ unsigned f2bf(float f) { unsigned u = __builtin_bit_cast(unsigned, f); return (u + 0x7fffu + ((u >> 16) & 1u)) >> 16; }
; __device__ __forceinline__ bf16x8 pack8(const float (&f)[8]) { u32x4 h; h.x = pk2(f[0], f[1]); h.y = pk2(f[2], f[3]); h.z = pk2(f[4], f[5]); h.w = pk2(f[6], f[7]); return __builtin_bit_cast(bf16x8, h); }
; template <bool FINAL> __device__ __forceinline__ void phase_s5_scan(const Fr& F) {
;     ...
;         for (int sub = 0; sub < 4; ++sub) {
;             const bf16x8 A1 = __builtin_bit_cast(bf16x8, uc[sub]);
; #pragma unroll
;             for (int nt = 0; nt < 8; ++nt) {
;                 f32x4 acc = {0.f, 0.f, 0.f, 0.f};
;                 acc = __builtin_amdgcn_mfma_f32_16x16x32_bf16(A1, B1[nt], acc, 0, 0, 0);
; #pragma unroll
;                 for (int reg = 0; reg < 4; ++reg) BUl[(4 * lq + reg) * 132 + 16 * nt + l15] = acc[reg];
;             }
;             asm volatile("s_waitcnt lgkmcnt(0)" ::: "memory");
; #pragma unroll 4
;             for (int jj = 0; jj < 16; ++jj) {
;                 const float br_ = BUl[jj * 132 + lane], bi_ = BUl[jj * 132 + 64 + lane];
;                 const float nr = ar * xr - ai * xi + br_, ni = ar * xi + ai * xr + bi_; xr = nr; xi = ni;
;                 if (FINAL) { BUl[jj * 132 + lane] = xr; BUl[jj * 132 + 64 + lane] = xi; }
;             }
;             if (FINAL) {
;                 asm volatile("s_waitcnt lgkmcnt(0)" ::: "memory");
;                 f32x4 acc = {0.f, 0.f, 0.f, 0.f};
; #pragma unroll
;                 for (int ks = 0; ks < 4; ++ks) {
;                     const f32x4 t0 = *(const f32x4*)(BUl + l15 * 132 + 32 * ks + 8 * lq), t1 = *(const f32x4*)(BUl + l15 * 132 + 32 * ks + 8 * lq + 4);
;                     const float xf[8] = {t0.x, t0.y, t0.z, t0.w, t1.x, t1.y, t1.z, t1.w};
;                     acc = __builtin_amdgcn_mfma_f32_16x16x32_bf16(pack8(xf), Chi[ks], acc, 0, 0, 0);
;                 }
; #pragma unroll
;                 for (int reg = 0; reg < 4; ++reg) { const int tok = tokof(s, chunk * 64 + sub * 16 + 4 * lq + reg);
;                     Yb[((size_t)b * TB + tok) * D + g * 16 + l15] = (bf16)f2bf(acc[reg]); }
;                 asm volatile("s_waitcnt lgkmcnt(0)" ::: "memory");
;             }
;         }
	v_pk_mov_b32 v[232:233], v[170:171], v[186:187] op_sel:[0,0]
	v_pk_mov_b32 v[234:235], v[174:175], v[190:191] op_sel:[0,0]
	v_pk_mov_b32 v[244:245], v[178:179], v[194:195] op_sel:[0,0]
	v_pk_mov_b32 v[254:255], v[182:183], v[198:199] op_sel:[0,0]
	v_mfma_f32_16x16x32_bf16 v[120:123], v[40:43], v[216:219], 0
	v_pk_fma_f32 v[232:233], v[32:33], v[200:201], v[232:233] op_sel_hi:[0,1,1]
	v_pk_fma_f32 v[234:235], v[34:35], v[202:203], v[234:235] op_sel_hi:[0,1,1]
	v_pk_fma_f32 v[244:245], v[36:37], v[204:205], v[244:245] op_sel_hi:[0,1,1]
	v_pk_fma_f32 v[254:255], v[38:39], v[206:207], v[254:255] op_sel_hi:[0,1,1]
	v_mfma_f32_16x16x32_bf16 v[120:123], v[44:47], v[220:223], v[120:123]
	v_pk_fma_f32 v[200:201], v[32:33], v[200:201], v[232:233] op_sel:[1,1,0] op_sel_hi:[1,0,1] neg_lo:[1,0,0]
	v_pk_fma_f32 v[202:203], v[34:35], v[202:203], v[234:235] op_sel:[1,1,0] op_sel_hi:[1,0,1] neg_lo:[1,0,0]
	v_pk_fma_f32 v[204:205], v[36:37], v[204:205], v[244:245] op_sel:[1,1,0] op_sel_hi:[1,0,1] neg_lo:[1,0,0]
	v_pk_fma_f32 v[206:207], v[38:39], v[206:207], v[254:255] op_sel:[1,1,0] op_sel_hi:[1,0,1] neg_lo:[1,0,0]
	v_mfma_f32_16x16x32_bf16 v[120:123], v[48:51], v[224:227], v[120:123]
	v_cvt_pk_bf16_f32 v124, v200, v201
	v_cvt_pk_bf16_f32 v125, v202, v203
	v_cvt_pk_bf16_f32 v126, v204, v205
	v_cvt_pk_bf16_f32 v127, v206, v207
	v_mfma_f32_16x16x32_bf16 v[120:123], v[52:55], v[228:231], v[120:123]
	ds_write_b128 v241, v[124:127] offset:4608
	v_pk_mov_b32 v[232:233], v[170:171], v[186:187] op_sel:[1,1]
	v_pk_mov_b32 v[234:235], v[174:175], v[190:191] op_sel:[1,1]
	v_pk_mov_b32 v[244:245], v[178:179], v[194:195] op_sel:[1,1]
	v_pk_mov_b32 v[254:255], v[182:183], v[198:199] op_sel:[1,1]
	v_pk_fma_f32 v[232:233], v[32:33], v[200:201], v[232:233] op_sel_hi:[0,1,1]
	v_pk_fma_f32 v[234:235], v[34:35], v[202:203], v[234:235] op_sel_hi:[0,1,1]
	v_pk_fma_f32 v[244:245], v[36:37], v[204:205], v[244:245] op_sel_hi:[0,1,1]
	v_pk_fma_f32 v[254:255], v[38:39], v[206:207], v[254:255] op_sel_hi:[0,1,1]
	v_pk_fma_f32 v[200:201], v[32:33], v[200:201], v[232:233] op_sel:[1,1,0] op_sel_hi:[1,0,1] neg_lo:[1,0,0]
	v_pk_fma_f32 v[202:203], v[34:35], v[202:203], v[234:235] op_sel:[1,1,0] op_sel_hi:[1,0,1] neg_lo:[1,0,0]
	v_pk_fma_f32 v[204:205], v[36:37], v[204:205], v[244:245] op_sel:[1,1,0] op_sel_hi:[1,0,1] neg_lo:[1,0,0]
	v_pk_fma_f32 v[206:207], v[38:39], v[206:207], v[254:255] op_sel:[1,1,0] op_sel_hi:[1,0,1] neg_lo:[1,0,0]
	v_cvt_pk_bf16_f32 v124, v200, v201
	v_cvt_pk_bf16_f32 v125, v202, v203
	v_cvt_pk_bf16_f32 v126, v204, v205
	v_cvt_pk_bf16_f32 v127, v206, v207
	ds_write_b128 v241, v[124:127] offset:4864
	global_load_dwordx4 v[76:79], v238, s[20:21]
	v_add_u32_e32 v238, v238, v243
	v_cvt_pk_bf16_f32 v124, v120, v121
	v_cvt_pk_bf16_f32 v125, v122, v123
	s_nop 0
	global_store_dwordx2 v239, v[124:125], s[24:25]
	v_add_u32_e32 v239, v239, v243
	s_waitcnt vmcnt(33)
	ds_read_b128 v[216:219], v242 offset:4096
	ds_read_b128 v[220:223], v242 offset:4160
	ds_read_b128 v[224:227], v242 offset:4224
	ds_read_b128 v[228:231], v242 offset:4288
	v_pk_mov_b32 v[232:233], v[136:137], v[152:153] op_sel:[0,0]
	v_pk_mov_b32 v[234:235], v[140:141], v[156:157] op_sel:[0,0]
	v_pk_mov_b32 v[244:245], v[144:145], v[160:161] op_sel:[0,0]
	v_pk_mov_b32 v[254:255], v[148:149], v[164:165] op_sel:[0,0]
	v_mfma_f32_16x16x32_bf16 v[168:171], v[84:87], v[0:3], 0
	v_pk_fma_f32 v[232:233], v[32:33], v[200:201], v[232:233] op_sel_hi:[0,1,1]
	v_pk_fma_f32 v[234:235], v[34:35], v[202:203], v[234:235] op_sel_hi:[0,1,1]
	v_pk_fma_f32 v[244:245], v[36:37], v[204:205], v[244:245] op_sel_hi:[0,1,1]
	v_pk_fma_f32 v[254:255], v[38:39], v[206:207], v[254:255] op_sel_hi:[0,1,1]
	v_mfma_f32_16x16x32_bf16 v[172:175], v[84:87], v[4:7], 0
	v_pk_fma_f32 v[200:201], v[32:33], v[200:201], v[232:233] op_sel:[1,1,0] op_sel_hi:[1,0,1] neg_lo:[1,0,0]
	v_pk_fma_f32 v[202:203], v[34:35], v[202:203], v[234:235] op_sel:[1,1,0] op_sel_hi:[1,0,1] neg_lo:[1,0,0]
	v_pk_fma_f32 v[204:205], v[36:37], v[204:205], v[244:245] op_sel:[1,1,0] op_sel_hi:[1,0,1] neg_lo:[1,0,0]
	v_pk_fma_f32 v[206:207], v[38:39], v[206:207], v[254:255] op_sel:[1,1,0] op_sel_hi:[1,0,1] neg_lo:[1,0,0]
	v_mfma_f32_16x16x32_bf16 v[176:179], v[84:87], v[8:11], 0
	v_cvt_pk_bf16_f32 v124, v200, v201
	v_cvt_pk_bf16_f32 v125, v202, v203
	v_cvt_pk_bf16_f32 v126, v204, v205
	v_cvt_pk_bf16_f32 v127, v206, v207
	v_mfma_f32_16x16x32_bf16 v[180:183], v[84:87], v[12:15], 0
	ds_write_b128 v241, v[124:127] offset:0
	v_pk_mov_b32 v[232:233], v[136:137], v[152:153] op_sel:[1,1]
	v_pk_mov_b32 v[234:235], v[140:141], v[156:157] op_sel:[1,1]
	v_pk_mov_b32 v[244:245], v[144:145], v[160:161] op_sel:[1,1]
	v_mfma_f32_16x16x32_bf16 v[184:187], v[84:87], v[16:19], 0
	v_pk_mov_b32 v[254:255], v[148:149], v[164:165] op_sel:[1,1]
	v_pk_fma_f32 v[232:233], v[32:33], v[200:201], v[232:233] op_sel_hi:[0,1,1]
	v_pk_fma_f32 v[234:235], v[34:35], v[202:203], v[234:235] op_sel_hi:[0,1,1]
	v_pk_fma_f32 v[244:245], v[36:37], v[204:205], v[244:245] op_sel_hi:[0,1,1]
	v_mfma_f32_16x16x32_bf16 v[188:191], v[84:87], v[20:23], 0
	v_pk_fma_f32 v[254:255], v[38:39], v[206:207], v[254:255] op_sel_hi:[0,1,1]
	v_pk_fma_f32 v[200:201], v[32:33], v[200:201], v[232:233] op_sel:[1,1,0] op_sel_hi:[1,0,1] neg_lo:[1,0,0]
	v_pk_fma_f32 v[202:203], v[34:35], v[202:203], v[234:235] op_sel:[1,1,0] op_sel_hi:[1,0,1] neg_lo:[1,0,0]
	v_pk_fma_f32 v[204:205], v[36:37], v[204:205], v[244:245] op_sel:[1,1,0] op_sel_hi:[1,0,1] neg_lo:[1,0,0]
	v_mfma_f32_16x16x32_bf16 v[192:195], v[84:87], v[24:27], 0
	v_pk_fma_f32 v[206:207], v[38:39], v[206:207], v[254:255] op_sel:[1,1,0] op_sel_hi:[1,0,1] neg_lo:[1,0,0]
	v_cvt_pk_bf16_f32 v124, v200, v201
	v_cvt_pk_bf16_f32 v125, v202, v203
	v_cvt_pk_bf16_f32 v126, v204, v205
	v_mfma_f32_16x16x32_bf16 v[196:199], v[84:87], v[28:31], 0
	v_cvt_pk_bf16_f32 v127, v206, v207
	ds_write_b128 v241, v[124:127] offset:256
	s_waitcnt lgkmcnt(2)
; __device__ __forceinline__ unsigned f2bf(float f) { unsigned u = __builtin_bit_cast(unsigned, f); return (u + 0x7fffu + ((u >> 16) & 1u)) >> 16; }
; __device__ __forceinline__ bf16x8 pack8(const float (&f)[8]) { u32x4 h; h.x = pk2(f[0], f[1]); h.y = pk2(f[2], f[3]); h.z = pk2(f[4], f[5]); h.w = pk2(f[6], f[7]); return __builtin_bit_cast(bf16x8, h); }
; template <bool FINAL> __device__ __forceinline__ void phase_s5_scan(const Fr& F) {
;     ...
;         for (int sub = 0; sub < 4; ++sub) {
;             const bf16x8 A1 = __builtin_bit_cast(bf16x8, uc[sub]);
; #pragma unroll
;             for (int nt = 0; nt < 8; ++nt) {
;                 f32x4 acc = {0.f, 0.f, 0.f, 0.f};
;                 acc = __builtin_amdgcn_mfma_f32_16x16x32_bf16(A1, B1[nt], acc, 0, 0, 0);
; #pragma unroll
;                 for (int reg = 0; reg < 4; ++reg) BUl[(4 * lq + reg) * 132 + 16 * nt + l15] = acc[reg];
;             }
;             asm volatile("s_waitcnt lgkmcnt(0)" ::: "memory");
; #pragma unroll 4
;             for (int jj = 0; jj < 16; ++jj) {
;                 const float br_ = BUl[jj * 132 + lane], bi_ = BUl[jj * 132 + 64 + lane];
;                 const float nr = ar * xr - ai * xi + br_, ni = ar * xi + ai * xr + bi_; xr = nr; xi = ni;
;                 if (FINAL) { BUl[jj * 132 + lane] = xr; BUl[jj * 132 + 64 + lane] = xi; }
;             }
;             if (FINAL) {
;                 asm volatile("s_waitcnt lgkmcnt(0)" ::: "memory");
;                 f32x4 acc = {0.f, 0.f, 0.f, 0.f};
; #pragma unroll
;                 for (int ks = 0; ks < 4; ++ks) {
;                     const f32x4 t0 = *(const f32x4*)(BUl + l15 * 132 + 32 * ks + 8 * lq), t1 = *(const f32x4*)(BUl + l15 * 132 + 32 * ks + 8 * lq + 4);
;                     const float xf[8] = {t0.x, t0.y, t0.z, t0.w, t1.x, t1.y, t1.z, t1.w};
;                     acc = __builtin_amdgcn_mfma_f32_16x16x32_bf16(pack8(xf), Chi[ks], acc, 0, 0, 0);
;                 }
; #pragma unroll
;                 for (int reg = 0; reg < 4; ++reg) { const int tok = tokof(s, chunk * 64 + sub * 16 + 4 * lq + reg);
;                     Yb[((size_t)b * TB + tok) * D + g * 16 + l15] = (bf16)f2bf(acc[reg]); }
;                 asm volatile("s_waitcnt lgkmcnt(0)" ::: "memory");
;             }
;         }
	v_pk_mov_b32 v[232:233], v[138:139], v[154:155] op_sel:[0,0]
	v_pk_mov_b32 v[234:235], v[142:143], v[158:159] op_sel:[0,0]
	v_pk_mov_b32 v[244:245], v[146:147], v[162:163] op_sel:[0,0]
	v_pk_mov_b32 v[254:255], v[150:151], v[166:167] op_sel:[0,0]
	v_mfma_f32_16x16x32_bf16 v[120:123], v[40:43], v[216:219], 0
	v_pk_fma_f32 v[232:233], v[32:33], v[200:201], v[232:233] op_sel_hi:[0,1,1]
	v_pk_fma_f32 v[234:235], v[34:35], v[202:203], v[234:235] op_sel_hi:[0,1,1]
	v_pk_fma_f32 v[244:245], v[36:37], v[204:205], v[244:245] op_sel_hi:[0,1,1]
	v_pk_fma_f32 v[254:255], v[38:39], v[206:207], v[254:255] op_sel_hi:[0,1,1]
	v_mfma_f32_16x16x32_bf16 v[120:123], v[44:47], v[220:223], v[120:123]
	v_pk_fma_f32 v[200:201], v[32:33], v[200:201], v[232:233] op_sel:[1,1,0] op_sel_hi:[1,0,1] neg_lo:[1,0,0]
	v_pk_fma_f32 v[202:203], v[34:35], v[202:203], v[234:235] op_sel:[1,1,0] op_sel_hi:[1,0,1] neg_lo:[1,0,0]
	v_pk_fma_f32 v[204:205], v[36:37], v[204:205], v[244:245] op_sel:[1,1,0] op_sel_hi:[1,0,1] neg_lo:[1,0,0]
	v_pk_fma_f32 v[206:207], v[38:39], v[206:207], v[254:255] op_sel:[1,1,0] op_sel_hi:[1,0,1] neg_lo:[1,0,0]
	v_mfma_f32_16x16x32_bf16 v[120:123], v[48:51], v[224:227], v[120:123]
	v_cvt_pk_bf16_f32 v124, v200, v201
	v_cvt_pk_bf16_f32 v125, v202, v203
	v_cvt_pk_bf16_f32 v126, v204, v205
	v_cvt_pk_bf16_f32 v127, v206, v207
	v_mfma_f32_16x16x32_bf16 v[120:123], v[52:55], v[228:231], v[120:123]
	ds_write_b128 v241, v[124:127] offset:512
	v_pk_mov_b32 v[232:233], v[138:139], v[154:155] op_sel:[1,1]
	v_pk_mov_b32 v[234:235], v[142:143], v[158:159] op_sel:[1,1]
	v_pk_mov_b32 v[244:245], v[146:147], v[162:163] op_sel:[1,1]
	v_pk_mov_b32 v[254:255], v[150:151], v[166:167] op_sel:[1,1]
	v_pk_fma_f32 v[232:233], v[32:33], v[200:201], v[232:233] op_sel_hi:[0,1,1]
	v_pk_fma_f32 v[234:235], v[34:35], v[202:203], v[234:235] op_sel_hi:[0,1,1]
	v_pk_fma_f32 v[244:245], v[36:37], v[204:205], v[244:245] op_sel_hi:[0,1,1]
	v_pk_fma_f32 v[254:255], v[38:39], v[206:207], v[254:255] op_sel_hi:[0,1,1]
	v_pk_fma_f32 v[200:201], v[32:33], v[200:201], v[232:233] op_sel:[1,1,0] op_sel_hi:[1,0,1] neg_lo:[1,0,0]
	v_pk_fma_f32 v[202:203], v[34:35], v[202:203], v[234:235] op_sel:[1,1,0] op_sel_hi:[1,0,1] neg_lo:[1,0,0]
	v_pk_fma_f32 v[204:205], v[36:37], v[204:205], v[244:245] op_sel:[1,1,0] op_sel_hi:[1,0,1] neg_lo:[1,0,0]
	v_pk_fma_f32 v[206:207], v[38:39], v[206:207], v[254:255] op_sel:[1,1,0] op_sel_hi:[1,0,1] neg_lo:[1,0,0]
	v_cvt_pk_bf16_f32 v124, v200, v201
	v_cvt_pk_bf16_f32 v125, v202, v203
	v_cvt_pk_bf16_f32 v126, v204, v205
	v_cvt_pk_bf16_f32 v127, v206, v207
	ds_write_b128 v241, v[124:127] offset:768
	global_load_dwordx4 v[80:83], v238, s[20:21]
	v_add_u32_e32 v238, v238, v243
	v_cvt_pk_bf16_f32 v124, v120, v121
	v_cvt_pk_bf16_f32 v125, v122, v123
	s_nop 0
	global_store_dwordx2 v239, v[124:125], s[24:25]
	v_add_u32_e32 v239, v239, v243
	s_waitcnt vmcnt(33)
	ds_read_b128 v[216:219], v242 offset:0
	ds_read_b128 v[220:223], v242 offset:64
	ds_read_b128 v[224:227], v242 offset:128
	ds_read_b128 v[228:231], v242 offset:192
	v_pk_mov_b32 v[232:233], v[168:169], v[184:185] op_sel:[0,0]
	v_pk_mov_b32 v[234:235], v[172:173], v[188:189] op_sel:[0,0]
	v_pk_mov_b32 v[244:245], v[176:177], v[192:193] op_sel:[0,0]
	v_pk_mov_b32 v[254:255], v[180:181], v[196:197] op_sel:[0,0]
	v_mfma_f32_16x16x32_bf16 v[136:139], v[88:91], v[0:3], 0
	v_pk_fma_f32 v[232:233], v[32:33], v[200:201], v[232:233] op_sel_hi:[0,1,1]
	v_pk_fma_f32 v[234:235], v[34:35], v[202:203], v[234:235] op_sel_hi:[0,1,1]
	v_pk_fma_f32 v[244:245], v[36:37], v[204:205], v[244:245] op_sel_hi:[0,1,1]
	v_pk_fma_f32 v[254:255], v[38:39], v[206:207], v[254:255] op_sel_hi:[0,1,1]
	v_mfma_f32_16x16x32_bf16 v[140:143], v[88:91], v[4:7], 0
	v_pk_fma_f32 v[200:201], v[32:33], v[200:201], v[232:233] op_sel:[1,1,0] op_sel_hi:[1,0,1] neg_lo:[1,0,0]
	v_pk_fma_f32 v[202:203], v[34:35], v[202:203], v[234:235] op_sel:[1,1,0] op_sel_hi:[1,0,1] neg_lo:[1,0,0]
	v_pk_fma_f32 v[204:205], v[36:37], v[204:205], v[244:245] op_sel:[1,1,0] op_sel_hi:[1,0,1] neg_lo:[1,0,0]
	v_pk_fma_f32 v[206:207], v[38:39], v[206:207], v[254:255] op_sel:[1,1,0] op_sel_hi:[1,0,1] neg_lo:[1,0,0]
	v_mfma_f32_16x16x32_bf16 v[144:147], v[88:91], v[8:11], 0
	v_cvt_pk_bf16_f32 v124, v200, v201
	v_cvt_pk_bf16_f32 v125, v202, v203
	v_cvt_pk_bf16_f32 v126, v204, v205
	v_cvt_pk_bf16_f32 v127, v206, v207
	v_mfma_f32_16x16x32_bf16 v[148:151], v[88:91], v[12:15], 0
	ds_write_b128 v241, v[124:127] offset:4096
	v_pk_mov_b32 v[232:233], v[168:169], v[184:185] op_sel:[1,1]
	v_pk_mov_b32 v[234:235], v[172:173], v[188:189] op_sel:[1,1]
	v_pk_mov_b32 v[244:245], v[176:177], v[192:193] op_sel:[1,1]
	v_mfma_f32_16x16x32_bf16 v[152:155], v[88:91], v[16:19], 0
	v_pk_mov_b32 v[254:255], v[180:181], v[196:197] op_sel:[1,1]
	v_pk_fma_f32 v[232:233], v[32:33], v[200:201], v[232:233] op_sel_hi:[0,1,1]
	v_pk_fma_f32 v[234:235], v[34:35], v[202:203], v[234:235] op_sel_hi:[0,1,1]
	v_pk_fma_f32 v[244:245], v[36:37], v[204:205], v[244:245] op_sel_hi:[0,1,1]
	v_mfma_f32_16x16x32_bf16 v[156:159], v[88:91], v[20:23], 0
	v_pk_fma_f32 v[254:255], v[38:39], v[206:207], v[254:255] op_sel_hi:[0,1,1]
	v_pk_fma_f32 v[200:201], v[32:33], v[200:201], v[232:233] op_sel:[1,1,0] op_sel_hi:[1,0,1] neg_lo:[1,0,0]
	v_pk_fma_f32 v[202:203], v[34:35], v[202:203], v[234:235] op_sel:[1,1,0] op_sel_hi:[1,0,1] neg_lo:[1,0,0]
	v_pk_fma_f32 v[204:205], v[36:37], v[204:205], v[244:245] op_sel:[1,1,0] op_sel_hi:[1,0,1] neg_lo:[1,0,0]
	v_mfma_f32_16x16x32_bf16 v[160:163], v[88:91], v[24:27], 0
	v_pk_fma_f32 v[206:207], v[38:39], v[206:207], v[254:255] op_sel:[1,1,0] op_sel_hi:[1,0,1] neg_lo:[1,0,0]
	v_cvt_pk_bf16_f32 v124, v200, v201
	v_cvt_pk_bf16_f32 v125, v202, v203
	v_cvt_pk_bf16_f32 v126, v204, v205
	v_mfma_f32_16x16x32_bf16 v[164:167], v[88:91], v[28:31], 0
	v_cvt_pk_bf16_f32 v127, v206, v207
	ds_write_b128 v241, v[124:127] offset:4352
	s_waitcnt lgkmcnt(2)
; __device__ __forceinline__ unsigned f2bf(float f) { unsigned u = __builtin_bit_cast(unsigned, f); return (u + 0x7fffu + ((u >> 16) & 1u)) >> 16; }
; __device__ __forceinline__ bf16x8 pack8(const float (&f)[8]) { u32x4 h; h.x = pk2(f[0], f[1]); h.y = pk2(f[2], f[3]); h.z = pk2(f[4], f[5]); h.w = pk2(f[6], f[7]); return __builtin_bit_cast(bf16x8, h); }
; template <bool FINAL> __device__ __forceinline__ void phase_s5_scan(const Fr& F) {
;     ...
;         for (int sub = 0; sub < 4; ++sub) {
;             const bf16x8 A1 = __builtin_bit_cast(bf16x8, uc[sub]);
; #pragma unroll
;             for (int nt = 0; nt < 8; ++nt) {
;                 f32x4 acc = {0.f, 0.f, 0.f, 0.f};
;                 acc = __builtin_amdgcn_mfma_f32_16x16x32_bf16(A1, B1[nt], acc, 0, 0, 0);
; #pragma unroll
;                 for (int reg = 0; reg < 4; ++reg) BUl[(4 * lq + reg) * 132 + 16 * nt + l15] = acc[reg];
;             }
;             asm volatile("s_waitcnt lgkmcnt(0)" ::: "memory");
; #pragma unroll 4
;             for (int jj = 0; jj < 16; ++jj) {
;                 const float br_ = BUl[jj * 132 + lane], bi_ = BUl[jj * 132 + 64 + lane];
;                 const float nr = ar * xr - ai * xi + br_, ni = ar * xi + ai * xr + bi_; xr = nr; xi = ni;
;                 if (FINAL) { BUl[jj * 132 + lane] = xr; BUl[jj * 132 + 64 + lane] = xi; }
;             }
;             if (FINAL) {
;                 asm volatile("s_waitcnt lgkmcnt(0)" ::: "memory");
;                 f32x4 acc = {0.f, 0.f, 0.f, 0.f};
; #pragma unroll
;                 for (int ks = 0; ks < 4; ++ks) {
;                     const f32x4 t0 = *(const f32x4*)(BUl + l15 * 132 + 32 * ks + 8 * lq), t1 = *(const f32x4*)(BUl + l15 * 132 + 32 * ks + 8 * lq + 4);
;                     const float xf[8] = {t0.x, t0.y, t0.z, t0.w, t1.x, t1.y, t1.z, t1.w};
;                     acc = __builtin_amdgcn_mfma_f32_16x16x32_bf16(pack8(xf), Chi[ks], acc, 0, 0, 0);
;                 }
; #pragma unroll
;                 for (int reg = 0; reg < 4; ++reg) { const int tok = tokof(s, chunk * 64 + sub * 16 + 4 * lq + reg);
;                     Yb[((size_t)b * TB + tok) * D + g * 16 + l15] = (bf16)f2bf(acc[reg]); }
;                 asm volatile("s_waitcnt lgkmcnt(0)" ::: "memory");
;             }
;         }
	v_pk_mov_b32 v[232:233], v[170:171], v[186:187] op_sel:[0,0]
	v_pk_mov_b32 v[234:235], v[174:175], v[190:191] op_sel:[0,0]
	v_pk_mov_b32 v[244:245], v[178:179], v[194:195] op_sel:[0,0]
	v_pk_mov_b32 v[254:255], v[182:183], v[198:199] op_sel:[0,0]
	v_mfma_f32_16x16x32_bf16 v[120:123], v[40:43], v[216:219], 0
	v_pk_fma_f32 v[232:233], v[32:33], v[200:201], v[232:233] op_sel_hi:[0,1,1]
	v_pk_fma_f32 v[234:235], v[34:35], v[202:203], v[234:235] op_sel_hi:[0,1,1]
	v_pk_fma_f32 v[244:245], v[36:37], v[204:205], v[244:245] op_sel_hi:[0,1,1]
	v_pk_fma_f32 v[254:255], v[38:39], v[206:207], v[254:255] op_sel_hi:[0,1,1]
	v_mfma_f32_16x16x32_bf16 v[120:123], v[44:47], v[220:223], v[120:123]
	v_pk_fma_f32 v[200:201], v[32:33], v[200:201], v[232:233] op_sel:[1,1,0] op_sel_hi:[1,0,1] neg_lo:[1,0,0]
	v_pk_fma_f32 v[202:203], v[34:35], v[202:203], v[234:235] op_sel:[1,1,0] op_sel_hi:[1,0,1] neg_lo:[1,0,0]
	v_pk_fma_f32 v[204:205], v[36:37], v[204:205], v[244:245] op_sel:[1,1,0] op_sel_hi:[1,0,1] neg_lo:[1,0,0]
	v_pk_fma_f32 v[206:207], v[38:39], v[206:207], v[254:255] op_sel:[1,1,0] op_sel_hi:[1,0,1] neg_lo:[1,0,0]
	v_mfma_f32_16x16x32_bf16 v[120:123], v[48:51], v[224:227], v[120:123]
	v_cvt_pk_bf16_f32 v124, v200, v201
	v_cvt_pk_bf16_f32 v125, v202, v203
	v_cvt_pk_bf16_f32 v126, v204, v205
	v_cvt_pk_bf16_f32 v127, v206, v207
	v_mfma_f32_16x16x32_bf16 v[120:123], v[52:55], v[228:231], v[120:123]
	ds_write_b128 v241, v[124:127] offset:4608
	v_pk_mov_b32 v[232:233], v[170:171], v[186:187] op_sel:[1,1]
	v_pk_mov_b32 v[234:235], v[174:175], v[190:191] op_sel:[1,1]
	v_pk_mov_b32 v[244:245], v[178:179], v[194:195] op_sel:[1,1]
	v_pk_mov_b32 v[254:255], v[182:183], v[198:199] op_sel:[1,1]
	v_pk_fma_f32 v[232:233], v[32:33], v[200:201], v[232:233] op_sel_hi:[0,1,1]
	v_pk_fma_f32 v[234:235], v[34:35], v[202:203], v[234:235] op_sel_hi:[0,1,1]
	v_pk_fma_f32 v[244:245], v[36:37], v[204:205], v[244:245] op_sel_hi:[0,1,1]
	v_pk_fma_f32 v[254:255], v[38:39], v[206:207], v[254:255] op_sel_hi:[0,1,1]
	v_pk_fma_f32 v[200:201], v[32:33], v[200:201], v[232:233] op_sel:[1,1,0] op_sel_hi:[1,0,1] neg_lo:[1,0,0]
	v_pk_fma_f32 v[202:203], v[34:35], v[202:203], v[234:235] op_sel:[1,1,0] op_sel_hi:[1,0,1] neg_lo:[1,0,0]
	v_pk_fma_f32 v[204:205], v[36:37], v[204:205], v[244:245] op_sel:[1,1,0] op_sel_hi:[1,0,1] neg_lo:[1,0,0]
	v_pk_fma_f32 v[206:207], v[38:39], v[206:207], v[254:255] op_sel:[1,1,0] op_sel_hi:[1,0,1] neg_lo:[1,0,0]
	v_cvt_pk_bf16_f32 v124, v200, v201
	v_cvt_pk_bf16_f32 v125, v202, v203
	v_cvt_pk_bf16_f32 v126, v204, v205
	v_cvt_pk_bf16_f32 v127, v206, v207
	ds_write_b128 v241, v[124:127] offset:4864
	global_load_dwordx4 v[84:87], v238, s[20:21]
	v_add_u32_e32 v238, v238, v243
	v_cvt_pk_bf16_f32 v124, v120, v121
	v_cvt_pk_bf16_f32 v125, v122, v123
	s_nop 0
	global_store_dwordx2 v239, v[124:125], s[24:25]
	v_add_u32_e32 v239, v239, v243
	s_waitcnt vmcnt(33)
	ds_read_b128 v[216:219], v242 offset:4096
	ds_read_b128 v[220:223], v242 offset:4160
	ds_read_b128 v[224:227], v242 offset:4224
	ds_read_b128 v[228:231], v242 offset:4288
	v_pk_mov_b32 v[232:233], v[136:137], v[152:153] op_sel:[0,0]
	v_pk_mov_b32 v[234:235], v[140:141], v[156:157] op_sel:[0,0]
	v_pk_mov_b32 v[244:245], v[144:145], v[160:161] op_sel:[0,0]
	v_pk_mov_b32 v[254:255], v[148:149], v[164:165] op_sel:[0,0]
	v_mfma_f32_16x16x32_bf16 v[168:171], v[92:95], v[0:3], 0
	v_pk_fma_f32 v[232:233], v[32:33], v[200:201], v[232:233] op_sel_hi:[0,1,1]
	v_pk_fma_f32 v[234:235], v[34:35], v[202:203], v[234:235] op_sel_hi:[0,1,1]
	v_pk_fma_f32 v[244:245], v[36:37], v[204:205], v[244:245] op_sel_hi:[0,1,1]
	v_pk_fma_f32 v[254:255], v[38:39], v[206:207], v[254:255] op_sel_hi:[0,1,1]
	v_mfma_f32_16x16x32_bf16 v[172:175], v[92:95], v[4:7], 0
	v_pk_fma_f32 v[200:201], v[32:33], v[200:201], v[232:233] op_sel:[1,1,0] op_sel_hi:[1,0,1] neg_lo:[1,0,0]
	v_pk_fma_f32 v[202:203], v[34:35], v[202:203], v[234:235] op_sel:[1,1,0] op_sel_hi:[1,0,1] neg_lo:[1,0,0]
	v_pk_fma_f32 v[204:205], v[36:37], v[204:205], v[244:245] op_sel:[1,1,0] op_sel_hi:[1,0,1] neg_lo:[1,0,0]
	v_pk_fma_f32 v[206:207], v[38:39], v[206:207], v[254:255] op_sel:[1,1,0] op_sel_hi:[1,0,1] neg_lo:[1,0,0]
	v_mfma_f32_16x16x32_bf16 v[176:179], v[92:95], v[8:11], 0
	v_cvt_pk_bf16_f32 v124, v200, v201
	v_cvt_pk_bf16_f32 v125, v202, v203
	v_cvt_pk_bf16_f32 v126, v204, v205
	v_cvt_pk_bf16_f32 v127, v206, v207
	v_mfma_f32_16x16x32_bf16 v[180:183], v[92:95], v[12:15], 0
	ds_write_b128 v241, v[124:127] offset:0
	v_pk_mov_b32 v[232:233], v[136:137], v[152:153] op_sel:[1,1]
	v_pk_mov_b32 v[234:235], v[140:141], v[156:157] op_sel:[1,1]
	v_pk_mov_b32 v[244:245], v[144:145], v[160:161] op_sel:[1,1]
	v_mfma_f32_16x16x32_bf16 v[184:187], v[92:95], v[16:19], 0
	v_pk_mov_b32 v[254:255], v[148:149], v[164:165] op_sel:[1,1]
	v_pk_fma_f32 v[232:233], v[32:33], v[200:201], v[232:233] op_sel_hi:[0,1,1]
	v_pk_fma_f32 v[234:235], v[34:35], v[202:203], v[234:235] op_sel_hi:[0,1,1]
	v_pk_fma_f32 v[244:245], v[36:37], v[204:205], v[244:245] op_sel_hi:[0,1,1]
	v_mfma_f32_16x16x32_bf16 v[188:191], v[92:95], v[20:23], 0
	v_pk_fma_f32 v[254:255], v[38:39], v[206:207], v[254:255] op_sel_hi:[0,1,1]
	v_pk_fma_f32 v[200:201], v[32:33], v[200:201], v[232:233] op_sel:[1,1,0] op_sel_hi:[1,0,1] neg_lo:[1,0,0]
	v_pk_fma_f32 v[202:203], v[34:35], v[202:203], v[234:235] op_sel:[1,1,0] op_sel_hi:[1,0,1] neg_lo:[1,0,0]
	v_pk_fma_f32 v[204:205], v[36:37], v[204:205], v[244:245] op_sel:[1,1,0] op_sel_hi:[1,0,1] neg_lo:[1,0,0]
	v_mfma_f32_16x16x32_bf16 v[192:195], v[92:95], v[24:27], 0
	v_pk_fma_f32 v[206:207], v[38:39], v[206:207], v[254:255] op_sel:[1,1,0] op_sel_hi:[1,0,1] neg_lo:[1,0,0]
	v_cvt_pk_bf16_f32 v124, v200, v201
	v_cvt_pk_bf16_f32 v125, v202, v203
	v_cvt_pk_bf16_f32 v126, v204, v205
	v_mfma_f32_16x16x32_bf16 v[196:199], v[92:95], v[28:31], 0
	v_cvt_pk_bf16_f32 v127, v206, v207
	ds_write_b128 v241, v[124:127] offset:256
	s_waitcnt lgkmcnt(2)
; __device__ __forceinline__ unsigned f2bf(float f) { unsigned u = __builtin_bit_cast(unsigned, f); return (u + 0x7fffu + ((u >> 16) & 1u)) >> 16; }
; __device__ __forceinline__ bf16x8 pack8(const float (&f)[8]) { u32x4 h; h.x = pk2(f[0], f[1]); h.y = pk2(f[2], f[3]); h.z = pk2(f[4], f[5]); h.w = pk2(f[6], f[7]); return __builtin_bit_cast(bf16x8, h); }
; template <bool FINAL> __device__ __forceinline__ void phase_s5_scan(const Fr& F) {
;     ...
;         for (int sub = 0; sub < 4; ++sub) {
;             const bf16x8 A1 = __builtin_bit_cast(bf16x8, uc[sub]);
; #pragma unroll
;             for (int nt = 0; nt < 8; ++nt) {
;                 f32x4 acc = {0.f, 0.f, 0.f, 0.f};
;                 acc = __builtin_amdgcn_mfma_f32_16x16x32_bf16(A1, B1[nt], acc, 0, 0, 0);
; #pragma unroll
;                 for (int reg = 0; reg < 4; ++reg) BUl[(4 * lq + reg) * 132 + 16 * nt + l15] = acc[reg];
;             }
;             asm volatile("s_waitcnt lgkmcnt(0)" ::: "memory");
; #pragma unroll 4
;             for (int jj = 0; jj < 16; ++jj) {
;                 const float br_ = BUl[jj * 132 + lane], bi_ = BUl[jj * 132 + 64 + lane];
;                 const float nr = ar * xr - ai * xi + br_, ni = ar * xi + ai * xr + bi_; xr = nr; xi = ni;
;                 if (FINAL) { BUl[jj * 132 + lane] = xr; BUl[jj * 132 + 64 + lane] = xi; }
;             }
;             if (FINAL) {
;                 asm volatile("s_waitcnt lgkmcnt(0)" ::: "memory");
;                 f32x4 acc = {0.f, 0.f, 0.f, 0.f};
; #pragma unroll
;                 for (int ks = 0; ks < 4; ++ks) {
;                     const f32x4 t0 = *(const f32x4*)(BUl + l15 * 132 + 32 * ks + 8 * lq), t1 = *(const f32x4*)(BUl + l15 * 132 + 32 * ks + 8 * lq + 4);
;                     const float xf[8] = {t0.x, t0.y, t0.z, t0.w, t1.x, t1.y, t1.z, t1.w};
;                     acc = __builtin_amdgcn_mfma_f32_16x16x32_bf16(pack8(xf), Chi[ks], acc, 0, 0, 0);
;                 }
; #pragma unroll
;                 for (int reg = 0; reg < 4; ++reg) { const int tok = tokof(s, chunk * 64 + sub * 16 + 4 * lq + reg);
;                     Yb[((size_t)b * TB + tok) * D + g * 16 + l15] = (bf16)f2bf(acc[reg]); }
;                 asm volatile("s_waitcnt lgkmcnt(0)" ::: "memory");
;             }
;         }
	v_pk_mov_b32 v[232:233], v[138:139], v[154:155] op_sel:[0,0]
	v_pk_mov_b32 v[234:235], v[142:143], v[158:159] op_sel:[0,0]
	v_pk_mov_b32 v[244:245], v[146:147], v[162:163] op_sel:[0,0]
	v_pk_mov_b32 v[254:255], v[150:151], v[166:167] op_sel:[0,0]
	v_mfma_f32_16x16x32_bf16 v[120:123], v[40:43], v[216:219], 0
	v_pk_fma_f32 v[232:233], v[32:33], v[200:201], v[232:233] op_sel_hi:[0,1,1]
	v_pk_fma_f32 v[234:235], v[34:35], v[202:203], v[234:235] op_sel_hi:[0,1,1]
	v_pk_fma_f32 v[244:245], v[36:37], v[204:205], v[244:245] op_sel_hi:[0,1,1]
	v_pk_fma_f32 v[254:255], v[38:39], v[206:207], v[254:255] op_sel_hi:[0,1,1]
	v_mfma_f32_16x16x32_bf16 v[120:123], v[44:47], v[220:223], v[120:123]
	v_pk_fma_f32 v[200:201], v[32:33], v[200:201], v[232:233] op_sel:[1,1,0] op_sel_hi:[1,0,1] neg_lo:[1,0,0]
	v_pk_fma_f32 v[202:203], v[34:35], v[202:203], v[234:235] op_sel:[1,1,0] op_sel_hi:[1,0,1] neg_lo:[1,0,0]
	v_pk_fma_f32 v[204:205], v[36:37], v[204:205], v[244:245] op_sel:[1,1,0] op_sel_hi:[1,0,1] neg_lo:[1,0,0]
	v_pk_fma_f32 v[206:207], v[38:39], v[206:207], v[254:255] op_sel:[1,1,0] op_sel_hi:[1,0,1] neg_lo:[1,0,0]
	v_mfma_f32_16x16x32_bf16 v[120:123], v[48:51], v[224:227], v[120:123]
	v_cvt_pk_bf16_f32 v124, v200, v201
	v_cvt_pk_bf16_f32 v125, v202, v203
	v_cvt_pk_bf16_f32 v126, v204, v205
	v_cvt_pk_bf16_f32 v127, v206, v207
	v_mfma_f32_16x16x32_bf16 v[120:123], v[52:55], v[228:231], v[120:123]
	ds_write_b128 v241, v[124:127] offset:512
	v_pk_mov_b32 v[232:233], v[138:139], v[154:155] op_sel:[1,1]
	v_pk_mov_b32 v[234:235], v[142:143], v[158:159] op_sel:[1,1]
	v_pk_mov_b32 v[244:245], v[146:147], v[162:163] op_sel:[1,1]
	v_pk_mov_b32 v[254:255], v[150:151], v[166:167] op_sel:[1,1]
	v_pk_fma_f32 v[232:233], v[32:33], v[200:201], v[232:233] op_sel_hi:[0,1,1]
	v_pk_fma_f32 v[234:235], v[34:35], v[202:203], v[234:235] op_sel_hi:[0,1,1]
	v_pk_fma_f32 v[244:245], v[36:37], v[204:205], v[244:245] op_sel_hi:[0,1,1]
	v_pk_fma_f32 v[254:255], v[38:39], v[206:207], v[254:255] op_sel_hi:[0,1,1]
	v_pk_fma_f32 v[200:201], v[32:33], v[200:201], v[232:233] op_sel:[1,1,0] op_sel_hi:[1,0,1] neg_lo:[1,0,0]
	v_pk_fma_f32 v[202:203], v[34:35], v[202:203], v[234:235] op_sel:[1,1,0] op_sel_hi:[1,0,1] neg_lo:[1,0,0]
	v_pk_fma_f32 v[204:205], v[36:37], v[204:205], v[244:245] op_sel:[1,1,0] op_sel_hi:[1,0,1] neg_lo:[1,0,0]
	v_pk_fma_f32 v[206:207], v[38:39], v[206:207], v[254:255] op_sel:[1,1,0] op_sel_hi:[1,0,1] neg_lo:[1,0,0]
	v_cvt_pk_bf16_f32 v124, v200, v201
	v_cvt_pk_bf16_f32 v125, v202, v203
	v_cvt_pk_bf16_f32 v126, v204, v205
	v_cvt_pk_bf16_f32 v127, v206, v207
	ds_write_b128 v241, v[124:127] offset:768
	global_load_dwordx4 v[88:91], v238, s[20:21]
	v_add_u32_e32 v238, v238, v243
	v_cvt_pk_bf16_f32 v124, v120, v121
	v_cvt_pk_bf16_f32 v125, v122, v123
	s_nop 0
	global_store_dwordx2 v239, v[124:125], s[24:25]
	v_add_u32_e32 v239, v239, v243
	s_waitcnt vmcnt(33)
	ds_read_b128 v[216:219], v242 offset:0
	ds_read_b128 v[220:223], v242 offset:64
	ds_read_b128 v[224:227], v242 offset:128
	ds_read_b128 v[228:231], v242 offset:192
	v_pk_mov_b32 v[232:233], v[168:169], v[184:185] op_sel:[0,0]
	v_pk_mov_b32 v[234:235], v[172:173], v[188:189] op_sel:[0,0]
	v_pk_mov_b32 v[244:245], v[176:177], v[192:193] op_sel:[0,0]
	v_pk_mov_b32 v[254:255], v[180:181], v[196:197] op_sel:[0,0]
	v_mfma_f32_16x16x32_bf16 v[136:139], v[96:99], v[0:3], 0
	v_pk_fma_f32 v[232:233], v[32:33], v[200:201], v[232:233] op_sel_hi:[0,1,1]
	v_pk_fma_f32 v[234:235], v[34:35], v[202:203], v[234:235] op_sel_hi:[0,1,1]
	v_pk_fma_f32 v[244:245], v[36:37], v[204:205], v[244:245] op_sel_hi:[0,1,1]
	v_pk_fma_f32 v[254:255], v[38:39], v[206:207], v[254:255] op_sel_hi:[0,1,1]
	v_mfma_f32_16x16x32_bf16 v[140:143], v[96:99], v[4:7], 0
	v_pk_fma_f32 v[200:201], v[32:33], v[200:201], v[232:233] op_sel:[1,1,0] op_sel_hi:[1,0,1] neg_lo:[1,0,0]
	v_pk_fma_f32 v[202:203], v[34:35], v[202:203], v[234:235] op_sel:[1,1,0] op_sel_hi:[1,0,1] neg_lo:[1,0,0]
	v_pk_fma_f32 v[204:205], v[36:37], v[204:205], v[244:245] op_sel:[1,1,0] op_sel_hi:[1,0,1] neg_lo:[1,0,0]
	v_pk_fma_f32 v[206:207], v[38:39], v[206:207], v[254:255] op_sel:[1,1,0] op_sel_hi:[1,0,1] neg_lo:[1,0,0]
	v_mfma_f32_16x16x32_bf16 v[144:147], v[96:99], v[8:11], 0
	v_cvt_pk_bf16_f32 v124, v200, v201
	v_cvt_pk_bf16_f32 v125, v202, v203
	v_cvt_pk_bf16_f32 v126, v204, v205
	v_cvt_pk_bf16_f32 v127, v206, v207
	v_mfma_f32_16x16x32_bf16 v[148:151], v[96:99], v[12:15], 0
	ds_write_b128 v241, v[124:127] offset:4096
	v_pk_mov_b32 v[232:233], v[168:169], v[184:185] op_sel:[1,1]
	v_pk_mov_b32 v[234:235], v[172:173], v[188:189] op_sel:[1,1]
	v_pk_mov_b32 v[244:245], v[176:177], v[192:193] op_sel:[1,1]
	v_mfma_f32_16x16x32_bf16 v[152:155], v[96:99], v[16:19], 0
	v_pk_mov_b32 v[254:255], v[180:181], v[196:197] op_sel:[1,1]
	v_pk_fma_f32 v[232:233], v[32:33], v[200:201], v[232:233] op_sel_hi:[0,1,1]
	v_pk_fma_f32 v[234:235], v[34:35], v[202:203], v[234:235] op_sel_hi:[0,1,1]
	v_pk_fma_f32 v[244:245], v[36:37], v[204:205], v[244:245] op_sel_hi:[0,1,1]
	v_mfma_f32_16x16x32_bf16 v[156:159], v[96:99], v[20:23], 0
	v_pk_fma_f32 v[254:255], v[38:39], v[206:207], v[254:255] op_sel_hi:[0,1,1]
	v_pk_fma_f32 v[200:201], v[32:33], v[200:201], v[232:233] op_sel:[1,1,0] op_sel_hi:[1,0,1] neg_lo:[1,0,0]
	v_pk_fma_f32 v[202:203], v[34:35], v[202:203], v[234:235] op_sel:[1,1,0] op_sel_hi:[1,0,1] neg_lo:[1,0,0]
	v_pk_fma_f32 v[204:205], v[36:37], v[204:205], v[244:245] op_sel:[1,1,0] op_sel_hi:[1,0,1] neg_lo:[1,0,0]
	v_mfma_f32_16x16x32_bf16 v[160:163], v[96:99], v[24:27], 0
	v_pk_fma_f32 v[206:207], v[38:39], v[206:207], v[254:255] op_sel:[1,1,0] op_sel_hi:[1,0,1] neg_lo:[1,0,0]
	v_cvt_pk_bf16_f32 v124, v200, v201
	v_cvt_pk_bf16_f32 v125, v202, v203
	v_cvt_pk_bf16_f32 v126, v204, v205
	v_mfma_f32_16x16x32_bf16 v[164:167], v[96:99], v[28:31], 0
	v_cvt_pk_bf16_f32 v127, v206, v207
	ds_write_b128 v241, v[124:127] offset:4352
	s_waitcnt lgkmcnt(2)
; __device__ __forceinline__ unsigned f2bf(float f) { unsigned u = __builtin_bit_cast(unsigned, f); return (u + 0x7fffu + ((u >> 16) & 1u)) >> 16; }
; __device__ __forceinline__ bf16x8 pack8(const float (&f)[8]) { u32x4 h; h.x = pk2(f[0], f[1]); h.y = pk2(f[2], f[3]); h.z = pk2(f[4], f[5]); h.w = pk2(f[6], f[7]); return __builtin_bit_cast(bf16x8, h); }
; template <bool FINAL> __device__ __forceinline__ void phase_s5_scan(const Fr& F) {
;     ...
;         for (int sub = 0; sub < 4; ++sub) {
;             const bf16x8 A1 = __builtin_bit_cast(bf16x8, uc[sub]);
; #pragma unroll
;             for (int nt = 0; nt < 8; ++nt) {
;                 f32x4 acc = {0.f, 0.f, 0.f, 0.f};
;                 acc = __builtin_amdgcn_mfma_f32_16x16x32_bf16(A1, B1[nt], acc, 0, 0, 0);
; #pragma unroll
;                 for (int reg = 0; reg < 4; ++reg) BUl[(4 * lq + reg) * 132 + 16 * nt + l15] = acc[reg];
;             }
;             asm volatile("s_waitcnt lgkmcnt(0)" ::: "memory");
; #pragma unroll 4
;             for (int jj = 0; jj < 16; ++jj) {
;                 const float br_ = BUl[jj * 132 + lane], bi_ = BUl[jj * 132 + 64 + lane];
;                 const float nr = ar * xr - ai * xi + br_, ni = ar * xi + ai * xr + bi_; xr = nr; xi = ni;
;                 if (FINAL) { BUl[jj * 132 + lane] = xr; BUl[jj * 132 + 64 + lane] = xi; }
;             }
;             if (FINAL) {
;                 asm volatile("s_waitcnt lgkmcnt(0)" ::: "memory");
;                 f32x4 acc = {0.f, 0.f, 0.f, 0.f};
; #pragma unroll
;                 for (int ks = 0; ks < 4; ++ks) {
;                     const f32x4 t0 = *(const f32x4*)(BUl + l15 * 132 + 32 * ks + 8 * lq), t1 = *(const f32x4*)(BUl + l15 * 132 + 32 * ks + 8 * lq + 4);
;                     const float xf[8] = {t0.x, t0.y, t0.z, t0.w, t1.x, t1.y, t1.z, t1.w};
;                     acc = __builtin_amdgcn_mfma_f32_16x16x32_bf16(pack8(xf), Chi[ks], acc, 0, 0, 0);
;                 }
; #pragma unroll
;                 for (int reg = 0; reg < 4; ++reg) { const int tok = tokof(s, chunk * 64 + sub * 16 + 4 * lq + reg);
;                     Yb[((size_t)b * TB + tok) * D + g * 16 + l15] = (bf16)f2bf(acc[reg]); }
;                 asm volatile("s_waitcnt lgkmcnt(0)" ::: "memory");
;             }
;         }
	v_pk_mov_b32 v[232:233], v[170:171], v[186:187] op_sel:[0,0]
	v_pk_mov_b32 v[234:235], v[174:175], v[190:191] op_sel:[0,0]
	v_pk_mov_b32 v[244:245], v[178:179], v[194:195] op_sel:[0,0]
	v_pk_mov_b32 v[254:255], v[182:183], v[198:199] op_sel:[0,0]
	v_mfma_f32_16x16x32_bf16 v[120:123], v[40:43], v[216:219], 0
	v_pk_fma_f32 v[232:233], v[32:33], v[200:201], v[232:233] op_sel_hi:[0,1,1]
	v_pk_fma_f32 v[234:235], v[34:35], v[202:203], v[234:235] op_sel_hi:[0,1,1]
	v_pk_fma_f32 v[244:245], v[36:37], v[204:205], v[244:245] op_sel_hi:[0,1,1]
	v_pk_fma_f32 v[254:255], v[38:39], v[206:207], v[254:255] op_sel_hi:[0,1,1]
	v_mfma_f32_16x16x32_bf16 v[120:123], v[44:47], v[220:223], v[120:123]
	v_pk_fma_f32 v[200:201], v[32:33], v[200:201], v[232:233] op_sel:[1,1,0] op_sel_hi:[1,0,1] neg_lo:[1,0,0]
	v_pk_fma_f32 v[202:203], v[34:35], v[202:203], v[234:235] op_sel:[1,1,0] op_sel_hi:[1,0,1] neg_lo:[1,0,0]
	v_pk_fma_f32 v[204:205], v[36:37], v[204:205], v[244:245] op_sel:[1,1,0] op_sel_hi:[1,0,1] neg_lo:[1,0,0]
	v_pk_fma_f32 v[206:207], v[38:39], v[206:207], v[254:255] op_sel:[1,1,0] op_sel_hi:[1,0,1] neg_lo:[1,0,0]
	v_mfma_f32_16x16x32_bf16 v[120:123], v[48:51], v[224:227], v[120:123]
	v_cvt_pk_bf16_f32 v124, v200, v201
	v_cvt_pk_bf16_f32 v125, v202, v203
	v_cvt_pk_bf16_f32 v126, v204, v205
	v_cvt_pk_bf16_f32 v127, v206, v207
	v_mfma_f32_16x16x32_bf16 v[120:123], v[52:55], v[228:231], v[120:123]
	ds_write_b128 v241, v[124:127] offset:4608
	v_pk_mov_b32 v[232:233], v[170:171], v[186:187] op_sel:[1,1]
	v_pk_mov_b32 v[234:235], v[174:175], v[190:191] op_sel:[1,1]
	v_pk_mov_b32 v[244:245], v[178:179], v[194:195] op_sel:[1,1]
	v_pk_mov_b32 v[254:255], v[182:183], v[198:199] op_sel:[1,1]
	v_pk_fma_f32 v[232:233], v[32:33], v[200:201], v[232:233] op_sel_hi:[0,1,1]
	v_pk_fma_f32 v[234:235], v[34:35], v[202:203], v[234:235] op_sel_hi:[0,1,1]
	v_pk_fma_f32 v[244:245], v[36:37], v[204:205], v[244:245] op_sel_hi:[0,1,1]
	v_pk_fma_f32 v[254:255], v[38:39], v[206:207], v[254:255] op_sel_hi:[0,1,1]
	v_pk_fma_f32 v[200:201], v[32:33], v[200:201], v[232:233] op_sel:[1,1,0] op_sel_hi:[1,0,1] neg_lo:[1,0,0]
	v_pk_fma_f32 v[202:203], v[34:35], v[202:203], v[234:235] op_sel:[1,1,0] op_sel_hi:[1,0,1] neg_lo:[1,0,0]
	v_pk_fma_f32 v[204:205], v[36:37], v[204:205], v[244:245] op_sel:[1,1,0] op_sel_hi:[1,0,1] neg_lo:[1,0,0]
	v_pk_fma_f32 v[206:207], v[38:39], v[206:207], v[254:255] op_sel:[1,1,0] op_sel_hi:[1,0,1] neg_lo:[1,0,0]
	v_cvt_pk_bf16_f32 v124, v200, v201
	v_cvt_pk_bf16_f32 v125, v202, v203
	v_cvt_pk_bf16_f32 v126, v204, v205
	v_cvt_pk_bf16_f32 v127, v206, v207
	ds_write_b128 v241, v[124:127] offset:4864
	global_load_dwordx4 v[92:95], v238, s[20:21]
	v_add_u32_e32 v238, v238, v243
	v_cvt_pk_bf16_f32 v124, v120, v121
	v_cvt_pk_bf16_f32 v125, v122, v123
	s_nop 0
	global_store_dwordx2 v239, v[124:125], s[24:25]
	v_add_u32_e32 v239, v239, v243
	s_waitcnt vmcnt(33)
	ds_read_b128 v[216:219], v242 offset:4096
	ds_read_b128 v[220:223], v242 offset:4160
	ds_read_b128 v[224:227], v242 offset:4224
	ds_read_b128 v[228:231], v242 offset:4288
	v_pk_mov_b32 v[232:233], v[136:137], v[152:153] op_sel:[0,0]
	v_pk_mov_b32 v[234:235], v[140:141], v[156:157] op_sel:[0,0]
	v_pk_mov_b32 v[244:245], v[144:145], v[160:161] op_sel:[0,0]
	v_pk_mov_b32 v[254:255], v[148:149], v[164:165] op_sel:[0,0]
	v_mfma_f32_16x16x32_bf16 v[168:171], v[100:103], v[0:3], 0
	v_pk_fma_f32 v[232:233], v[32:33], v[200:201], v[232:233] op_sel_hi:[0,1,1]
	v_pk_fma_f32 v[234:235], v[34:35], v[202:203], v[234:235] op_sel_hi:[0,1,1]
	v_pk_fma_f32 v[244:245], v[36:37], v[204:205], v[244:245] op_sel_hi:[0,1,1]
	v_pk_fma_f32 v[254:255], v[38:39], v[206:207], v[254:255] op_sel_hi:[0,1,1]
	v_mfma_f32_16x16x32_bf16 v[172:175], v[100:103], v[4:7], 0
	v_pk_fma_f32 v[200:201], v[32:33], v[200:201], v[232:233] op_sel:[1,1,0] op_sel_hi:[1,0,1] neg_lo:[1,0,0]
	v_pk_fma_f32 v[202:203], v[34:35], v[202:203], v[234:235] op_sel:[1,1,0] op_sel_hi:[1,0,1] neg_lo:[1,0,0]
	v_pk_fma_f32 v[204:205], v[36:37], v[204:205], v[244:245] op_sel:[1,1,0] op_sel_hi:[1,0,1] neg_lo:[1,0,0]
	v_pk_fma_f32 v[206:207], v[38:39], v[206:207], v[254:255] op_sel:[1,1,0] op_sel_hi:[1,0,1] neg_lo:[1,0,0]
	v_mfma_f32_16x16x32_bf16 v[176:179], v[100:103], v[8:11], 0
	v_cvt_pk_bf16_f32 v124, v200, v201
	v_cvt_pk_bf16_f32 v125, v202, v203
	v_cvt_pk_bf16_f32 v126, v204, v205
	v_cvt_pk_bf16_f32 v127, v206, v207
	v_mfma_f32_16x16x32_bf16 v[180:183], v[100:103], v[12:15], 0
	ds_write_b128 v241, v[124:127] offset:0
	v_pk_mov_b32 v[232:233], v[136:137], v[152:153] op_sel:[1,1]
	v_pk_mov_b32 v[234:235], v[140:141], v[156:157] op_sel:[1,1]
	v_pk_mov_b32 v[244:245], v[144:145], v[160:161] op_sel:[1,1]
	v_mfma_f32_16x16x32_bf16 v[184:187], v[100:103], v[16:19], 0
	v_pk_mov_b32 v[254:255], v[148:149], v[164:165] op_sel:[1,1]
	v_pk_fma_f32 v[232:233], v[32:33], v[200:201], v[232:233] op_sel_hi:[0,1,1]
	v_pk_fma_f32 v[234:235], v[34:35], v[202:203], v[234:235] op_sel_hi:[0,1,1]
	v_pk_fma_f32 v[244:245], v[36:37], v[204:205], v[244:245] op_sel_hi:[0,1,1]
	v_mfma_f32_16x16x32_bf16 v[188:191], v[100:103], v[20:23], 0
	v_pk_fma_f32 v[254:255], v[38:39], v[206:207], v[254:255] op_sel_hi:[0,1,1]
	v_pk_fma_f32 v[200:201], v[32:33], v[200:201], v[232:233] op_sel:[1,1,0] op_sel_hi:[1,0,1] neg_lo:[1,0,0]
	v_pk_fma_f32 v[202:203], v[34:35], v[202:203], v[234:235] op_sel:[1,1,0] op_sel_hi:[1,0,1] neg_lo:[1,0,0]
	v_pk_fma_f32 v[204:205], v[36:37], v[204:205], v[244:245] op_sel:[1,1,0] op_sel_hi:[1,0,1] neg_lo:[1,0,0]
	v_mfma_f32_16x16x32_bf16 v[192:195], v[100:103], v[24:27], 0
	v_pk_fma_f32 v[206:207], v[38:39], v[206:207], v[254:255] op_sel:[1,1,0] op_sel_hi:[1,0,1] neg_lo:[1,0,0]
	v_cvt_pk_bf16_f32 v124, v200, v201
	v_cvt_pk_bf16_f32 v125, v202, v203
	v_cvt_pk_bf16_f32 v126, v204, v205
	v_mfma_f32_16x16x32_bf16 v[196:199], v[100:103], v[28:31], 0
	v_cvt_pk_bf16_f32 v127, v206, v207
	ds_write_b128 v241, v[124:127] offset:256
	s_waitcnt lgkmcnt(2)
; __device__ __forceinline__ unsigned f2bf(float f) { unsigned u = __builtin_bit_cast(unsigned, f); return (u + 0x7fffu + ((u >> 16) & 1u)) >> 16; }
; __device__ __forceinline__ bf16x8 pack8(const float (&f)[8]) { u32x4 h; h.x = pk2(f[0], f[1]); h.y = pk2(f[2], f[3]); h.z = pk2(f[4], f[5]); h.w = pk2(f[6], f[7]); return __builtin_bit_cast(bf16x8, h); }
; template <bool FINAL> __device__ __forceinline__ void phase_s5_scan(const Fr& F) {
;     ...
;         for (int sub = 0; sub < 4; ++sub) {
;             const bf16x8 A1 = __builtin_bit_cast(bf16x8, uc[sub]);
; #pragma unroll
;             for (int nt = 0; nt < 8; ++nt) {
;                 f32x4 acc = {0.f, 0.f, 0.f, 0.f};
;                 acc = __builtin_amdgcn_mfma_f32_16x16x32_bf16(A1, B1[nt], acc, 0, 0, 0);
; #pragma unroll
;                 for (int reg = 0; reg < 4; ++reg) BUl[(4 * lq + reg) * 132 + 16 * nt + l15] = acc[reg];
;             }
;             asm volatile("s_waitcnt lgkmcnt(0)" ::: "memory");
; #pragma unroll 4
;             for (int jj = 0; jj < 16; ++jj) {
;                 const float br_ = BUl[jj * 132 + lane], bi_ = BUl[jj * 132 + 64 + lane];
;                 const float nr = ar * xr - ai * xi + br_, ni = ar * xi + ai * xr + bi_; xr = nr; xi = ni;
;                 if (FINAL) { BUl[jj * 132 + lane] = xr; BUl[jj * 132 + 64 + lane] = xi; }
;             }
;             if (FINAL) {
;                 asm volatile("s_waitcnt lgkmcnt(0)" ::: "memory");
;                 f32x4 acc = {0.f, 0.f, 0.f, 0.f};
; #pragma unroll
;                 for (int ks = 0; ks < 4; ++ks) {
;                     const f32x4 t0 = *(const f32x4*)(BUl + l15 * 132 + 32 * ks + 8 * lq), t1 = *(const f32x4*)(BUl + l15 * 132 + 32 * ks + 8 * lq + 4);
;                     const float xf[8] = {t0.x, t0.y, t0.z, t0.w, t1.x, t1.y, t1.z, t1.w};
;                     acc = __builtin_amdgcn_mfma_f32_16x16x32_bf16(pack8(xf), Chi[ks], acc, 0, 0, 0);
;                 }
; #pragma unroll
;                 for (int reg = 0; reg < 4; ++reg) { const int tok = tokof(s, chunk * 64 + sub * 16 + 4 * lq + reg);
;                     Yb[((size_t)b * TB + tok) * D + g * 16 + l15] = (bf16)f2bf(acc[reg]); }
;                 asm volatile("s_waitcnt lgkmcnt(0)" ::: "memory");
;             }
;         }
	v_pk_mov_b32 v[232:233], v[138:139], v[154:155] op_sel:[0,0]
	v_pk_mov_b32 v[234:235], v[142:143], v[158:159] op_sel:[0,0]
	v_pk_mov_b32 v[244:245], v[146:147], v[162:163] op_sel:[0,0]
	v_pk_mov_b32 v[254:255], v[150:151], v[166:167] op_sel:[0,0]
	v_mfma_f32_16x16x32_bf16 v[120:123], v[40:43], v[216:219], 0
	v_pk_fma_f32 v[232:233], v[32:33], v[200:201], v[232:233] op_sel_hi:[0,1,1]
	v_pk_fma_f32 v[234:235], v[34:35], v[202:203], v[234:235] op_sel_hi:[0,1,1]
	v_pk_fma_f32 v[244:245], v[36:37], v[204:205], v[244:245] op_sel_hi:[0,1,1]
	v_pk_fma_f32 v[254:255], v[38:39], v[206:207], v[254:255] op_sel_hi:[0,1,1]
	v_mfma_f32_16x16x32_bf16 v[120:123], v[44:47], v[220:223], v[120:123]
	v_pk_fma_f32 v[200:201], v[32:33], v[200:201], v[232:233] op_sel:[1,1,0] op_sel_hi:[1,0,1] neg_lo:[1,0,0]
	v_pk_fma_f32 v[202:203], v[34:35], v[202:203], v[234:235] op_sel:[1,1,0] op_sel_hi:[1,0,1] neg_lo:[1,0,0]
	v_pk_fma_f32 v[204:205], v[36:37], v[204:205], v[244:245] op_sel:[1,1,0] op_sel_hi:[1,0,1] neg_lo:[1,0,0]
	v_pk_fma_f32 v[206:207], v[38:39], v[206:207], v[254:255] op_sel:[1,1,0] op_sel_hi:[1,0,1] neg_lo:[1,0,0]
	v_mfma_f32_16x16x32_bf16 v[120:123], v[48:51], v[224:227], v[120:123]
	v_cvt_pk_bf16_f32 v124, v200, v201
	v_cvt_pk_bf16_f32 v125, v202, v203
	v_cvt_pk_bf16_f32 v126, v204, v205
	v_cvt_pk_bf16_f32 v127, v206, v207
	v_mfma_f32_16x16x32_bf16 v[120:123], v[52:55], v[228:231], v[120:123]
	ds_write_b128 v241, v[124:127] offset:512
	v_pk_mov_b32 v[232:233], v[138:139], v[154:155] op_sel:[1,1]
	v_pk_mov_b32 v[234:235], v[142:143], v[158:159] op_sel:[1,1]
	v_pk_mov_b32 v[244:245], v[146:147], v[162:163] op_sel:[1,1]
	v_pk_mov_b32 v[254:255], v[150:151], v[166:167] op_sel:[1,1]
	v_pk_fma_f32 v[232:233], v[32:33], v[200:201], v[232:233] op_sel_hi:[0,1,1]
	v_pk_fma_f32 v[234:235], v[34:35], v[202:203], v[234:235] op_sel_hi:[0,1,1]
	v_pk_fma_f32 v[244:245], v[36:37], v[204:205], v[244:245] op_sel_hi:[0,1,1]
	v_pk_fma_f32 v[254:255], v[38:39], v[206:207], v[254:255] op_sel_hi:[0,1,1]
	v_pk_fma_f32 v[200:201], v[32:33], v[200:201], v[232:233] op_sel:[1,1,0] op_sel_hi:[1,0,1] neg_lo:[1,0,0]
	v_pk_fma_f32 v[202:203], v[34:35], v[202:203], v[234:235] op_sel:[1,1,0] op_sel_hi:[1,0,1] neg_lo:[1,0,0]
	v_pk_fma_f32 v[204:205], v[36:37], v[204:205], v[244:245] op_sel:[1,1,0] op_sel_hi:[1,0,1] neg_lo:[1,0,0]
	v_pk_fma_f32 v[206:207], v[38:39], v[206:207], v[254:255] op_sel:[1,1,0] op_sel_hi:[1,0,1] neg_lo:[1,0,0]
	v_cvt_pk_bf16_f32 v124, v200, v201
	v_cvt_pk_bf16_f32 v125, v202, v203
	v_cvt_pk_bf16_f32 v126, v204, v205
	v_cvt_pk_bf16_f32 v127, v206, v207
	ds_write_b128 v241, v[124:127] offset:768
	global_load_dwordx4 v[96:99], v238, s[20:21]
	v_add_u32_e32 v238, v238, v243
	v_cvt_pk_bf16_f32 v124, v120, v121
	v_cvt_pk_bf16_f32 v125, v122, v123
	s_nop 0
	global_store_dwordx2 v239, v[124:125], s[24:25]
	v_add_u32_e32 v239, v239, v243
	s_waitcnt vmcnt(33)
	ds_read_b128 v[216:219], v242 offset:0
	ds_read_b128 v[220:223], v242 offset:64
	ds_read_b128 v[224:227], v242 offset:128
	ds_read_b128 v[228:231], v242 offset:192
	v_pk_mov_b32 v[232:233], v[168:169], v[184:185] op_sel:[0,0]
	v_pk_mov_b32 v[234:235], v[172:173], v[188:189] op_sel:[0,0]
	v_pk_mov_b32 v[244:245], v[176:177], v[192:193] op_sel:[0,0]
	v_pk_mov_b32 v[254:255], v[180:181], v[196:197] op_sel:[0,0]
	v_mfma_f32_16x16x32_bf16 v[136:139], v[104:107], v[0:3], 0
	v_pk_fma_f32 v[232:233], v[32:33], v[200:201], v[232:233] op_sel_hi:[0,1,1]
	v_pk_fma_f32 v[234:235], v[34:35], v[202:203], v[234:235] op_sel_hi:[0,1,1]
	v_pk_fma_f32 v[244:245], v[36:37], v[204:205], v[244:245] op_sel_hi:[0,1,1]
	v_pk_fma_f32 v[254:255], v[38:39], v[206:207], v[254:255] op_sel_hi:[0,1,1]
	v_mfma_f32_16x16x32_bf16 v[140:143], v[104:107], v[4:7], 0
	v_pk_fma_f32 v[200:201], v[32:33], v[200:201], v[232:233] op_sel:[1,1,0] op_sel_hi:[1,0,1] neg_lo:[1,0,0]
	v_pk_fma_f32 v[202:203], v[34:35], v[202:203], v[234:235] op_sel:[1,1,0] op_sel_hi:[1,0,1] neg_lo:[1,0,0]
	v_pk_fma_f32 v[204:205], v[36:37], v[204:205], v[244:245] op_sel:[1,1,0] op_sel_hi:[1,0,1] neg_lo:[1,0,0]
	v_pk_fma_f32 v[206:207], v[38:39], v[206:207], v[254:255] op_sel:[1,1,0] op_sel_hi:[1,0,1] neg_lo:[1,0,0]
	v_mfma_f32_16x16x32_bf16 v[144:147], v[104:107], v[8:11], 0
	v_cvt_pk_bf16_f32 v124, v200, v201
	v_cvt_pk_bf16_f32 v125, v202, v203
	v_cvt_pk_bf16_f32 v126, v204, v205
	v_cvt_pk_bf16_f32 v127, v206, v207
	v_mfma_f32_16x16x32_bf16 v[148:151], v[104:107], v[12:15], 0
	ds_write_b128 v241, v[124:127] offset:4096
	v_pk_mov_b32 v[232:233], v[168:169], v[184:185] op_sel:[1,1]
	v_pk_mov_b32 v[234:235], v[172:173], v[188:189] op_sel:[1,1]
	v_pk_mov_b32 v[244:245], v[176:177], v[192:193] op_sel:[1,1]
	v_mfma_f32_16x16x32_bf16 v[152:155], v[104:107], v[16:19], 0
	v_pk_mov_b32 v[254:255], v[180:181], v[196:197] op_sel:[1,1]
	v_pk_fma_f32 v[232:233], v[32:33], v[200:201], v[232:233] op_sel_hi:[0,1,1]
	v_pk_fma_f32 v[234:235], v[34:35], v[202:203], v[234:235] op_sel_hi:[0,1,1]
	v_pk_fma_f32 v[244:245], v[36:37], v[204:205], v[244:245] op_sel_hi:[0,1,1]
	v_mfma_f32_16x16x32_bf16 v[156:159], v[104:107], v[20:23], 0
	v_pk_fma_f32 v[254:255], v[38:39], v[206:207], v[254:255] op_sel_hi:[0,1,1]
	v_pk_fma_f32 v[200:201], v[32:33], v[200:201], v[232:233] op_sel:[1,1,0] op_sel_hi:[1,0,1] neg_lo:[1,0,0]
	v_pk_fma_f32 v[202:203], v[34:35], v[202:203], v[234:235] op_sel:[1,1,0] op_sel_hi:[1,0,1] neg_lo:[1,0,0]
	v_pk_fma_f32 v[204:205], v[36:37], v[204:205], v[244:245] op_sel:[1,1,0] op_sel_hi:[1,0,1] neg_lo:[1,0,0]
	v_mfma_f32_16x16x32_bf16 v[160:163], v[104:107], v[24:27], 0
	v_pk_fma_f32 v[206:207], v[38:39], v[206:207], v[254:255] op_sel:[1,1,0] op_sel_hi:[1,0,1] neg_lo:[1,0,0]
	v_cvt_pk_bf16_f32 v124, v200, v201
	v_cvt_pk_bf16_f32 v125, v202, v203
	v_cvt_pk_bf16_f32 v126, v204, v205
	v_mfma_f32_16x16x32_bf16 v[164:167], v[104:107], v[28:31], 0
	v_cvt_pk_bf16_f32 v127, v206, v207
	ds_write_b128 v241, v[124:127] offset:4352
	s_waitcnt lgkmcnt(2)
; __device__ __forceinline__ unsigned f2bf(float f) { unsigned u = __builtin_bit_cast(unsigned, f); return (u + 0x7fffu + ((u >> 16) & 1u)) >> 16; }
; __device__ __forceinline__ bf16x8 pack8(const float (&f)[8]) { u32x4 h; h.x = pk2(f[0], f[1]); h.y = pk2(f[2], f[3]); h.z = pk2(f[4], f[5]); h.w = pk2(f[6], f[7]); return __builtin_bit_cast(bf16x8, h); }
; template <bool FINAL> __device__ __forceinline__ void phase_s5_scan(const Fr& F) {
;     ...
;         for (int sub = 0; sub < 4; ++sub) {
;             const bf16x8 A1 = __builtin_bit_cast(bf16x8, uc[sub]);
; #pragma unroll
;             for (int nt = 0; nt < 8; ++nt) {
;                 f32x4 acc = {0.f, 0.f, 0.f, 0.f};
;                 acc = __builtin_amdgcn_mfma_f32_16x16x32_bf16(A1, B1[nt], acc, 0, 0, 0);
; #pragma unroll
;                 for (int reg = 0; reg < 4; ++reg) BUl[(4 * lq + reg) * 132 + 16 * nt + l15] = acc[reg];
;             }
;             asm volatile("s_waitcnt lgkmcnt(0)" ::: "memory");
; #pragma unroll 4
;             for (int jj = 0; jj < 16; ++jj) {
;                 const float br_ = BUl[jj * 132 + lane], bi_ = BUl[jj * 132 + 64 + lane];
;                 const float nr = ar * xr - ai * xi + br_, ni = ar * xi + ai * xr + bi_; xr = nr; xi = ni;
;                 if (FINAL) { BUl[jj * 132 + lane] = xr; BUl[jj * 132 + 64 + lane] = xi; }
;             }
;             if (FINAL) {
;                 asm volatile("s_waitcnt lgkmcnt(0)" ::: "memory");
;                 f32x4 acc = {0.f, 0.f, 0.f, 0.f};
; #pragma unroll
;                 for (int ks = 0; ks < 4; ++ks) {
;                     const f32x4 t0 = *(const f32x4*)(BUl + l15 * 132 + 32 * ks + 8 * lq), t1 = *(const f32x4*)(BUl + l15 * 132 + 32 * ks + 8 * lq + 4);
;                     const float xf[8] = {t0.x, t0.y, t0.z, t0.w, t1.x, t1.y, t1.z, t1.w};
;                     acc = __builtin_amdgcn_mfma_f32_16x16x32_bf16(pack8(xf), Chi[ks], acc, 0, 0, 0);
;                 }
; #pragma unroll
;                 for (int reg = 0; reg < 4; ++reg) { const int tok = tokof(s, chunk * 64 + sub * 16 + 4 * lq + reg);
;                     Yb[((size_t)b * TB + tok) * D + g * 16 + l15] = (bf16)f2bf(acc[reg]); }
;                 asm volatile("s_waitcnt lgkmcnt(0)" ::: "memory");
;             }
;         }
	v_pk_mov_b32 v[232:233], v[170:171], v[186:187] op_sel:[0,0]
	v_pk_mov_b32 v[234:235], v[174:175], v[190:191] op_sel:[0,0]
	v_pk_mov_b32 v[244:245], v[178:179], v[194:195] op_sel:[0,0]
	v_pk_mov_b32 v[254:255], v[182:183], v[198:199] op_sel:[0,0]
	v_mfma_f32_16x16x32_bf16 v[120:123], v[40:43], v[216:219], 0
	v_pk_fma_f32 v[232:233], v[32:33], v[200:201], v[232:233] op_sel_hi:[0,1,1]
	v_pk_fma_f32 v[234:235], v[34:35], v[202:203], v[234:235] op_sel_hi:[0,1,1]
	v_pk_fma_f32 v[244:245], v[36:37], v[204:205], v[244:245] op_sel_hi:[0,1,1]
	v_pk_fma_f32 v[254:255], v[38:39], v[206:207], v[254:255] op_sel_hi:[0,1,1]
	v_mfma_f32_16x16x32_bf16 v[120:123], v[44:47], v[220:223], v[120:123]
	v_pk_fma_f32 v[200:201], v[32:33], v[200:201], v[232:233] op_sel:[1,1,0] op_sel_hi:[1,0,1] neg_lo:[1,0,0]
	v_pk_fma_f32 v[202:203], v[34:35], v[202:203], v[234:235] op_sel:[1,1,0] op_sel_hi:[1,0,1] neg_lo:[1,0,0]
	v_pk_fma_f32 v[204:205], v[36:37], v[204:205], v[244:245] op_sel:[1,1,0] op_sel_hi:[1,0,1] neg_lo:[1,0,0]
	v_pk_fma_f32 v[206:207], v[38:39], v[206:207], v[254:255] op_sel:[1,1,0] op_sel_hi:[1,0,1] neg_lo:[1,0,0]
	v_mfma_f32_16x16x32_bf16 v[120:123], v[48:51], v[224:227], v[120:123]
	v_cvt_pk_bf16_f32 v124, v200, v201
	v_cvt_pk_bf16_f32 v125, v202, v203
	v_cvt_pk_bf16_f32 v126, v204, v205
	v_cvt_pk_bf16_f32 v127, v206, v207
	v_mfma_f32_16x16x32_bf16 v[120:123], v[52:55], v[228:231], v[120:123]
	ds_write_b128 v241, v[124:127] offset:4608
	v_pk_mov_b32 v[232:233], v[170:171], v[186:187] op_sel:[1,1]
	v_pk_mov_b32 v[234:235], v[174:175], v[190:191] op_sel:[1,1]
	v_pk_mov_b32 v[244:245], v[178:179], v[194:195] op_sel:[1,1]
	v_pk_mov_b32 v[254:255], v[182:183], v[198:199] op_sel:[1,1]
	v_pk_fma_f32 v[232:233], v[32:33], v[200:201], v[232:233] op_sel_hi:[0,1,1]
	v_pk_fma_f32 v[234:235], v[34:35], v[202:203], v[234:235] op_sel_hi:[0,1,1]
	v_pk_fma_f32 v[244:245], v[36:37], v[204:205], v[244:245] op_sel_hi:[0,1,1]
	v_pk_fma_f32 v[254:255], v[38:39], v[206:207], v[254:255] op_sel_hi:[0,1,1]
	v_pk_fma_f32 v[200:201], v[32:33], v[200:201], v[232:233] op_sel:[1,1,0] op_sel_hi:[1,0,1] neg_lo:[1,0,0]
	v_pk_fma_f32 v[202:203], v[34:35], v[202:203], v[234:235] op_sel:[1,1,0] op_sel_hi:[1,0,1] neg_lo:[1,0,0]
	v_pk_fma_f32 v[204:205], v[36:37], v[204:205], v[244:245] op_sel:[1,1,0] op_sel_hi:[1,0,1] neg_lo:[1,0,0]
	v_pk_fma_f32 v[206:207], v[38:39], v[206:207], v[254:255] op_sel:[1,1,0] op_sel_hi:[1,0,1] neg_lo:[1,0,0]
	v_cvt_pk_bf16_f32 v124, v200, v201
	v_cvt_pk_bf16_f32 v125, v202, v203
	v_cvt_pk_bf16_f32 v126, v204, v205
	v_cvt_pk_bf16_f32 v127, v206, v207
	ds_write_b128 v241, v[124:127] offset:4864
	global_load_dwordx4 v[100:103], v238, s[20:21]
	v_add_u32_e32 v238, v238, v243
	v_cvt_pk_bf16_f32 v124, v120, v121
	v_cvt_pk_bf16_f32 v125, v122, v123
	s_nop 0
	global_store_dwordx2 v239, v[124:125], s[24:25]
	v_add_u32_e32 v239, v239, v243
	s_waitcnt vmcnt(33)
	ds_read_b128 v[216:219], v242 offset:4096
	ds_read_b128 v[220:223], v242 offset:4160
	ds_read_b128 v[224:227], v242 offset:4224
	ds_read_b128 v[228:231], v242 offset:4288
	v_pk_mov_b32 v[232:233], v[136:137], v[152:153] op_sel:[0,0]
	v_pk_mov_b32 v[234:235], v[140:141], v[156:157] op_sel:[0,0]
	v_pk_mov_b32 v[244:245], v[144:145], v[160:161] op_sel:[0,0]
	v_pk_mov_b32 v[254:255], v[148:149], v[164:165] op_sel:[0,0]
	v_mfma_f32_16x16x32_bf16 v[168:171], v[108:111], v[0:3], 0
	v_pk_fma_f32 v[232:233], v[32:33], v[200:201], v[232:233] op_sel_hi:[0,1,1]
	v_pk_fma_f32 v[234:235], v[34:35], v[202:203], v[234:235] op_sel_hi:[0,1,1]
	v_pk_fma_f32 v[244:245], v[36:37], v[204:205], v[244:245] op_sel_hi:[0,1,1]
	v_pk_fma_f32 v[254:255], v[38:39], v[206:207], v[254:255] op_sel_hi:[0,1,1]
	v_mfma_f32_16x16x32_bf16 v[172:175], v[108:111], v[4:7], 0
	v_pk_fma_f32 v[200:201], v[32:33], v[200:201], v[232:233] op_sel:[1,1,0] op_sel_hi:[1,0,1] neg_lo:[1,0,0]
	v_pk_fma_f32 v[202:203], v[34:35], v[202:203], v[234:235] op_sel:[1,1,0] op_sel_hi:[1,0,1] neg_lo:[1,0,0]
	v_pk_fma_f32 v[204:205], v[36:37], v[204:205], v[244:245] op_sel:[1,1,0] op_sel_hi:[1,0,1] neg_lo:[1,0,0]
	v_pk_fma_f32 v[206:207], v[38:39], v[206:207], v[254:255] op_sel:[1,1,0] op_sel_hi:[1,0,1] neg_lo:[1,0,0]
	v_mfma_f32_16x16x32_bf16 v[176:179], v[108:111], v[8:11], 0
	v_cvt_pk_bf16_f32 v124, v200, v201
	v_cvt_pk_bf16_f32 v125, v202, v203
	v_cvt_pk_bf16_f32 v126, v204, v205
	v_cvt_pk_bf16_f32 v127, v206, v207
	v_mfma_f32_16x16x32_bf16 v[180:183], v[108:111], v[12:15], 0
	ds_write_b128 v241, v[124:127] offset:0
	v_pk_mov_b32 v[232:233], v[136:137], v[152:153] op_sel:[1,1]
	v_pk_mov_b32 v[234:235], v[140:141], v[156:157] op_sel:[1,1]
	v_pk_mov_b32 v[244:245], v[144:145], v[160:161] op_sel:[1,1]
	v_mfma_f32_16x16x32_bf16 v[184:187], v[108:111], v[16:19], 0
	v_pk_mov_b32 v[254:255], v[148:149], v[164:165] op_sel:[1,1]
	v_pk_fma_f32 v[232:233], v[32:33], v[200:201], v[232:233] op_sel_hi:[0,1,1]
	v_pk_fma_f32 v[234:235], v[34:35], v[202:203], v[234:235] op_sel_hi:[0,1,1]
	v_pk_fma_f32 v[244:245], v[36:37], v[204:205], v[244:245] op_sel_hi:[0,1,1]
	v_mfma_f32_16x16x32_bf16 v[188:191], v[108:111], v[20:23], 0
	v_pk_fma_f32 v[254:255], v[38:39], v[206:207], v[254:255] op_sel_hi:[0,1,1]
	v_pk_fma_f32 v[200:201], v[32:33], v[200:201], v[232:233] op_sel:[1,1,0] op_sel_hi:[1,0,1] neg_lo:[1,0,0]
	v_pk_fma_f32 v[202:203], v[34:35], v[202:203], v[234:235] op_sel:[1,1,0] op_sel_hi:[1,0,1] neg_lo:[1,0,0]
	v_pk_fma_f32 v[204:205], v[36:37], v[204:205], v[244:245] op_sel:[1,1,0] op_sel_hi:[1,0,1] neg_lo:[1,0,0]
	v_mfma_f32_16x16x32_bf16 v[192:195], v[108:111], v[24:27], 0
	v_pk_fma_f32 v[206:207], v[38:39], v[206:207], v[254:255] op_sel:[1,1,0] op_sel_hi:[1,0,1] neg_lo:[1,0,0]
	v_cvt_pk_bf16_f32 v124, v200, v201
	v_cvt_pk_bf16_f32 v125, v202, v203
	v_cvt_pk_bf16_f32 v126, v204, v205
	v_mfma_f32_16x16x32_bf16 v[196:199], v[108:111], v[28:31], 0
	v_cvt_pk_bf16_f32 v127, v206, v207
	ds_write_b128 v241, v[124:127] offset:256
	s_waitcnt lgkmcnt(2)
; __device__ __forceinline__ unsigned f2bf(float f) { unsigned u = __builtin_bit_cast(unsigned, f); return (u + 0x7fffu + ((u >> 16) & 1u)) >> 16; }
; __device__ __forceinline__ bf16x8 pack8(const float (&f)[8]) { u32x4 h; h.x = pk2(f[0], f[1]); h.y = pk2(f[2], f[3]); h.z = pk2(f[4], f[5]); h.w = pk2(f[6], f[7]); return __builtin_bit_cast(bf16x8, h); }
; template <bool FINAL> __device__ __forceinline__ void phase_s5_scan(const Fr& F) {
;     ...
;         for (int sub = 0; sub < 4; ++sub) {
;             const bf16x8 A1 = __builtin_bit_cast(bf16x8, uc[sub]);
; #pragma unroll
;             for (int nt = 0; nt < 8; ++nt) {
;                 f32x4 acc = {0.f, 0.f, 0.f, 0.f};
;                 acc = __builtin_amdgcn_mfma_f32_16x16x32_bf16(A1, B1[nt], acc, 0, 0, 0);
; #pragma unroll
;                 for (int reg = 0; reg < 4; ++reg) BUl[(4 * lq + reg) * 132 + 16 * nt + l15] = acc[reg];
;             }
;             asm volatile("s_waitcnt lgkmcnt(0)" ::: "memory");
; #pragma unroll 4
;             for (int jj = 0; jj < 16; ++jj) {
;                 const float br_ = BUl[jj * 132 + lane], bi_ = BUl[jj * 132 + 64 + lane];
;                 const float nr = ar * xr - ai * xi + br_, ni = ar * xi + ai * xr + bi_; xr = nr; xi = ni;
;                 if (FINAL) { BUl[jj * 132 + lane] = xr; BUl[jj * 132 + 64 + lane] = xi; }
;             }
;             if (FINAL) {
;                 asm volatile("s_waitcnt lgkmcnt(0)" ::: "memory");
;                 f32x4 acc = {0.f, 0.f, 0.f, 0.f};
; #pragma unroll
;                 for (int ks = 0; ks < 4; ++ks) {
;                     const f32x4 t0 = *(const f32x4*)(BUl + l15 * 132 + 32 * ks + 8 * lq), t1 = *(const f32x4*)(BUl + l15 * 132 + 32 * ks + 8 * lq + 4);
;                     const float xf[8] = {t0.x, t0.y, t0.z, t0.w, t1.x, t1.y, t1.z, t1.w};
;                     acc = __builtin_amdgcn_mfma_f32_16x16x32_bf16(pack8(xf), Chi[ks], acc, 0, 0, 0);
;                 }
; #pragma unroll
;                 for (int reg = 0; reg < 4; ++reg) { const int tok = tokof(s, chunk * 64 + sub * 16 + 4 * lq + reg);
;                     Yb[((size_t)b * TB + tok) * D + g * 16 + l15] = (bf16)f2bf(acc[reg]); }
;                 asm volatile("s_waitcnt lgkmcnt(0)" ::: "memory");
;             }
;         }
	v_pk_mov_b32 v[232:233], v[138:139], v[154:155] op_sel:[0,0]
	v_pk_mov_b32 v[234:235], v[142:143], v[158:159] op_sel:[0,0]
	v_pk_mov_b32 v[244:245], v[146:147], v[162:163] op_sel:[0,0]
	v_pk_mov_b32 v[254:255], v[150:151], v[166:167] op_sel:[0,0]
	v_mfma_f32_16x16x32_bf16 v[120:123], v[40:43], v[216:219], 0
	v_pk_fma_f32 v[232:233], v[32:33], v[200:201], v[232:233] op_sel_hi:[0,1,1]
	v_pk_fma_f32 v[234:235], v[34:35], v[202:203], v[234:235] op_sel_hi:[0,1,1]
	v_pk_fma_f32 v[244:245], v[36:37], v[204:205], v[244:245] op_sel_hi:[0,1,1]
	v_pk_fma_f32 v[254:255], v[38:39], v[206:207], v[254:255] op_sel_hi:[0,1,1]
	v_mfma_f32_16x16x32_bf16 v[120:123], v[44:47], v[220:223], v[120:123]
	v_pk_fma_f32 v[200:201], v[32:33], v[200:201], v[232:233] op_sel:[1,1,0] op_sel_hi:[1,0,1] neg_lo:[1,0,0]
	v_pk_fma_f32 v[202:203], v[34:35], v[202:203], v[234:235] op_sel:[1,1,0] op_sel_hi:[1,0,1] neg_lo:[1,0,0]
	v_pk_fma_f32 v[204:205], v[36:37], v[204:205], v[244:245] op_sel:[1,1,0] op_sel_hi:[1,0,1] neg_lo:[1,0,0]
	v_pk_fma_f32 v[206:207], v[38:39], v[206:207], v[254:255] op_sel:[1,1,0] op_sel_hi:[1,0,1] neg_lo:[1,0,0]
	v_mfma_f32_16x16x32_bf16 v[120:123], v[48:51], v[224:227], v[120:123]
	v_cvt_pk_bf16_f32 v124, v200, v201
	v_cvt_pk_bf16_f32 v125, v202, v203
	v_cvt_pk_bf16_f32 v126, v204, v205
	v_cvt_pk_bf16_f32 v127, v206, v207
	v_mfma_f32_16x16x32_bf16 v[120:123], v[52:55], v[228:231], v[120:123]
	ds_write_b128 v241, v[124:127] offset:512
	v_pk_mov_b32 v[232:233], v[138:139], v[154:155] op_sel:[1,1]
	v_pk_mov_b32 v[234:235], v[142:143], v[158:159] op_sel:[1,1]
	v_pk_mov_b32 v[244:245], v[146:147], v[162:163] op_sel:[1,1]
	v_pk_mov_b32 v[254:255], v[150:151], v[166:167] op_sel:[1,1]
	v_pk_fma_f32 v[232:233], v[32:33], v[200:201], v[232:233] op_sel_hi:[0,1,1]
	v_pk_fma_f32 v[234:235], v[34:35], v[202:203], v[234:235] op_sel_hi:[0,1,1]
	v_pk_fma_f32 v[244:245], v[36:37], v[204:205], v[244:245] op_sel_hi:[0,1,1]
	v_pk_fma_f32 v[254:255], v[38:39], v[206:207], v[254:255] op_sel_hi:[0,1,1]
	v_pk_fma_f32 v[200:201], v[32:33], v[200:201], v[232:233] op_sel:[1,1,0] op_sel_hi:[1,0,1] neg_lo:[1,0,0]
	v_pk_fma_f32 v[202:203], v[34:35], v[202:203], v[234:235] op_sel:[1,1,0] op_sel_hi:[1,0,1] neg_lo:[1,0,0]
	v_pk_fma_f32 v[204:205], v[36:37], v[204:205], v[244:245] op_sel:[1,1,0] op_sel_hi:[1,0,1] neg_lo:[1,0,0]
	v_pk_fma_f32 v[206:207], v[38:39], v[206:207], v[254:255] op_sel:[1,1,0] op_sel_hi:[1,0,1] neg_lo:[1,0,0]
	v_cvt_pk_bf16_f32 v124, v200, v201
	v_cvt_pk_bf16_f32 v125, v202, v203
	v_cvt_pk_bf16_f32 v126, v204, v205
	v_cvt_pk_bf16_f32 v127, v206, v207
	ds_write_b128 v241, v[124:127] offset:768
	global_load_dwordx4 v[104:107], v238, s[20:21]
	v_add_u32_e32 v238, v238, v243
	v_cvt_pk_bf16_f32 v124, v120, v121
	v_cvt_pk_bf16_f32 v125, v122, v123
	s_nop 0
	global_store_dwordx2 v239, v[124:125], s[24:25]
	v_add_u32_e32 v239, v239, v243
	s_waitcnt vmcnt(33)
	ds_read_b128 v[216:219], v242 offset:0
	ds_read_b128 v[220:223], v242 offset:64
	ds_read_b128 v[224:227], v242 offset:128
	ds_read_b128 v[228:231], v242 offset:192
	v_pk_mov_b32 v[232:233], v[168:169], v[184:185] op_sel:[0,0]
	v_pk_mov_b32 v[234:235], v[172:173], v[188:189] op_sel:[0,0]
	v_pk_mov_b32 v[244:245], v[176:177], v[192:193] op_sel:[0,0]
	v_pk_mov_b32 v[254:255], v[180:181], v[196:197] op_sel:[0,0]
	v_mfma_f32_16x16x32_bf16 v[136:139], v[112:115], v[0:3], 0
	v_pk_fma_f32 v[232:233], v[32:33], v[200:201], v[232:233] op_sel_hi:[0,1,1]
	v_pk_fma_f32 v[234:235], v[34:35], v[202:203], v[234:235] op_sel_hi:[0,1,1]
	v_pk_fma_f32 v[244:245], v[36:37], v[204:205], v[244:245] op_sel_hi:[0,1,1]
	v_pk_fma_f32 v[254:255], v[38:39], v[206:207], v[254:255] op_sel_hi:[0,1,1]
	v_mfma_f32_16x16x32_bf16 v[140:143], v[112:115], v[4:7], 0
	v_pk_fma_f32 v[200:201], v[32:33], v[200:201], v[232:233] op_sel:[1,1,0] op_sel_hi:[1,0,1] neg_lo:[1,0,0]
	v_pk_fma_f32 v[202:203], v[34:35], v[202:203], v[234:235] op_sel:[1,1,0] op_sel_hi:[1,0,1] neg_lo:[1,0,0]
	v_pk_fma_f32 v[204:205], v[36:37], v[204:205], v[244:245] op_sel:[1,1,0] op_sel_hi:[1,0,1] neg_lo:[1,0,0]
	v_pk_fma_f32 v[206:207], v[38:39], v[206:207], v[254:255] op_sel:[1,1,0] op_sel_hi:[1,0,1] neg_lo:[1,0,0]
	v_mfma_f32_16x16x32_bf16 v[144:147], v[112:115], v[8:11], 0
	v_cvt_pk_bf16_f32 v124, v200, v201
	v_cvt_pk_bf16_f32 v125, v202, v203
	v_cvt_pk_bf16_f32 v126, v204, v205
	v_cvt_pk_bf16_f32 v127, v206, v207
	v_mfma_f32_16x16x32_bf16 v[148:151], v[112:115], v[12:15], 0
	ds_write_b128 v241, v[124:127] offset:4096
	v_pk_mov_b32 v[232:233], v[168:169], v[184:185] op_sel:[1,1]
	v_pk_mov_b32 v[234:235], v[172:173], v[188:189] op_sel:[1,1]
	v_pk_mov_b32 v[244:245], v[176:177], v[192:193] op_sel:[1,1]
	v_mfma_f32_16x16x32_bf16 v[152:155], v[112:115], v[16:19], 0
	v_pk_mov_b32 v[254:255], v[180:181], v[196:197] op_sel:[1,1]
	v_pk_fma_f32 v[232:233], v[32:33], v[200:201], v[232:233] op_sel_hi:[0,1,1]
	v_pk_fma_f32 v[234:235], v[34:35], v[202:203], v[234:235] op_sel_hi:[0,1,1]
	v_pk_fma_f32 v[244:245], v[36:37], v[204:205], v[244:245] op_sel_hi:[0,1,1]
	v_mfma_f32_16x16x32_bf16 v[156:159], v[112:115], v[20:23], 0
	v_pk_fma_f32 v[254:255], v[38:39], v[206:207], v[254:255] op_sel_hi:[0,1,1]
	v_pk_fma_f32 v[200:201], v[32:33], v[200:201], v[232:233] op_sel:[1,1,0] op_sel_hi:[1,0,1] neg_lo:[1,0,0]
	v_pk_fma_f32 v[202:203], v[34:35], v[202:203], v[234:235] op_sel:[1,1,0] op_sel_hi:[1,0,1] neg_lo:[1,0,0]
	v_pk_fma_f32 v[204:205], v[36:37], v[204:205], v[244:245] op_sel:[1,1,0] op_sel_hi:[1,0,1] neg_lo:[1,0,0]
	v_mfma_f32_16x16x32_bf16 v[160:163], v[112:115], v[24:27], 0
	v_pk_fma_f32 v[206:207], v[38:39], v[206:207], v[254:255] op_sel:[1,1,0] op_sel_hi:[1,0,1] neg_lo:[1,0,0]
	v_cvt_pk_bf16_f32 v124, v200, v201
	v_cvt_pk_bf16_f32 v125, v202, v203
	v_cvt_pk_bf16_f32 v126, v204, v205
	v_mfma_f32_16x16x32_bf16 v[164:167], v[112:115], v[28:31], 0
	v_cvt_pk_bf16_f32 v127, v206, v207
	ds_write_b128 v241, v[124:127] offset:4352
	s_waitcnt lgkmcnt(2)
; __device__ __forceinline__ unsigned f2bf(float f) { unsigned u = __builtin_bit_cast(unsigned, f); return (u + 0x7fffu + ((u >> 16) & 1u)) >> 16; }
; __device__ __forceinline__ bf16x8 pack8(const float (&f)[8]) { u32x4 h; h.x = pk2(f[0], f[1]); h.y = pk2(f[2], f[3]); h.z = pk2(f[4], f[5]); h.w = pk2(f[6], f[7]); return __builtin_bit_cast(bf16x8, h); }
; template <bool FINAL> __device__ __forceinline__ void phase_s5_scan(const Fr& F) {
;     ...
;         for (int sub = 0; sub < 4; ++sub) {
;             const bf16x8 A1 = __builtin_bit_cast(bf16x8, uc[sub]);
; #pragma unroll
;             for (int nt = 0; nt < 8; ++nt) {
;                 f32x4 acc = {0.f, 0.f, 0.f, 0.f};
;                 acc = __builtin_amdgcn_mfma_f32_16x16x32_bf16(A1, B1[nt], acc, 0, 0, 0);
; #pragma unroll
;                 for (int reg = 0; reg < 4; ++reg) BUl[(4 * lq + reg) * 132 + 16 * nt + l15] = acc[reg];
;             }
;             asm volatile("s_waitcnt lgkmcnt(0)" ::: "memory");
; #pragma unroll 4
;             for (int jj = 0; jj < 16; ++jj) {
;                 const float br_ = BUl[jj * 132 + lane], bi_ = BUl[jj * 132 + 64 + lane];
;                 const float nr = ar * xr - ai * xi + br_, ni = ar * xi + ai * xr + bi_; xr = nr; xi = ni;
;                 if (FINAL) { BUl[jj * 132 + lane] = xr; BUl[jj * 132 + 64 + lane] = xi; }
;             }
;             if (FINAL) {
;                 asm volatile("s_waitcnt lgkmcnt(0)" ::: "memory");
;                 f32x4 acc = {0.f, 0.f, 0.f, 0.f};
; #pragma unroll
;                 for (int ks = 0; ks < 4; ++ks) {
;                     const f32x4 t0 = *(const f32x4*)(BUl + l15 * 132 + 32 * ks + 8 * lq), t1 = *(const f32x4*)(BUl + l15 * 132 + 32 * ks + 8 * lq + 4);
;                     const float xf[8] = {t0.x, t0.y, t0.z, t0.w, t1.x, t1.y, t1.z, t1.w};
;                     acc = __builtin_amdgcn_mfma_f32_16x16x32_bf16(pack8(xf), Chi[ks], acc, 0, 0, 0);
;                 }
; #pragma unroll
;                 for (int reg = 0; reg < 4; ++reg) { const int tok = tokof(s, chunk * 64 + sub * 16 + 4 * lq + reg);
;                     Yb[((size_t)b * TB + tok) * D + g * 16 + l15] = (bf16)f2bf(acc[reg]); }
;                 asm volatile("s_waitcnt lgkmcnt(0)" ::: "memory");
;             }
;         }
	v_pk_mov_b32 v[232:233], v[170:171], v[186:187] op_sel:[0,0]
	v_pk_mov_b32 v[234:235], v[174:175], v[190:191] op_sel:[0,0]
	v_pk_mov_b32 v[244:245], v[178:179], v[194:195] op_sel:[0,0]
	v_pk_mov_b32 v[254:255], v[182:183], v[198:199] op_sel:[0,0]
	v_mfma_f32_16x16x32_bf16 v[120:123], v[40:43], v[216:219], 0
	v_pk_fma_f32 v[232:233], v[32:33], v[200:201], v[232:233] op_sel_hi:[0,1,1]
	v_pk_fma_f32 v[234:235], v[34:35], v[202:203], v[234:235] op_sel_hi:[0,1,1]
	v_pk_fma_f32 v[244:245], v[36:37], v[204:205], v[244:245] op_sel_hi:[0,1,1]
	v_pk_fma_f32 v[254:255], v[38:39], v[206:207], v[254:255] op_sel_hi:[0,1,1]
	v_mfma_f32_16x16x32_bf16 v[120:123], v[44:47], v[220:223], v[120:123]
	v_pk_fma_f32 v[200:201], v[32:33], v[200:201], v[232:233] op_sel:[1,1,0] op_sel_hi:[1,0,1] neg_lo:[1,0,0]
	v_pk_fma_f32 v[202:203], v[34:35], v[202:203], v[234:235] op_sel:[1,1,0] op_sel_hi:[1,0,1] neg_lo:[1,0,0]
	v_pk_fma_f32 v[204:205], v[36:37], v[204:205], v[244:245] op_sel:[1,1,0] op_sel_hi:[1,0,1] neg_lo:[1,0,0]
	v_pk_fma_f32 v[206:207], v[38:39], v[206:207], v[254:255] op_sel:[1,1,0] op_sel_hi:[1,0,1] neg_lo:[1,0,0]
	v_mfma_f32_16x16x32_bf16 v[120:123], v[48:51], v[224:227], v[120:123]
	v_cvt_pk_bf16_f32 v124, v200, v201
	v_cvt_pk_bf16_f32 v125, v202, v203
	v_cvt_pk_bf16_f32 v126, v204, v205
	v_cvt_pk_bf16_f32 v127, v206, v207
	v_mfma_f32_16x16x32_bf16 v[120:123], v[52:55], v[228:231], v[120:123]
	ds_write_b128 v241, v[124:127] offset:4608
	v_pk_mov_b32 v[232:233], v[170:171], v[186:187] op_sel:[1,1]
	v_pk_mov_b32 v[234:235], v[174:175], v[190:191] op_sel:[1,1]
	v_pk_mov_b32 v[244:245], v[178:179], v[194:195] op_sel:[1,1]
	v_pk_mov_b32 v[254:255], v[182:183], v[198:199] op_sel:[1,1]
	v_pk_fma_f32 v[232:233], v[32:33], v[200:201], v[232:233] op_sel_hi:[0,1,1]
	v_pk_fma_f32 v[234:235], v[34:35], v[202:203], v[234:235] op_sel_hi:[0,1,1]
	v_pk_fma_f32 v[244:245], v[36:37], v[204:205], v[244:245] op_sel_hi:[0,1,1]
	v_pk_fma_f32 v[254:255], v[38:39], v[206:207], v[254:255] op_sel_hi:[0,1,1]
	v_pk_fma_f32 v[200:201], v[32:33], v[200:201], v[232:233] op_sel:[1,1,0] op_sel_hi:[1,0,1] neg_lo:[1,0,0]
	v_pk_fma_f32 v[202:203], v[34:35], v[202:203], v[234:235] op_sel:[1,1,0] op_sel_hi:[1,0,1] neg_lo:[1,0,0]
	v_pk_fma_f32 v[204:205], v[36:37], v[204:205], v[244:245] op_sel:[1,1,0] op_sel_hi:[1,0,1] neg_lo:[1,0,0]
	v_pk_fma_f32 v[206:207], v[38:39], v[206:207], v[254:255] op_sel:[1,1,0] op_sel_hi:[1,0,1] neg_lo:[1,0,0]
	v_cvt_pk_bf16_f32 v124, v200, v201
	v_cvt_pk_bf16_f32 v125, v202, v203
	v_cvt_pk_bf16_f32 v126, v204, v205
	v_cvt_pk_bf16_f32 v127, v206, v207
	ds_write_b128 v241, v[124:127] offset:4864
	global_load_dwordx4 v[108:111], v238, s[20:21]
	v_add_u32_e32 v238, v238, v243
	v_cvt_pk_bf16_f32 v124, v120, v121
	v_cvt_pk_bf16_f32 v125, v122, v123
	s_nop 0
	global_store_dwordx2 v239, v[124:125], s[24:25]
	v_add_u32_e32 v239, v239, v243
	s_waitcnt vmcnt(33)
	ds_read_b128 v[216:219], v242 offset:4096
	ds_read_b128 v[220:223], v242 offset:4160
	ds_read_b128 v[224:227], v242 offset:4224
	ds_read_b128 v[228:231], v242 offset:4288
	v_pk_mov_b32 v[232:233], v[136:137], v[152:153] op_sel:[0,0]
	v_pk_mov_b32 v[234:235], v[140:141], v[156:157] op_sel:[0,0]
	v_pk_mov_b32 v[244:245], v[144:145], v[160:161] op_sel:[0,0]
	v_pk_mov_b32 v[254:255], v[148:149], v[164:165] op_sel:[0,0]
	v_mfma_f32_16x16x32_bf16 v[168:171], v[116:119], v[0:3], 0
	v_pk_fma_f32 v[232:233], v[32:33], v[200:201], v[232:233] op_sel_hi:[0,1,1]
	v_pk_fma_f32 v[234:235], v[34:35], v[202:203], v[234:235] op_sel_hi:[0,1,1]
	v_pk_fma_f32 v[244:245], v[36:37], v[204:205], v[244:245] op_sel_hi:[0,1,1]
	v_pk_fma_f32 v[254:255], v[38:39], v[206:207], v[254:255] op_sel_hi:[0,1,1]
	v_mfma_f32_16x16x32_bf16 v[172:175], v[116:119], v[4:7], 0
	v_pk_fma_f32 v[200:201], v[32:33], v[200:201], v[232:233] op_sel:[1,1,0] op_sel_hi:[1,0,1] neg_lo:[1,0,0]
	v_pk_fma_f32 v[202:203], v[34:35], v[202:203], v[234:235] op_sel:[1,1,0] op_sel_hi:[1,0,1] neg_lo:[1,0,0]
	v_pk_fma_f32 v[204:205], v[36:37], v[204:205], v[244:245] op_sel:[1,1,0] op_sel_hi:[1,0,1] neg_lo:[1,0,0]
	v_pk_fma_f32 v[206:207], v[38:39], v[206:207], v[254:255] op_sel:[1,1,0] op_sel_hi:[1,0,1] neg_lo:[1,0,0]
	v_mfma_f32_16x16x32_bf16 v[176:179], v[116:119], v[8:11], 0
	v_cvt_pk_bf16_f32 v124, v200, v201
	v_cvt_pk_bf16_f32 v125, v202, v203
	v_cvt_pk_bf16_f32 v126, v204, v205
	v_cvt_pk_bf16_f32 v127, v206, v207
	v_mfma_f32_16x16x32_bf16 v[180:183], v[116:119], v[12:15], 0
	ds_write_b128 v241, v[124:127] offset:0
	v_pk_mov_b32 v[232:233], v[136:137], v[152:153] op_sel:[1,1]
	v_pk_mov_b32 v[234:235], v[140:141], v[156:157] op_sel:[1,1]
	v_pk_mov_b32 v[244:245], v[144:145], v[160:161] op_sel:[1,1]
	v_mfma_f32_16x16x32_bf16 v[184:187], v[116:119], v[16:19], 0
	v_pk_mov_b32 v[254:255], v[148:149], v[164:165] op_sel:[1,1]
	v_pk_fma_f32 v[232:233], v[32:33], v[200:201], v[232:233] op_sel_hi:[0,1,1]
	v_pk_fma_f32 v[234:235], v[34:35], v[202:203], v[234:235] op_sel_hi:[0,1,1]
	v_pk_fma_f32 v[244:245], v[36:37], v[204:205], v[244:245] op_sel_hi:[0,1,1]
	v_mfma_f32_16x16x32_bf16 v[188:191], v[116:119], v[20:23], 0
	v_pk_fma_f32 v[254:255], v[38:39], v[206:207], v[254:255] op_sel_hi:[0,1,1]
	v_pk_fma_f32 v[200:201], v[32:33], v[200:201], v[232:233] op_sel:[1,1,0] op_sel_hi:[1,0,1] neg_lo:[1,0,0]
	v_pk_fma_f32 v[202:203], v[34:35], v[202:203], v[234:235] op_sel:[1,1,0] op_sel_hi:[1,0,1] neg_lo:[1,0,0]
	v_pk_fma_f32 v[204:205], v[36:37], v[204:205], v[244:245] op_sel:[1,1,0] op_sel_hi:[1,0,1] neg_lo:[1,0,0]
	v_mfma_f32_16x16x32_bf16 v[192:195], v[116:119], v[24:27], 0
	v_pk_fma_f32 v[206:207], v[38:39], v[206:207], v[254:255] op_sel:[1,1,0] op_sel_hi:[1,0,1] neg_lo:[1,0,0]
	v_cvt_pk_bf16_f32 v124, v200, v201
	v_cvt_pk_bf16_f32 v125, v202, v203
	v_cvt_pk_bf16_f32 v126, v204, v205
	v_mfma_f32_16x16x32_bf16 v[196:199], v[116:119], v[28:31], 0
	v_cvt_pk_bf16_f32 v127, v206, v207
	ds_write_b128 v241, v[124:127] offset:256
	s_waitcnt lgkmcnt(2)
; __device__ __forceinline__ unsigned f2bf(float f) { unsigned u = __builtin_bit_cast(unsigned, f); return (u + 0x7fffu + ((u >> 16) & 1u)) >> 16; }
; __device__ __forceinline__ bf16x8 pack8(const float (&f)[8]) { u32x4 h; h.x = pk2(f[0], f[1]); h.y = pk2(f[2], f[3]); h.z = pk2(f[4], f[5]); h.w = pk2(f[6], f[7]); return __builtin_bit_cast(bf16x8, h); }
; template <bool FINAL> __device__ __forceinline__ void phase_s5_scan(const Fr& F) {
;     ...
;         for (int sub = 0; sub < 4; ++sub) {
;             const bf16x8 A1 = __builtin_bit_cast(bf16x8, uc[sub]);
; #pragma unroll
;             for (int nt = 0; nt < 8; ++nt) {
;                 f32x4 acc = {0.f, 0.f, 0.f, 0.f};
;                 acc = __builtin_amdgcn_mfma_f32_16x16x32_bf16(A1, B1[nt], acc, 0, 0, 0);
; #pragma unroll
;                 for (int reg = 0; reg < 4; ++reg) BUl[(4 * lq + reg) * 132 + 16 * nt + l15] = acc[reg];
;             }
;             asm volatile("s_waitcnt lgkmcnt(0)" ::: "memory");
; #pragma unroll 4
;             for (int jj = 0; jj < 16; ++jj) {
;                 const float br_ = BUl[jj * 132 + lane], bi_ = BUl[jj * 132 + 64 + lane];
;                 const float nr = ar * xr - ai * xi + br_, ni = ar * xi + ai * xr + bi_; xr = nr; xi = ni;
;                 if (FINAL) { BUl[jj * 132 + lane] = xr; BUl[jj * 132 + 64 + lane] = xi; }
;             }
;             if (FINAL) {
;                 asm volatile("s_waitcnt lgkmcnt(0)" ::: "memory");
;                 f32x4 acc = {0.f, 0.f, 0.f, 0.f};
; #pragma unroll
;                 for (int ks = 0; ks < 4; ++ks) {
;                     const f32x4 t0 = *(const f32x4*)(BUl + l15 * 132 + 32 * ks + 8 * lq), t1 = *(const f32x4*)(BUl + l15 * 132 + 32 * ks + 8 * lq + 4);
;                     const float xf[8] = {t0.x, t0.y, t0.z, t0.w, t1.x, t1.y, t1.z, t1.w};
;                     acc = __builtin_amdgcn_mfma_f32_16x16x32_bf16(pack8(xf), Chi[ks], acc, 0, 0, 0);
;                 }
; #pragma unroll
;                 for (int reg = 0; reg < 4; ++reg) { const int tok = tokof(s, chunk * 64 + sub * 16 + 4 * lq + reg);
;                     Yb[((size_t)b * TB + tok) * D + g * 16 + l15] = (bf16)f2bf(acc[reg]); }
;                 asm volatile("s_waitcnt lgkmcnt(0)" ::: "memory");
;             }
;         }
	v_pk_mov_b32 v[232:233], v[138:139], v[154:155] op_sel:[0,0]
	v_pk_mov_b32 v[234:235], v[142:143], v[158:159] op_sel:[0,0]
	v_pk_mov_b32 v[244:245], v[146:147], v[162:163] op_sel:[0,0]
	v_pk_mov_b32 v[254:255], v[150:151], v[166:167] op_sel:[0,0]
	v_mfma_f32_16x16x32_bf16 v[120:123], v[40:43], v[216:219], 0
	v_pk_fma_f32 v[232:233], v[32:33], v[200:201], v[232:233] op_sel_hi:[0,1,1]
	v_pk_fma_f32 v[234:235], v[34:35], v[202:203], v[234:235] op_sel_hi:[0,1,1]
	v_pk_fma_f32 v[244:245], v[36:37], v[204:205], v[244:245] op_sel_hi:[0,1,1]
	v_pk_fma_f32 v[254:255], v[38:39], v[206:207], v[254:255] op_sel_hi:[0,1,1]
	v_mfma_f32_16x16x32_bf16 v[120:123], v[44:47], v[220:223], v[120:123]
	v_pk_fma_f32 v[200:201], v[32:33], v[200:201], v[232:233] op_sel:[1,1,0] op_sel_hi:[1,0,1] neg_lo:[1,0,0]
	v_pk_fma_f32 v[202:203], v[34:35], v[202:203], v[234:235] op_sel:[1,1,0] op_sel_hi:[1,0,1] neg_lo:[1,0,0]
	v_pk_fma_f32 v[204:205], v[36:37], v[204:205], v[244:245] op_sel:[1,1,0] op_sel_hi:[1,0,1] neg_lo:[1,0,0]
	v_pk_fma_f32 v[206:207], v[38:39], v[206:207], v[254:255] op_sel:[1,1,0] op_sel_hi:[1,0,1] neg_lo:[1,0,0]
	v_mfma_f32_16x16x32_bf16 v[120:123], v[48:51], v[224:227], v[120:123]
	v_cvt_pk_bf16_f32 v124, v200, v201
	v_cvt_pk_bf16_f32 v125, v202, v203
	v_cvt_pk_bf16_f32 v126, v204, v205
	v_cvt_pk_bf16_f32 v127, v206, v207
	v_mfma_f32_16x16x32_bf16 v[120:123], v[52:55], v[228:231], v[120:123]
	ds_write_b128 v241, v[124:127] offset:512
	v_pk_mov_b32 v[232:233], v[138:139], v[154:155] op_sel:[1,1]
	v_pk_mov_b32 v[234:235], v[142:143], v[158:159] op_sel:[1,1]
	v_pk_mov_b32 v[244:245], v[146:147], v[162:163] op_sel:[1,1]
	v_pk_mov_b32 v[254:255], v[150:151], v[166:167] op_sel:[1,1]
	v_pk_fma_f32 v[232:233], v[32:33], v[200:201], v[232:233] op_sel_hi:[0,1,1]
	v_pk_fma_f32 v[234:235], v[34:35], v[202:203], v[234:235] op_sel_hi:[0,1,1]
	v_pk_fma_f32 v[244:245], v[36:37], v[204:205], v[244:245] op_sel_hi:[0,1,1]
	v_pk_fma_f32 v[254:255], v[38:39], v[206:207], v[254:255] op_sel_hi:[0,1,1]
	v_pk_fma_f32 v[200:201], v[32:33], v[200:201], v[232:233] op_sel:[1,1,0] op_sel_hi:[1,0,1] neg_lo:[1,0,0]
	v_pk_fma_f32 v[202:203], v[34:35], v[202:203], v[234:235] op_sel:[1,1,0] op_sel_hi:[1,0,1] neg_lo:[1,0,0]
	v_pk_fma_f32 v[204:205], v[36:37], v[204:205], v[244:245] op_sel:[1,1,0] op_sel_hi:[1,0,1] neg_lo:[1,0,0]
	v_pk_fma_f32 v[206:207], v[38:39], v[206:207], v[254:255] op_sel:[1,1,0] op_sel_hi:[1,0,1] neg_lo:[1,0,0]
	v_cvt_pk_bf16_f32 v124, v200, v201
	v_cvt_pk_bf16_f32 v125, v202, v203
	v_cvt_pk_bf16_f32 v126, v204, v205
	v_cvt_pk_bf16_f32 v127, v206, v207
	ds_write_b128 v241, v[124:127] offset:768
	global_load_dwordx4 v[112:115], v238, s[20:21]
	v_add_u32_e32 v238, v238, v243
	v_cvt_pk_bf16_f32 v124, v120, v121
	v_cvt_pk_bf16_f32 v125, v122, v123
	s_nop 0
	global_store_dwordx2 v239, v[124:125], s[24:25]
	v_add_u32_e32 v239, v239, v243
	ds_read_b128 v[216:219], v242 offset:0
	ds_read_b128 v[220:223], v242 offset:64
	ds_read_b128 v[224:227], v242 offset:128
	ds_read_b128 v[228:231], v242 offset:192
	v_pk_mov_b32 v[232:233], v[168:169], v[184:185] op_sel:[0,0]
	v_pk_mov_b32 v[234:235], v[172:173], v[188:189] op_sel:[0,0]
	v_pk_mov_b32 v[244:245], v[176:177], v[192:193] op_sel:[0,0]
	v_pk_mov_b32 v[254:255], v[180:181], v[196:197] op_sel:[0,0]
	v_pk_fma_f32 v[232:233], v[32:33], v[200:201], v[232:233] op_sel_hi:[0,1,1]
	v_pk_fma_f32 v[234:235], v[34:35], v[202:203], v[234:235] op_sel_hi:[0,1,1]
	v_pk_fma_f32 v[244:245], v[36:37], v[204:205], v[244:245] op_sel_hi:[0,1,1]
	v_pk_fma_f32 v[254:255], v[38:39], v[206:207], v[254:255] op_sel_hi:[0,1,1]
	v_pk_fma_f32 v[200:201], v[32:33], v[200:201], v[232:233] op_sel:[1,1,0] op_sel_hi:[1,0,1] neg_lo:[1,0,0]
	v_pk_fma_f32 v[202:203], v[34:35], v[202:203], v[234:235] op_sel:[1,1,0] op_sel_hi:[1,0,1] neg_lo:[1,0,0]
	v_pk_fma_f32 v[204:205], v[36:37], v[204:205], v[244:245] op_sel:[1,1,0] op_sel_hi:[1,0,1] neg_lo:[1,0,0]
	v_pk_fma_f32 v[206:207], v[38:39], v[206:207], v[254:255] op_sel:[1,1,0] op_sel_hi:[1,0,1] neg_lo:[1,0,0]
	v_cvt_pk_bf16_f32 v124, v200, v201
	v_cvt_pk_bf16_f32 v125, v202, v203
	v_cvt_pk_bf16_f32 v126, v204, v205
	v_cvt_pk_bf16_f32 v127, v206, v207
	ds_write_b128 v241, v[124:127] offset:4096
	v_pk_mov_b32 v[232:233], v[168:169], v[184:185] op_sel:[1,1]
	v_pk_mov_b32 v[234:235], v[172:173], v[188:189] op_sel:[1,1]
	v_pk_mov_b32 v[244:245], v[176:177], v[192:193] op_sel:[1,1]
	v_pk_mov_b32 v[254:255], v[180:181], v[196:197] op_sel:[1,1]
	v_pk_fma_f32 v[232:233], v[32:33], v[200:201], v[232:233] op_sel_hi:[0,1,1]
	v_pk_fma_f32 v[234:235], v[34:35], v[202:203], v[234:235] op_sel_hi:[0,1,1]
	v_pk_fma_f32 v[244:245], v[36:37], v[204:205], v[244:245] op_sel_hi:[0,1,1]
	v_pk_fma_f32 v[254:255], v[38:39], v[206:207], v[254:255] op_sel_hi:[0,1,1]
	v_pk_fma_f32 v[200:201], v[32:33], v[200:201], v[232:233] op_sel:[1,1,0] op_sel_hi:[1,0,1] neg_lo:[1,0,0]
	v_pk_fma_f32 v[202:203], v[34:35], v[202:203], v[234:235] op_sel:[1,1,0] op_sel_hi:[1,0,1] neg_lo:[1,0,0]
	v_pk_fma_f32 v[204:205], v[36:37], v[204:205], v[244:245] op_sel:[1,1,0] op_sel_hi:[1,0,1] neg_lo:[1,0,0]
	v_pk_fma_f32 v[206:207], v[38:39], v[206:207], v[254:255] op_sel:[1,1,0] op_sel_hi:[1,0,1] neg_lo:[1,0,0]
	v_cvt_pk_bf16_f32 v124, v200, v201
	v_cvt_pk_bf16_f32 v125, v202, v203
	v_cvt_pk_bf16_f32 v126, v204, v205
	v_cvt_pk_bf16_f32 v127, v206, v207
	ds_write_b128 v241, v[124:127] offset:4352
	s_waitcnt lgkmcnt(2)
; __device__ __forceinline__ unsigned f2bf(float f) { unsigned u = __builtin_bit_cast(unsigned, f); return (u + 0x7fffu + ((u >> 16) & 1u)) >> 16; }
; __device__ __forceinline__ bf16x8 pack8(const float (&f)[8]) { u32x4 h; h.x = pk2(f[0], f[1]); h.y = pk2(f[2], f[3]); h.z = pk2(f[4], f[5]); h.w = pk2(f[6], f[7]); return __builtin_bit_cast(bf16x8, h); }
; template <bool FINAL> __device__ __forceinline__ void phase_s5_scan(const Fr& F) {
;     ...
; #pragma unroll 4
;             for (int jj = 0; jj < 16; ++jj) {
;                 const float br_ = BUl[jj * 132 + lane], bi_ = BUl[jj * 132 + 64 + lane];
;                 const float nr = ar * xr - ai * xi + br_, ni = ar * xi + ai * xr + bi_; xr = nr; xi = ni;
;                 if (FINAL) { BUl[jj * 132 + lane] = xr; BUl[jj * 132 + 64 + lane] = xi; }
;             }
;             if (FINAL) {
;                 asm volatile("s_waitcnt lgkmcnt(0)" ::: "memory");
;                 f32x4 acc = {0.f, 0.f, 0.f, 0.f};
; #pragma unroll
;                 for (int ks = 0; ks < 4; ++ks) {
;                     const f32x4 t0 = *(const f32x4*)(BUl + l15 * 132 + 32 * ks + 8 * lq), t1 = *(const f32x4*)(BUl + l15 * 132 + 32 * ks + 8 * lq + 4);
;                     const float xf[8] = {t0.x, t0.y, t0.z, t0.w, t1.x, t1.y, t1.z, t1.w};
;                     acc = __builtin_amdgcn_mfma_f32_16x16x32_bf16(pack8(xf), Chi[ks], acc, 0, 0, 0);
;                 }
; #pragma unroll
;                 for (int reg = 0; reg < 4; ++reg) { const int tok = tokof(s, chunk * 64 + sub * 16 + 4 * lq + reg);
;                     Yb[((size_t)b * TB + tok) * D + g * 16 + l15] = (bf16)f2bf(acc[reg]); }
;                 asm volatile("s_waitcnt lgkmcnt(0)" ::: "memory");
;             }
;         }
;         if (!FINAL) { float* e = E + ((size_t)task * 64 + lane) * 2; e[0] = xr; e[1] = xi; }
;     }
	v_pk_mov_b32 v[232:233], v[170:171], v[186:187] op_sel:[0,0]
	v_pk_mov_b32 v[234:235], v[174:175], v[190:191] op_sel:[0,0]
	v_pk_mov_b32 v[244:245], v[178:179], v[194:195] op_sel:[0,0]
	v_pk_mov_b32 v[254:255], v[182:183], v[198:199] op_sel:[0,0]
	v_mfma_f32_16x16x32_bf16 v[120:123], v[40:43], v[216:219], 0
	v_pk_fma_f32 v[232:233], v[32:33], v[200:201], v[232:233] op_sel_hi:[0,1,1]
	v_pk_fma_f32 v[234:235], v[34:35], v[202:203], v[234:235] op_sel_hi:[0,1,1]
	v_pk_fma_f32 v[244:245], v[36:37], v[204:205], v[244:245] op_sel_hi:[0,1,1]
	v_pk_fma_f32 v[254:255], v[38:39], v[206:207], v[254:255] op_sel_hi:[0,1,1]
	v_mfma_f32_16x16x32_bf16 v[120:123], v[44:47], v[220:223], v[120:123]
	v_pk_fma_f32 v[200:201], v[32:33], v[200:201], v[232:233] op_sel:[1,1,0] op_sel_hi:[1,0,1] neg_lo:[1,0,0]
	v_pk_fma_f32 v[202:203], v[34:35], v[202:203], v[234:235] op_sel:[1,1,0] op_sel_hi:[1,0,1] neg_lo:[1,0,0]
	v_pk_fma_f32 v[204:205], v[36:37], v[204:205], v[244:245] op_sel:[1,1,0] op_sel_hi:[1,0,1] neg_lo:[1,0,0]
	v_pk_fma_f32 v[206:207], v[38:39], v[206:207], v[254:255] op_sel:[1,1,0] op_sel_hi:[1,0,1] neg_lo:[1,0,0]
	v_mfma_f32_16x16x32_bf16 v[120:123], v[48:51], v[224:227], v[120:123]
	v_cvt_pk_bf16_f32 v124, v200, v201
	v_cvt_pk_bf16_f32 v125, v202, v203
	v_cvt_pk_bf16_f32 v126, v204, v205
	v_cvt_pk_bf16_f32 v127, v206, v207
	v_mfma_f32_16x16x32_bf16 v[120:123], v[52:55], v[228:231], v[120:123]
	ds_write_b128 v241, v[124:127] offset:4608
	v_pk_mov_b32 v[232:233], v[170:171], v[186:187] op_sel:[1,1]
	v_pk_mov_b32 v[234:235], v[174:175], v[190:191] op_sel:[1,1]
	v_pk_mov_b32 v[244:245], v[178:179], v[194:195] op_sel:[1,1]
	v_pk_mov_b32 v[254:255], v[182:183], v[198:199] op_sel:[1,1]
	v_pk_fma_f32 v[232:233], v[32:33], v[200:201], v[232:233] op_sel_hi:[0,1,1]
	v_pk_fma_f32 v[234:235], v[34:35], v[202:203], v[234:235] op_sel_hi:[0,1,1]
	v_pk_fma_f32 v[244:245], v[36:37], v[204:205], v[244:245] op_sel_hi:[0,1,1]
	v_pk_fma_f32 v[254:255], v[38:39], v[206:207], v[254:255] op_sel_hi:[0,1,1]
	v_pk_fma_f32 v[200:201], v[32:33], v[200:201], v[232:233] op_sel:[1,1,0] op_sel_hi:[1,0,1] neg_lo:[1,0,0]
	v_pk_fma_f32 v[202:203], v[34:35], v[202:203], v[234:235] op_sel:[1,1,0] op_sel_hi:[1,0,1] neg_lo:[1,0,0]
	v_pk_fma_f32 v[204:205], v[36:37], v[204:205], v[244:245] op_sel:[1,1,0] op_sel_hi:[1,0,1] neg_lo:[1,0,0]
	v_pk_fma_f32 v[206:207], v[38:39], v[206:207], v[254:255] op_sel:[1,1,0] op_sel_hi:[1,0,1] neg_lo:[1,0,0]
	v_cvt_pk_bf16_f32 v124, v200, v201
	v_cvt_pk_bf16_f32 v125, v202, v203
	v_cvt_pk_bf16_f32 v126, v204, v205
	v_cvt_pk_bf16_f32 v127, v206, v207
	ds_write_b128 v241, v[124:127] offset:4864
	global_load_dwordx4 v[116:119], v238, s[20:21]
	v_add_u32_e32 v238, v238, v243
	v_cvt_pk_bf16_f32 v124, v120, v121
	v_cvt_pk_bf16_f32 v125, v122, v123
	s_nop 0
	global_store_dwordx2 v239, v[124:125], s[24:25]
	v_add_u32_e32 v239, v239, v243
	ds_read_b128 v[216:219], v242 offset:4096
	ds_read_b128 v[220:223], v242 offset:4160
	ds_read_b128 v[224:227], v242 offset:4224
	ds_read_b128 v[228:231], v242 offset:4288
	s_waitcnt lgkmcnt(0)
	v_mfma_f32_16x16x32_bf16 v[120:123], v[40:43], v[216:219], 0
	v_mfma_f32_16x16x32_bf16 v[120:123], v[44:47], v[220:223], v[120:123]
	v_mfma_f32_16x16x32_bf16 v[120:123], v[48:51], v[224:227], v[120:123]
	v_mfma_f32_16x16x32_bf16 v[120:123], v[52:55], v[228:231], v[120:123]
	s_nop 7
	s_nop 1
	v_cvt_pk_bf16_f32 v124, v120, v121
	v_cvt_pk_bf16_f32 v125, v122, v123
	s_nop 0
	global_store_dwordx2 v239, v[124:125], s[24:25]
	v_add_u32_e32 v239, v239, v243
	s_add_i32 s14, s14, 16
	s_add_i32 s19, s19, 1
	s_cmp_lt_u32 s19, s56
	s_cbranch_scc1 .Ls5b_grp
	s_waitcnt vmcnt(0) lgkmcnt(0)
	v_mov_b32_e32 v2, s34
	v_mov_b32_e32 v3, s35
